# fused LayerNorm row statistics: xor-16/xor-32 lane exchanges by v_permlane swaps instead of ds_bpermute round trips (bit-identical)
# speedup vs baseline: 1.0055x; 1.0055x over previous
.LBB0_415:
	s_lshl_b32 s0, s3, 10
	s_lshl_b64 s[8:9], s[0:1], 2
	v_readlane_b32 s3, v253, 4
	s_add_u32 s8, s3, s8
	v_readlane_b32 s3, v253, 5
	s_addc_u32 s9, s3, s9
	v_lshl_add_u64 v[20:21], v[160:161], 2, s[8:9]
	global_load_dwordx4 v[196:199], v[20:21], off
	global_load_dwordx4 v[200:203], v[20:21], off offset:64
	global_load_dwordx4 v[204:207], v[20:21], off offset:512
	global_load_dwordx4 v[208:211], v[20:21], off offset:576
	s_mov_b32 s8, 0x3a800000
	s_lshl_b32 s10, s23, 5
	v_readlane_b32 s3, v254, 17
	s_add_i32 s3, s3, s10
	s_lshl_b32 s11, s34, 2
	v_cmp_gt_u32_e32 vcc, 16, v178
	s_waitcnt vmcnt(0)
	v_pk_mul_f32 v[174:175], v[196:197], s[8:9] op_sel_hi:[1,0]
	v_pk_mul_f32 v[176:177], v[198:199], s[8:9] op_sel_hi:[1,0]
	v_pk_mul_f32 v[170:171], v[200:201], s[8:9] op_sel_hi:[1,0]
	v_pk_mul_f32 v[172:173], v[202:203], s[8:9] op_sel_hi:[1,0]
	v_pk_mul_f32 v[166:167], v[204:205], s[8:9] op_sel_hi:[1,0]
	v_pk_mul_f32 v[168:169], v[206:207], s[8:9] op_sel_hi:[1,0]
	v_mbcnt_lo_u32_b32 v30, -1, 0
	v_mbcnt_hi_u32_b32 v30, -1, v30
	v_pk_mul_f32 v[162:163], v[208:209], s[8:9] op_sel_hi:[1,0]
	v_pk_mul_f32 v[164:165], v[210:211], s[8:9] op_sel_hi:[1,0]
	v_ashrrev_i32_e32 v31, 5, v30
	v_add_u32_e32 v16, s3, v31
	v_and_b32_e32 v180, 31, v30
	v_ashrrev_i32_e32 v17, 31, v16
	v_readlane_b32 s8, v253, 47
	v_lshlrev_b64 v[16:17], 11, v[16:17]
	v_readlane_b32 s9, v253, 48
	s_lshl_b32 s3, s23, 14
	v_bitop3_b32 v18, v31, v180, 15 bitop3:0x6c
	v_lshl_add_u64 v[16:17], s[8:9], 0, v[16:17]
	s_add_i32 s3, s3, 0
	v_lshlrev_b32_e32 v230, 4, v18
	v_lshl_add_u64 v[18:19], v[16:17], 0, v[230:231]
	s_mov_b32 m0, s3
	s_mov_b64 s[8:9], 0x1000
	global_load_lds_dwordx4 v[18:19], off
	v_lshl_add_u64 v[18:19], v[16:17], 0, s[8:9]
	v_add_u32_e32 v16, 2, v31
	v_bitop3_b32 v16, v16, v180, 15 bitop3:0x6c
	v_lshlrev_b32_e32 v16, 4, v16
	v_mov_b32_e32 v17, v231
	s_add_i32 m0, s3, 0x400
	v_lshl_add_u64 v[20:21], v[18:19], 0, v[16:17]
	global_load_lds_dwordx4 v[20:21], off
	v_lshl_add_u64 v[20:21], v[18:19], 0, s[8:9]
	v_add_u32_e32 v18, 4, v31
	v_bitop3_b32 v18, v18, v180, 15 bitop3:0x6c
	v_lshlrev_b32_e32 v18, 4, v18
	v_mov_b32_e32 v19, v231
	s_add_i32 m0, s3, 0x800
	v_lshl_add_u64 v[22:23], v[20:21], 0, v[18:19]
	global_load_lds_dwordx4 v[22:23], off
	v_lshl_add_u64 v[22:23], v[20:21], 0, s[8:9]
	v_add_u32_e32 v20, 6, v31
	v_bitop3_b32 v20, v20, v180, 15 bitop3:0x6c
	v_lshlrev_b32_e32 v20, 4, v20
	v_mov_b32_e32 v21, v231
	s_add_i32 m0, s3, 0xc00
	v_lshl_add_u64 v[24:25], v[22:23], 0, v[20:21]
	global_load_lds_dwordx4 v[24:25], off
	v_lshl_add_u64 v[24:25], v[22:23], 0, s[8:9]
	v_xor_b32_e32 v22, 0x80, v230
	v_mov_b32_e32 v23, v231
	s_add_i32 m0, s3, 0x1000
	v_lshl_add_u64 v[26:27], v[24:25], 0, v[22:23]
	global_load_lds_dwordx4 v[26:27], off
	v_lshl_add_u64 v[26:27], v[24:25], 0, s[8:9]
	v_add_u32_e32 v24, 10, v31
	v_bitop3_b32 v24, v24, v180, 15 bitop3:0x6c
	v_lshlrev_b32_e32 v24, 4, v24
	v_mov_b32_e32 v25, v231
	s_add_i32 m0, s3, 0x1400
	v_lshl_add_u64 v[28:29], v[26:27], 0, v[24:25]
	global_load_lds_dwordx4 v[28:29], off
	v_add_u32_e32 v28, 12, v31
	v_lshl_add_u64 v[26:27], v[26:27], 0, s[8:9]
	v_bitop3_b32 v28, v28, v180, 15 bitop3:0x6c
	v_lshlrev_b32_e32 v28, 4, v28
	v_mov_b32_e32 v29, v231
	v_add_u32_e32 v181, 14, v31
	v_lshl_add_u64 v[182:183], v[26:27], 0, v[28:29]
	s_add_i32 m0, s3, 0x1800
	v_lshl_add_u64 v[26:27], v[26:27], 0, s[8:9]
	v_bitop3_b32 v180, v181, v180, 15 bitop3:0x6c
	global_load_lds_dwordx4 v[182:183], off
	v_lshlrev_b32_e32 v180, 4, v180
	v_mov_b32_e32 v181, v231
	v_lshl_add_u64 v[182:183], v[26:27], 0, v[180:181]
	s_add_i32 m0, s3, 0x1c00
	v_lshl_add_u64 v[26:27], v[26:27], 0, s[8:9]
	global_load_lds_dwordx4 v[182:183], off
	s_add_i32 m0, s3, 0x2000
	v_lshl_add_u64 v[182:183], v[26:27], 0, v[230:231]
	v_lshl_add_u64 v[26:27], v[26:27], 0, s[8:9]
	global_load_lds_dwordx4 v[182:183], off
	s_add_i32 m0, s3, 0x2400
	v_lshl_add_u64 v[16:17], v[26:27], 0, v[16:17]
	global_load_lds_dwordx4 v[16:17], off
	v_lshl_add_u64 v[16:17], v[26:27], 0, s[8:9]
	s_add_i32 m0, s3, 0x2800
	v_lshl_add_u64 v[18:19], v[16:17], 0, v[18:19]
	v_lshl_add_u64 v[16:17], v[16:17], 0, s[8:9]
	global_load_lds_dwordx4 v[18:19], off
	s_add_i32 m0, s3, 0x2c00
	v_lshl_add_u64 v[18:19], v[16:17], 0, v[20:21]
	v_lshl_add_u64 v[16:17], v[16:17], 0, s[8:9]
	global_load_lds_dwordx4 v[18:19], off
	s_add_i32 m0, s3, 0x3000
	v_lshl_add_u64 v[18:19], v[16:17], 0, v[22:23]
	v_lshl_add_u64 v[16:17], v[16:17], 0, s[8:9]
	global_load_lds_dwordx4 v[18:19], off
	s_add_i32 m0, s3, 0x3400
	v_lshl_add_u64 v[18:19], v[16:17], 0, v[24:25]
	v_lshl_add_u64 v[16:17], v[16:17], 0, s[8:9]
	global_load_lds_dwordx4 v[18:19], off
	s_add_i32 m0, s3, 0x3800
	v_lshl_add_u64 v[18:19], v[16:17], 0, v[28:29]
	v_lshl_add_u64 v[16:17], v[16:17], 0, s[8:9]
	global_load_lds_dwordx4 v[18:19], off
	s_add_i32 m0, s3, 0x3c00
	v_lshl_add_u64 v[18:19], v[16:17], 0, v[180:181]
	v_lshl_add_u64 v[16:17], v[16:17], 0, s[8:9]
	global_load_lds_dwordx4 v[18:19], off
	v_lshrrev_b32_e32 v18, 1, v30
	v_lshlrev_b32_e32 v17, 9, v30
	v_and_b32_e32 v17, 0x200, v17
	v_and_b32_e32 v18, 8, v18
	v_add_u32_e32 v28, s11, v31
	v_and_b32_e32 v16, 15, v30
	v_add3_u32 v183, 0, v17, v18
	v_add_u32_e32 v17, 16, v28
	v_bitop3_b32 v17, v17, v30, 15 bitop3:0x78
	s_lshl_b32 s3, s22, 15
	v_lshlrev_b32_e32 v16, 9, v16
	v_lshlrev_b32_e32 v180, 4, v17
	v_or_b32_e32 v184, s3, v16
	v_mov_b32_e32 v17, s3
	s_movk_i32 s3, 0x9c00
	v_bitop3_b32 v16, v16, s3, v17 bitop3:0xc8
	v_add_u32_e32 v181, v183, v16
	v_bitop3_b32 v16, v28, v30, 15 bitop3:0x78
	v_lshlrev_b32_e32 v182, 4, v16
	s_waitcnt vmcnt(0)
	s_barrier
	v_add_u32_e32 v185, v181, v182
	ds_read_b64 v[16:17], v185
	s_mov_b32 s8, 0x3fd744fd
	s_lshl_b32 s3, s34, 3
	s_add_i32 s12, s3, 0
	s_waitcnt lgkmcnt(0)
	v_cvt_f32_f16_e32 v18, v16
	v_cvt_f32_f16_sdwa v19, v16 dst_sel:DWORD dst_unused:UNUSED_PAD src0_sel:WORD_1
	v_cvt_f32_f16_e32 v16, v17
	v_cvt_f32_f16_sdwa v17, v17 dst_sel:DWORD dst_unused:UNUSED_PAD src0_sel:WORD_1
	v_pk_mul_f32 v[20:21], v[18:19], s[8:9] op_sel_hi:[1,0]
	v_pk_mul_f32 v[16:17], v[16:17], s[8:9] op_sel_hi:[1,0]
	s_nop 0
	v_pk_fma_f32 v[18:19], v[158:159], v[176:177], v[16:17]
	v_pk_fma_f32 v[16:17], v[156:157], v[174:175], v[20:21]
	v_add_u32_e32 v20, 2, v28
	v_bitop3_b32 v20, v20, v30, 15 bitop3:0x78
	v_lshlrev_b32_e32 v156, 4, v20
	v_add_u32_e32 v157, v181, v156
	ds_read_b64 v[20:21], v157
	s_waitcnt lgkmcnt(0)
	v_cvt_f32_f16_e32 v22, v20
	v_cvt_f32_f16_sdwa v23, v20 dst_sel:DWORD dst_unused:UNUSED_PAD src0_sel:WORD_1
	v_cvt_f32_f16_e32 v20, v21
	v_cvt_f32_f16_sdwa v21, v21 dst_sel:DWORD dst_unused:UNUSED_PAD src0_sel:WORD_1
	v_pk_mul_f32 v[22:23], v[22:23], s[8:9] op_sel_hi:[1,0]
	s_nop 0
	v_pk_fma_f32 v[24:25], v[152:153], v[170:171], v[22:23]
	v_pk_mul_f32 v[20:21], v[20:21], s[8:9] op_sel_hi:[1,0]
	v_add_u32_e32 v153, v181, v180
	v_pk_fma_f32 v[26:27], v[154:155], v[172:173], v[20:21]
	ds_read_b64 v[20:21], v153
	s_waitcnt lgkmcnt(0)
	v_cvt_f32_f16_e32 v22, v20
	v_cvt_f32_f16_sdwa v23, v20 dst_sel:DWORD dst_unused:UNUSED_PAD src0_sel:WORD_1
	v_cvt_f32_f16_e32 v20, v21
	v_cvt_f32_f16_sdwa v21, v21 dst_sel:DWORD dst_unused:UNUSED_PAD src0_sel:WORD_1
	v_pk_mul_f32 v[22:23], v[22:23], s[8:9] op_sel_hi:[1,0]
	s_nop 0
	v_pk_fma_f32 v[148:149], v[148:149], v[166:167], v[22:23]
	v_pk_mul_f32 v[20:21], v[20:21], s[8:9] op_sel_hi:[1,0]
	s_nop 0
	v_pk_fma_f32 v[150:151], v[150:151], v[168:169], v[20:21]
	v_add_u32_e32 v20, 18, v28
	v_bitop3_b32 v20, v20, v30, 15 bitop3:0x78
	v_lshlrev_b32_e32 v152, 4, v20
	v_add_u32_e32 v154, v181, v152
	ds_read_b64 v[20:21], v154
	s_waitcnt lgkmcnt(0)
	v_cvt_f32_f16_e32 v22, v20
	v_cvt_f32_f16_sdwa v23, v20 dst_sel:DWORD dst_unused:UNUSED_PAD src0_sel:WORD_1
	v_cvt_f32_f16_e32 v20, v21
	v_cvt_f32_f16_sdwa v21, v21 dst_sel:DWORD dst_unused:UNUSED_PAD src0_sel:WORD_1
	v_pk_mul_f32 v[22:23], v[22:23], s[8:9] op_sel_hi:[1,0]
	s_nop 0
	v_pk_fma_f32 v[144:145], v[144:145], v[162:163], v[22:23]
	v_pk_mul_f32 v[20:21], v[20:21], s[8:9] op_sel_hi:[1,0]
	s_nop 0
	v_pk_fma_f32 v[146:147], v[146:147], v[164:165], v[20:21]
	s_nop 0
	ds_read_b64 v[20:21], v185 offset:8192
	s_waitcnt lgkmcnt(0)
	v_cvt_f32_f16_e32 v22, v20
	v_cvt_f32_f16_sdwa v23, v20 dst_sel:DWORD dst_unused:UNUSED_PAD src0_sel:WORD_1
	v_cvt_f32_f16_e32 v20, v21
	v_cvt_f32_f16_sdwa v21, v21 dst_sel:DWORD dst_unused:UNUSED_PAD src0_sel:WORD_1
	v_pk_mul_f32 v[28:29], v[22:23], s[8:9] op_sel_hi:[1,0]
	v_pk_mul_f32 v[20:21], v[20:21], s[8:9] op_sel_hi:[1,0]
	s_nop 0
	v_pk_fma_f32 v[22:23], v[142:143], v[176:177], v[20:21]
	v_pk_fma_f32 v[20:21], v[140:141], v[174:175], v[28:29]
	ds_read_b64 v[28:29], v157 offset:8192
	v_pk_add_f32 v[142:143], v[0:1], v[24:25]
	v_lshlrev_b32_e32 v24, 2, v178
	s_waitcnt lgkmcnt(0)
	v_cvt_f32_f16_e32 v30, v28
	v_cvt_f32_f16_sdwa v31, v28 dst_sel:DWORD dst_unused:UNUSED_PAD src0_sel:WORD_1
	v_cvt_f32_f16_e32 v28, v29
	v_cvt_f32_f16_sdwa v29, v29 dst_sel:DWORD dst_unused:UNUSED_PAD src0_sel:WORD_1
	v_pk_mul_f32 v[140:141], v[30:31], s[8:9] op_sel_hi:[1,0]
	v_pk_mul_f32 v[28:29], v[28:29], s[8:9] op_sel_hi:[1,0]
	s_nop 0
	v_pk_fma_f32 v[30:31], v[138:139], v[172:173], v[28:29]
	v_pk_fma_f32 v[28:29], v[136:137], v[170:171], v[140:141]
	ds_read_b64 v[136:137], v153 offset:8192
	v_add_u32_e32 v140, 0x10000, v181
	s_waitcnt lgkmcnt(0)
	v_cvt_f32_f16_e32 v138, v136
	v_cvt_f32_f16_sdwa v139, v136 dst_sel:DWORD dst_unused:UNUSED_PAD src0_sel:WORD_1
	v_cvt_f32_f16_e32 v136, v137
	v_cvt_f32_f16_sdwa v137, v137 dst_sel:DWORD dst_unused:UNUSED_PAD src0_sel:WORD_1
	v_pk_mul_f32 v[138:139], v[138:139], s[8:9] op_sel_hi:[1,0]
	s_nop 0
	v_pk_fma_f32 v[132:133], v[132:133], v[166:167], v[138:139]
	v_pk_mul_f32 v[136:137], v[136:137], s[8:9] op_sel_hi:[1,0]
	s_nop 0
	v_pk_fma_f32 v[134:135], v[134:135], v[168:169], v[136:137]
	ds_read_b64 v[136:137], v154 offset:8192
	s_waitcnt lgkmcnt(0)
	v_cvt_f32_f16_e32 v138, v136
	v_cvt_f32_f16_sdwa v139, v136 dst_sel:DWORD dst_unused:UNUSED_PAD src0_sel:WORD_1
	v_cvt_f32_f16_e32 v136, v137
	v_cvt_f32_f16_sdwa v137, v137 dst_sel:DWORD dst_unused:UNUSED_PAD src0_sel:WORD_1
	v_pk_mul_f32 v[138:139], v[138:139], s[8:9] op_sel_hi:[1,0]
	s_nop 0
	v_pk_fma_f32 v[128:129], v[128:129], v[162:163], v[138:139]
	v_pk_mul_f32 v[136:137], v[136:137], s[8:9] op_sel_hi:[1,0]
	s_nop 0
	v_pk_fma_f32 v[130:131], v[130:131], v[164:165], v[136:137]
	s_nop 0
	ds_read_b64 v[136:137], v185 offset:16384
	s_waitcnt lgkmcnt(0)
	v_cvt_f32_f16_e32 v138, v136
	v_cvt_f32_f16_sdwa v139, v136 dst_sel:DWORD dst_unused:UNUSED_PAD src0_sel:WORD_1
	v_cvt_f32_f16_e32 v136, v137
	v_cvt_f32_f16_sdwa v137, v137 dst_sel:DWORD dst_unused:UNUSED_PAD src0_sel:WORD_1
	v_pk_mul_f32 v[138:139], v[138:139], s[8:9] op_sel_hi:[1,0]
	s_nop 0
	v_pk_fma_f32 v[124:125], v[124:125], v[174:175], v[138:139]
	v_pk_mul_f32 v[136:137], v[136:137], s[8:9] op_sel_hi:[1,0]
	s_nop 0
	v_pk_fma_f32 v[126:127], v[126:127], v[176:177], v[136:137]
	ds_read_b64 v[136:137], v157 offset:16384
	s_waitcnt lgkmcnt(0)
	v_cvt_f32_f16_e32 v138, v136
	v_cvt_f32_f16_sdwa v139, v136 dst_sel:DWORD dst_unused:UNUSED_PAD src0_sel:WORD_1
	v_cvt_f32_f16_e32 v136, v137
	v_cvt_f32_f16_sdwa v137, v137 dst_sel:DWORD dst_unused:UNUSED_PAD src0_sel:WORD_1
	v_pk_mul_f32 v[138:139], v[138:139], s[8:9] op_sel_hi:[1,0]
	s_nop 0
	v_pk_fma_f32 v[120:121], v[120:121], v[170:171], v[138:139]
	v_pk_mul_f32 v[136:137], v[136:137], s[8:9] op_sel_hi:[1,0]
	s_nop 0
	v_pk_fma_f32 v[122:123], v[122:123], v[172:173], v[136:137]
	ds_read_b64 v[136:137], v153 offset:16384
	s_waitcnt lgkmcnt(0)
	v_cvt_f32_f16_e32 v138, v136
	v_cvt_f32_f16_sdwa v139, v136 dst_sel:DWORD dst_unused:UNUSED_PAD src0_sel:WORD_1
	v_cvt_f32_f16_e32 v136, v137
	v_cvt_f32_f16_sdwa v137, v137 dst_sel:DWORD dst_unused:UNUSED_PAD src0_sel:WORD_1
	v_pk_mul_f32 v[138:139], v[138:139], s[8:9] op_sel_hi:[1,0]
	s_nop 0
	v_pk_fma_f32 v[116:117], v[116:117], v[166:167], v[138:139]
	v_pk_mul_f32 v[136:137], v[136:137], s[8:9] op_sel_hi:[1,0]
	s_nop 0
	v_pk_fma_f32 v[118:119], v[118:119], v[168:169], v[136:137]
	ds_read_b64 v[136:137], v154 offset:16384
	s_waitcnt lgkmcnt(0)
	v_cvt_f32_f16_e32 v138, v136
	v_cvt_f32_f16_sdwa v139, v136 dst_sel:DWORD dst_unused:UNUSED_PAD src0_sel:WORD_1
	v_cvt_f32_f16_e32 v136, v137
	v_cvt_f32_f16_sdwa v137, v137 dst_sel:DWORD dst_unused:UNUSED_PAD src0_sel:WORD_1
	v_pk_mul_f32 v[138:139], v[138:139], s[8:9] op_sel_hi:[1,0]
	s_nop 0
	v_pk_fma_f32 v[112:113], v[112:113], v[162:163], v[138:139]
	v_pk_mul_f32 v[136:137], v[136:137], s[8:9] op_sel_hi:[1,0]
	s_nop 0
	v_pk_fma_f32 v[114:115], v[114:115], v[164:165], v[136:137]
	s_nop 0
	ds_read_b64 v[136:137], v185 offset:24576
	s_waitcnt lgkmcnt(0)
	v_cvt_f32_f16_e32 v138, v136
	v_cvt_f32_f16_sdwa v139, v136 dst_sel:DWORD dst_unused:UNUSED_PAD src0_sel:WORD_1
	v_cvt_f32_f16_e32 v136, v137
	v_cvt_f32_f16_sdwa v137, v137 dst_sel:DWORD dst_unused:UNUSED_PAD src0_sel:WORD_1
	v_pk_mul_f32 v[138:139], v[138:139], s[8:9] op_sel_hi:[1,0]
	s_nop 0
	v_pk_fma_f32 v[108:109], v[108:109], v[174:175], v[138:139]
	v_pk_mul_f32 v[136:137], v[136:137], s[8:9] op_sel_hi:[1,0]
	s_nop 0
	v_pk_fma_f32 v[110:111], v[110:111], v[176:177], v[136:137]
	ds_read_b64 v[136:137], v157 offset:24576
	v_xor_b32_e32 v157, 64, v24
	s_waitcnt lgkmcnt(0)
	v_cvt_f32_f16_e32 v138, v136
	v_cvt_f32_f16_sdwa v139, v136 dst_sel:DWORD dst_unused:UNUSED_PAD src0_sel:WORD_1
	v_cvt_f32_f16_e32 v136, v137
	v_cvt_f32_f16_sdwa v137, v137 dst_sel:DWORD dst_unused:UNUSED_PAD src0_sel:WORD_1
	v_pk_mul_f32 v[138:139], v[138:139], s[8:9] op_sel_hi:[1,0]
	s_nop 0
	v_pk_fma_f32 v[104:105], v[104:105], v[170:171], v[138:139]
	v_pk_mul_f32 v[136:137], v[136:137], s[8:9] op_sel_hi:[1,0]
	s_nop 0
	v_pk_fma_f32 v[106:107], v[106:107], v[172:173], v[136:137]
	ds_read_b64 v[136:137], v153 offset:24576
	s_waitcnt lgkmcnt(0)
	v_cvt_f32_f16_e32 v138, v136
	v_cvt_f32_f16_sdwa v139, v136 dst_sel:DWORD dst_unused:UNUSED_PAD src0_sel:WORD_1
	v_cvt_f32_f16_e32 v136, v137
	v_cvt_f32_f16_sdwa v137, v137 dst_sel:DWORD dst_unused:UNUSED_PAD src0_sel:WORD_1
	v_pk_mul_f32 v[138:139], v[138:139], s[8:9] op_sel_hi:[1,0]
	s_nop 0
	v_pk_fma_f32 v[100:101], v[100:101], v[166:167], v[138:139]
	v_pk_mul_f32 v[136:137], v[136:137], s[8:9] op_sel_hi:[1,0]
	s_nop 0
	v_pk_fma_f32 v[102:103], v[102:103], v[168:169], v[136:137]
	ds_read_b64 v[136:137], v154 offset:24576
	v_pk_add_f32 v[154:155], v[4:5], v[16:17]
	v_pk_add_f32 v[16:17], v[10:11], v[146:147]
	s_waitcnt lgkmcnt(0)
	v_cvt_f32_f16_e32 v138, v136
	v_cvt_f32_f16_sdwa v139, v136 dst_sel:DWORD dst_unused:UNUSED_PAD src0_sel:WORD_1
	v_cvt_f32_f16_e32 v136, v137
	v_cvt_f32_f16_sdwa v137, v137 dst_sel:DWORD dst_unused:UNUSED_PAD src0_sel:WORD_1
	v_pk_mul_f32 v[138:139], v[138:139], s[8:9] op_sel_hi:[1,0]
	s_nop 0
	v_pk_fma_f32 v[96:97], v[96:97], v[162:163], v[138:139]
	v_pk_mul_f32 v[136:137], v[136:137], s[8:9] op_sel_hi:[1,0]
	s_nop 0
	v_pk_fma_f32 v[98:99], v[98:99], v[164:165], v[136:137]
	v_add_u32_e32 v136, v140, v182
	ds_read_b64 v[136:137], v136
	s_waitcnt lgkmcnt(0)
	v_cvt_f32_f16_e32 v138, v136
	v_cvt_f32_f16_sdwa v139, v136 dst_sel:DWORD dst_unused:UNUSED_PAD src0_sel:WORD_1
	v_cvt_f32_f16_e32 v136, v137
	v_cvt_f32_f16_sdwa v137, v137 dst_sel:DWORD dst_unused:UNUSED_PAD src0_sel:WORD_1
	v_pk_mul_f32 v[138:139], v[138:139], s[8:9] op_sel_hi:[1,0]
	s_nop 0
	v_pk_fma_f32 v[92:93], v[92:93], v[174:175], v[138:139]
	v_pk_mul_f32 v[136:137], v[136:137], s[8:9] op_sel_hi:[1,0]
	s_nop 0
	v_pk_fma_f32 v[94:95], v[94:95], v[176:177], v[136:137]
	v_add_u32_e32 v136, v140, v156
	ds_read_b64 v[136:137], v136
	s_waitcnt lgkmcnt(0)
	v_cvt_f32_f16_e32 v138, v136
	v_cvt_f32_f16_sdwa v139, v136 dst_sel:DWORD dst_unused:UNUSED_PAD src0_sel:WORD_1
	v_cvt_f32_f16_e32 v136, v137
	v_cvt_f32_f16_sdwa v137, v137 dst_sel:DWORD dst_unused:UNUSED_PAD src0_sel:WORD_1
	v_pk_mul_f32 v[138:139], v[138:139], s[8:9] op_sel_hi:[1,0]
	s_nop 0
	v_pk_fma_f32 v[88:89], v[88:89], v[170:171], v[138:139]
	v_pk_mul_f32 v[136:137], v[136:137], s[8:9] op_sel_hi:[1,0]
	s_nop 0
	v_pk_fma_f32 v[90:91], v[90:91], v[172:173], v[136:137]
	v_add_u32_e32 v136, v140, v180
	ds_read_b64 v[136:137], v136
	s_waitcnt lgkmcnt(0)
	v_cvt_f32_f16_e32 v138, v136
	v_cvt_f32_f16_sdwa v139, v136 dst_sel:DWORD dst_unused:UNUSED_PAD src0_sel:WORD_1
	v_cvt_f32_f16_e32 v136, v137
	v_cvt_f32_f16_sdwa v137, v137 dst_sel:DWORD dst_unused:UNUSED_PAD src0_sel:WORD_1
	v_pk_mul_f32 v[138:139], v[138:139], s[8:9] op_sel_hi:[1,0]
	s_nop 0
	v_pk_fma_f32 v[84:85], v[84:85], v[166:167], v[138:139]
	v_pk_mul_f32 v[136:137], v[136:137], s[8:9] op_sel_hi:[1,0]
	s_nop 0
	v_pk_fma_f32 v[86:87], v[86:87], v[168:169], v[136:137]
	v_add_u32_e32 v136, v140, v152
	ds_read_b64 v[136:137], v136
	s_waitcnt lgkmcnt(0)
	v_cvt_f32_f16_e32 v138, v136
	v_cvt_f32_f16_sdwa v139, v136 dst_sel:DWORD dst_unused:UNUSED_PAD src0_sel:WORD_1
	v_cvt_f32_f16_e32 v136, v137
	v_cvt_f32_f16_sdwa v137, v137 dst_sel:DWORD dst_unused:UNUSED_PAD src0_sel:WORD_1
	v_pk_mul_f32 v[138:139], v[138:139], s[8:9] op_sel_hi:[1,0]
	s_nop 0
	v_pk_fma_f32 v[80:81], v[80:81], v[162:163], v[138:139]
	v_pk_mul_f32 v[136:137], v[136:137], s[8:9] op_sel_hi:[1,0]
	s_nop 0
	v_pk_fma_f32 v[82:83], v[82:83], v[164:165], v[136:137]
	v_add_u32_e32 v136, 0x12000, v184
	v_and_b32_e32 v136, 0xffffbc00, v136
	v_add_u32_e32 v140, v183, v136
	v_add_u32_e32 v136, v140, v182
	ds_read_b64 v[136:137], v136
	s_waitcnt lgkmcnt(0)
	v_cvt_f32_f16_e32 v138, v136
	v_cvt_f32_f16_sdwa v139, v136 dst_sel:DWORD dst_unused:UNUSED_PAD src0_sel:WORD_1
	v_cvt_f32_f16_e32 v136, v137
	v_cvt_f32_f16_sdwa v137, v137 dst_sel:DWORD dst_unused:UNUSED_PAD src0_sel:WORD_1
	v_pk_mul_f32 v[138:139], v[138:139], s[8:9] op_sel_hi:[1,0]
	s_nop 0
	v_pk_fma_f32 v[76:77], v[76:77], v[174:175], v[138:139]
	v_pk_mul_f32 v[136:137], v[136:137], s[8:9] op_sel_hi:[1,0]
	s_nop 0
	v_pk_fma_f32 v[78:79], v[78:79], v[176:177], v[136:137]
	v_add_u32_e32 v136, v140, v156
	ds_read_b64 v[136:137], v136
	s_waitcnt lgkmcnt(0)
	v_cvt_f32_f16_e32 v138, v136
	v_cvt_f32_f16_sdwa v139, v136 dst_sel:DWORD dst_unused:UNUSED_PAD src0_sel:WORD_1
	v_cvt_f32_f16_e32 v136, v137
	v_cvt_f32_f16_sdwa v137, v137 dst_sel:DWORD dst_unused:UNUSED_PAD src0_sel:WORD_1
	v_pk_mul_f32 v[138:139], v[138:139], s[8:9] op_sel_hi:[1,0]
	s_nop 0
	v_pk_fma_f32 v[72:73], v[72:73], v[170:171], v[138:139]
	v_pk_mul_f32 v[136:137], v[136:137], s[8:9] op_sel_hi:[1,0]
	s_nop 0
	v_pk_fma_f32 v[74:75], v[74:75], v[172:173], v[136:137]
	v_add_u32_e32 v136, v140, v180
	ds_read_b64 v[136:137], v136
	s_waitcnt lgkmcnt(0)
	v_cvt_f32_f16_e32 v138, v136
	v_cvt_f32_f16_sdwa v139, v136 dst_sel:DWORD dst_unused:UNUSED_PAD src0_sel:WORD_1
	v_cvt_f32_f16_e32 v136, v137
	v_cvt_f32_f16_sdwa v137, v137 dst_sel:DWORD dst_unused:UNUSED_PAD src0_sel:WORD_1
	v_pk_mul_f32 v[138:139], v[138:139], s[8:9] op_sel_hi:[1,0]
	s_nop 0
	v_pk_fma_f32 v[68:69], v[68:69], v[166:167], v[138:139]
	v_pk_mul_f32 v[136:137], v[136:137], s[8:9] op_sel_hi:[1,0]
	s_nop 0
	v_pk_fma_f32 v[70:71], v[70:71], v[168:169], v[136:137]
	v_add_u32_e32 v136, v140, v152
	ds_read_b64 v[136:137], v136
	v_add_u32_e32 v140, 0x14000, v181
	s_waitcnt lgkmcnt(0)
	v_cvt_f32_f16_e32 v138, v136
	v_cvt_f32_f16_sdwa v139, v136 dst_sel:DWORD dst_unused:UNUSED_PAD src0_sel:WORD_1
	v_cvt_f32_f16_e32 v136, v137
	v_cvt_f32_f16_sdwa v137, v137 dst_sel:DWORD dst_unused:UNUSED_PAD src0_sel:WORD_1
	v_pk_mul_f32 v[138:139], v[138:139], s[8:9] op_sel_hi:[1,0]
	s_nop 0
	v_pk_fma_f32 v[64:65], v[64:65], v[162:163], v[138:139]
	v_pk_mul_f32 v[136:137], v[136:137], s[8:9] op_sel_hi:[1,0]
	s_nop 0
	v_pk_fma_f32 v[66:67], v[66:67], v[164:165], v[136:137]
	v_add_u32_e32 v136, v140, v182
	ds_read_b64 v[136:137], v136
	s_waitcnt lgkmcnt(0)
	v_cvt_f32_f16_e32 v138, v136
	v_cvt_f32_f16_sdwa v139, v136 dst_sel:DWORD dst_unused:UNUSED_PAD src0_sel:WORD_1
	v_cvt_f32_f16_e32 v136, v137
	v_cvt_f32_f16_sdwa v137, v137 dst_sel:DWORD dst_unused:UNUSED_PAD src0_sel:WORD_1
	v_pk_mul_f32 v[138:139], v[138:139], s[8:9] op_sel_hi:[1,0]
	s_nop 0
	v_pk_fma_f32 v[60:61], v[60:61], v[174:175], v[138:139]
	v_pk_mul_f32 v[136:137], v[136:137], s[8:9] op_sel_hi:[1,0]
	s_nop 0
	v_pk_fma_f32 v[62:63], v[62:63], v[176:177], v[136:137]
	v_add_u32_e32 v136, v140, v156
	ds_read_b64 v[136:137], v136
	s_waitcnt lgkmcnt(0)
	v_cvt_f32_f16_e32 v138, v136
	v_cvt_f32_f16_sdwa v139, v136 dst_sel:DWORD dst_unused:UNUSED_PAD src0_sel:WORD_1
	v_cvt_f32_f16_e32 v136, v137
	v_cvt_f32_f16_sdwa v137, v137 dst_sel:DWORD dst_unused:UNUSED_PAD src0_sel:WORD_1
	v_pk_mul_f32 v[138:139], v[138:139], s[8:9] op_sel_hi:[1,0]
	s_nop 0
	v_pk_fma_f32 v[56:57], v[56:57], v[170:171], v[138:139]
	v_pk_mul_f32 v[136:137], v[136:137], s[8:9] op_sel_hi:[1,0]
	s_nop 0
	v_pk_fma_f32 v[58:59], v[58:59], v[172:173], v[136:137]
	v_add_u32_e32 v136, v140, v180
	ds_read_b64 v[136:137], v136
	s_waitcnt lgkmcnt(0)
	v_cvt_f32_f16_e32 v138, v136
	v_cvt_f32_f16_sdwa v139, v136 dst_sel:DWORD dst_unused:UNUSED_PAD src0_sel:WORD_1
	v_cvt_f32_f16_e32 v136, v137
	v_cvt_f32_f16_sdwa v137, v137 dst_sel:DWORD dst_unused:UNUSED_PAD src0_sel:WORD_1
	v_pk_mul_f32 v[138:139], v[138:139], s[8:9] op_sel_hi:[1,0]
	s_nop 0
	v_pk_fma_f32 v[52:53], v[52:53], v[166:167], v[138:139]
	v_pk_mul_f32 v[136:137], v[136:137], s[8:9] op_sel_hi:[1,0]
	s_nop 0
	v_pk_fma_f32 v[54:55], v[54:55], v[168:169], v[136:137]
	v_add_u32_e32 v136, v140, v152
	ds_read_b64 v[136:137], v136
	v_add_u32_e32 v140, 0x16000, v181
	s_waitcnt lgkmcnt(0)
	v_cvt_f32_f16_e32 v138, v136
	v_cvt_f32_f16_sdwa v139, v136 dst_sel:DWORD dst_unused:UNUSED_PAD src0_sel:WORD_1
	v_cvt_f32_f16_e32 v136, v137
	v_cvt_f32_f16_sdwa v137, v137 dst_sel:DWORD dst_unused:UNUSED_PAD src0_sel:WORD_1
	v_pk_mul_f32 v[138:139], v[138:139], s[8:9] op_sel_hi:[1,0]
	s_nop 0
	v_pk_fma_f32 v[48:49], v[48:49], v[162:163], v[138:139]
	v_pk_mul_f32 v[136:137], v[136:137], s[8:9] op_sel_hi:[1,0]
	s_nop 0
	v_pk_fma_f32 v[50:51], v[50:51], v[164:165], v[136:137]
	v_add_u32_e32 v136, v140, v182
	ds_read_b64 v[136:137], v136
	s_waitcnt lgkmcnt(0)
	v_cvt_f32_f16_e32 v138, v136
	v_cvt_f32_f16_sdwa v139, v136 dst_sel:DWORD dst_unused:UNUSED_PAD src0_sel:WORD_1
	v_cvt_f32_f16_e32 v136, v137
	v_cvt_f32_f16_sdwa v137, v137 dst_sel:DWORD dst_unused:UNUSED_PAD src0_sel:WORD_1
	v_pk_mul_f32 v[138:139], v[138:139], s[8:9] op_sel_hi:[1,0]
	s_nop 0
	v_pk_fma_f32 v[44:45], v[44:45], v[174:175], v[138:139]
	v_pk_mul_f32 v[136:137], v[136:137], s[8:9] op_sel_hi:[1,0]
	s_nop 0
	v_pk_fma_f32 v[46:47], v[46:47], v[176:177], v[136:137]
	v_add_u32_e32 v136, v140, v156
	ds_read_b64 v[136:137], v136
	v_xor_b32_e32 v156, 0x80, v24
	s_waitcnt lgkmcnt(0)
	v_cvt_f32_f16_e32 v138, v136
	v_cvt_f32_f16_sdwa v139, v136 dst_sel:DWORD dst_unused:UNUSED_PAD src0_sel:WORD_1
	v_cvt_f32_f16_e32 v136, v137
	v_cvt_f32_f16_sdwa v137, v137 dst_sel:DWORD dst_unused:UNUSED_PAD src0_sel:WORD_1
	v_pk_mul_f32 v[138:139], v[138:139], s[8:9] op_sel_hi:[1,0]
	s_nop 0
	v_pk_fma_f32 v[40:41], v[40:41], v[170:171], v[138:139]
	v_pk_mul_f32 v[136:137], v[136:137], s[8:9] op_sel_hi:[1,0]
	s_nop 0
	v_pk_fma_f32 v[42:43], v[42:43], v[172:173], v[136:137]
	v_add_u32_e32 v136, v140, v180
	ds_read_b64 v[136:137], v136
	s_waitcnt lgkmcnt(0)
	v_cvt_f32_f16_e32 v138, v136
	v_cvt_f32_f16_sdwa v139, v136 dst_sel:DWORD dst_unused:UNUSED_PAD src0_sel:WORD_1
	v_cvt_f32_f16_e32 v136, v137
	v_cvt_f32_f16_sdwa v137, v137 dst_sel:DWORD dst_unused:UNUSED_PAD src0_sel:WORD_1
	v_pk_mul_f32 v[138:139], v[138:139], s[8:9] op_sel_hi:[1,0]
	s_nop 0
	v_pk_fma_f32 v[36:37], v[36:37], v[166:167], v[138:139]
	v_pk_mul_f32 v[136:137], v[136:137], s[8:9] op_sel_hi:[1,0]
	s_nop 0
	v_pk_fma_f32 v[38:39], v[38:39], v[168:169], v[136:137]
	v_add_u32_e32 v136, v140, v152
	ds_read_b64 v[136:137], v136
	v_pk_add_f32 v[152:153], v[6:7], v[18:19]
	v_pk_add_f32 v[140:141], v[2:3], v[26:27]
	v_pk_mov_b32 v[24:25], v[154:155], v[152:153] op_sel:[1,0]
	v_mov_b32_e32 v26, v154
	s_waitcnt lgkmcnt(0)
	v_cvt_f32_f16_e32 v138, v136
	v_cvt_f32_f16_sdwa v139, v136 dst_sel:DWORD dst_unused:UNUSED_PAD src0_sel:WORD_1
	v_cvt_f32_f16_e32 v136, v137
	v_cvt_f32_f16_sdwa v137, v137 dst_sel:DWORD dst_unused:UNUSED_PAD src0_sel:WORD_1
	v_mov_b32_e32 v27, v153
	v_pk_add_f32 v[18:19], v[8:9], v[144:145]
	v_pk_add_f32 v[24:25], v[24:25], v[26:27]
	v_pk_mov_b32 v[26:27], v[142:143], v[140:141] op_sel:[1,0]
	v_mov_b32_e32 v144, v142
	v_mov_b32_e32 v145, v141
	v_pk_mul_f32 v[138:139], v[138:139], s[8:9] op_sel_hi:[1,0]
	v_pk_mul_f32 v[136:137], v[136:137], s[8:9] op_sel_hi:[1,0]
	v_pk_add_f32 v[26:27], v[26:27], v[144:145]
	v_pk_fma_f32 v[34:35], v[34:35], v[164:165], v[136:137]
	v_pk_fma_f32 v[32:33], v[32:33], v[162:163], v[138:139]
	v_pk_add_f32 v[136:137], v[14:15], v[150:151]
	v_pk_add_f32 v[138:139], v[12:13], v[148:149]
	v_add_f32_e32 v24, v24, v25
	v_pk_add_f32 v[26:27], v[26:27], v[26:27] op_sel_hi:[0,1]
	v_add_f32_e32 v25, 0, v24
	v_add_f32_e32 v145, v138, v139
	v_add_f32_e32 v147, v136, v137
	v_mov_b32_e32 v144, v18
	v_mov_b32_e32 v146, v19
	v_mov_b32_e32 v26, v16
	v_mov_b32_e32 v24, v17
	v_pk_add_f32 v[144:145], v[144:145], v[146:147]
	v_pk_add_f32 v[24:25], v[26:27], v[24:25]
	s_waitcnt lgkmcnt(0)
	s_barrier
	v_pk_add_f32 v[24:25], v[144:145], v[24:25]
	s_nop 0
	v_add_f32_e32 v24, v24, v25
	s_mov_b32 s100, 0xffff0000
	s_mov_b32 s101, 0xffff0000
	s_mov_b32 s98, 0
	s_mov_b32 s99, -1
	v_mov_b32_e32 v25, v24
	v_mov_b32_e32 v210, v24
	s_nop 1
	v_permlane16_swap_b32_e32 v25, v210
	v_cndmask_b32_e64 v25, v210, v25, s[100:101]
	s_waitcnt lgkmcnt(0)
	v_add_f32_e32 v24, v24, v25
	v_mov_b32_e32 v25, v24
	v_mov_b32_e32 v210, v24
	s_nop 1
	v_permlane32_swap_b32_e32 v25, v210
	v_cndmask_b32_e64 v25, v210, v25, s[98:99]
	s_waitcnt lgkmcnt(0)
	v_add_f32_e32 v24, v24, v25
	v_fmamk_f32 v26, v24, 0xbc800000, v153
	v_fmamk_f32 v144, v24, 0xbc800000, v155
	v_fmamk_f32 v25, v24, 0xbc800000, v152
	v_fmamk_f32 v27, v24, 0xbc800000, v154
	v_mul_f32_e32 v144, v144, v144
	v_mul_f32_e32 v26, v26, v26
	v_fmac_f32_e32 v144, v27, v27
	v_fmac_f32_e32 v26, v25, v25
	v_fmamk_f32 v27, v24, 0xbc800000, v141
	v_fmamk_f32 v145, v24, 0xbc800000, v143
	v_add_f32_e32 v25, v144, v26
	v_fmamk_f32 v26, v24, 0xbc800000, v140
	v_fmamk_f32 v144, v24, 0xbc800000, v142
	v_mul_f32_e32 v145, v145, v145
	v_mul_f32_e32 v27, v27, v27
	v_fmac_f32_e32 v145, v144, v144
	v_fmac_f32_e32 v27, v26, v26
	v_add_f32_e32 v26, v145, v27
	v_fmamk_f32 v27, v24, 0xbc800000, v137
	v_fmamk_f32 v145, v24, 0xbc800000, v139
	v_add_f32_e32 v25, v25, v26
	v_fmamk_f32 v26, v24, 0xbc800000, v136
	v_fmamk_f32 v144, v24, 0xbc800000, v138
	v_mul_f32_e32 v145, v145, v145
	v_mul_f32_e32 v27, v27, v27
	v_fmac_f32_e32 v145, v144, v144
	v_fmac_f32_e32 v27, v26, v26
	v_add_f32_e32 v26, v145, v27
	v_fmamk_f32 v27, v24, 0xbc800000, v17
	v_fmamk_f32 v145, v24, 0xbc800000, v19
	v_add_f32_e32 v25, v26, v25
	v_fmamk_f32 v26, v24, 0xbc800000, v16
	v_fmamk_f32 v144, v24, 0xbc800000, v18
	v_mul_f32_e32 v145, v145, v145
	v_mul_f32_e32 v27, v27, v27
	v_fmac_f32_e32 v145, v144, v144
	v_fmac_f32_e32 v27, v26, v26
	v_add_f32_e32 v26, v145, v27
	v_add_f32_e32 v25, v26, v25
	v_mov_b32_e32 v26, v25
	v_mov_b32_e32 v210, v25
	s_nop 1
	v_permlane16_swap_b32_e32 v26, v210
	v_cndmask_b32_e64 v26, v210, v26, s[100:101]
	s_waitcnt lgkmcnt(0)
	v_add_f32_e32 v25, v25, v26
	v_mov_b32_e32 v26, v25
	v_mov_b32_e32 v210, v25
	s_nop 1
	v_permlane32_swap_b32_e32 v26, v210
	v_cndmask_b32_e64 v26, v210, v26, s[98:99]
	s_and_saveexec_b64 s[8:9], vcc
	s_cbranch_execz .LBB0_417
	s_lshl_b32 s3, s22, 11
	s_add_i32 s3, s12, s3
	v_mul_f32_e32 v24, 0x3c800000, v24
	s_waitcnt lgkmcnt(0)
	v_add_f32_e32 v25, v25, v26
	v_lshl_add_u32 v26, v178, 5, s3
	ds_write_b64 v26, v[24:25]
.LBB0_417:
	s_or_b64 exec, exec, s[8:9]
	v_max_f32_e64 v24, |v153|, |v153|
	v_max_f32_e64 v25, |v152|, |v152|
	v_max_f32_e32 v24, v25, v24
	v_max_f32_e64 v25, |v141|, |v141|
	s_waitcnt lgkmcnt(0)
	v_max_f32_e64 v26, |v140|, |v140|
	v_max_f32_e32 v25, v26, v25
	v_max3_f32 v24, |v154|, |v155|, v24
	v_max3_f32 v25, |v142|, |v143|, v25
	v_max3_f32 v24, v24, 0, v25
	v_max_f32_e64 v25, |v137|, |v137|
	v_max_f32_e64 v26, |v136|, |v136|
	v_max_f32_e32 v25, v26, v25
	v_max_f32_e64 v26, |v17|, |v17|
	v_max_f32_e64 v27, |v16|, |v16|
	v_max_f32_e32 v26, v27, v26
	v_max3_f32 v25, |v138|, |v139|, v25
	v_max3_f32 v26, |v18|, |v19|, v26
	v_max3_f32 v24, v24, v25, v26
	v_mov_b32_e32 v25, v24
	v_mov_b32_e32 v210, v24
	s_nop 1
	v_permlane16_swap_b32_e32 v25, v210
	v_cndmask_b32_e64 v25, v210, v25, s[100:101]
	s_sub_i32 s11, s12, s11
	s_waitcnt lgkmcnt(0)
	v_max_f32_e32 v25, v25, v25
	v_max_f32_e32 v24, v24, v25
	v_mov_b32_e32 v25, v24
	v_mov_b32_e32 v210, v24
	s_nop 1
	v_permlane32_swap_b32_e32 v25, v210
	v_cndmask_b32_e64 v25, v210, v25, s[98:99]
	s_and_saveexec_b64 s[8:9], vcc
	s_cbranch_execz .LBB0_419
	s_lshl_b32 s3, s22, 10
	s_waitcnt lgkmcnt(0)
	v_max_f32_e32 v25, v25, v25
	v_max_f32_e32 v24, v24, v24
	s_add_i32 s3, s11, s3
	v_max_f32_e32 v24, v24, v25
	v_lshl_add_u32 v25, v178, 4, s3
	ds_write_b32 v25, v24 offset:16384
.LBB0_419:
	s_or_b64 exec, exec, s[8:9]
	v_pk_add_f32 v[150:151], v[6:7], v[22:23]
	v_pk_add_f32 v[148:149], v[4:5], v[20:21]
	v_pk_add_f32 v[144:145], v[2:3], v[30:31]
	v_pk_add_f32 v[146:147], v[0:1], v[28:29]
	v_pk_add_f32 v[134:135], v[14:15], v[134:135]
	v_pk_add_f32 v[132:133], v[12:13], v[132:133]
	v_pk_add_f32 v[20:21], v[10:11], v[130:131]
	v_pk_add_f32 v[22:23], v[8:9], v[128:129]
	s_waitcnt lgkmcnt(0)
	v_pk_mov_b32 v[24:25], v[148:149], v[150:151] op_sel:[1,0]
	v_mov_b32_e32 v26, v148
	v_mov_b32_e32 v27, v151
	v_pk_add_f32 v[24:25], v[24:25], v[26:27]
	v_pk_mov_b32 v[26:27], v[146:147], v[144:145] op_sel:[1,0]
	v_mov_b32_e32 v28, v146
	v_mov_b32_e32 v29, v145
	v_pk_add_f32 v[26:27], v[26:27], v[28:29]
	v_add_f32_e32 v24, v24, v25
	v_pk_add_f32 v[26:27], v[26:27], v[26:27] op_sel_hi:[0,1]
	v_add_f32_e32 v25, 0, v24
	v_add_f32_e32 v29, v132, v133
	v_add_f32_e32 v31, v134, v135
	v_mov_b32_e32 v28, v22
	v_mov_b32_e32 v30, v23
	v_mov_b32_e32 v26, v20
	v_mov_b32_e32 v24, v21
	v_pk_add_f32 v[28:29], v[28:29], v[30:31]
	v_pk_add_f32 v[24:25], v[26:27], v[24:25]
	s_nop 0
	v_pk_add_f32 v[24:25], v[28:29], v[24:25]
	s_nop 0
	v_add_f32_e32 v24, v24, v25
	v_mov_b32_e32 v25, v24
	v_mov_b32_e32 v210, v24
	s_nop 1
	v_permlane16_swap_b32_e32 v25, v210
	v_cndmask_b32_e64 v25, v210, v25, s[100:101]
	s_waitcnt lgkmcnt(0)
	v_add_f32_e32 v24, v24, v25
	v_mov_b32_e32 v25, v24
	v_mov_b32_e32 v210, v24
	s_nop 1
	v_permlane32_swap_b32_e32 v25, v210
	v_cndmask_b32_e64 v25, v210, v25, s[98:99]
	s_waitcnt lgkmcnt(0)
	v_add_f32_e32 v24, v24, v25
	v_fmamk_f32 v26, v24, 0xbc800000, v151
	v_fmamk_f32 v28, v24, 0xbc800000, v149
	v_fmamk_f32 v25, v24, 0xbc800000, v150
	v_fmamk_f32 v27, v24, 0xbc800000, v148
	v_mul_f32_e32 v28, v28, v28
	v_mul_f32_e32 v26, v26, v26
	v_fmac_f32_e32 v28, v27, v27
	v_fmac_f32_e32 v26, v25, v25
	v_fmamk_f32 v27, v24, 0xbc800000, v145
	v_fmamk_f32 v29, v24, 0xbc800000, v147
	v_add_f32_e32 v25, v28, v26
	v_fmamk_f32 v26, v24, 0xbc800000, v144
	v_fmamk_f32 v28, v24, 0xbc800000, v146
	v_mul_f32_e32 v29, v29, v29
	v_mul_f32_e32 v27, v27, v27
	v_fmac_f32_e32 v29, v28, v28
	v_fmac_f32_e32 v27, v26, v26
	v_add_f32_e32 v26, v29, v27
	v_fmamk_f32 v27, v24, 0xbc800000, v135
	v_fmamk_f32 v29, v24, 0xbc800000, v133
	v_add_f32_e32 v25, v25, v26
	v_fmamk_f32 v26, v24, 0xbc800000, v134
	v_fmamk_f32 v28, v24, 0xbc800000, v132
	v_mul_f32_e32 v29, v29, v29
	v_mul_f32_e32 v27, v27, v27
	v_fmac_f32_e32 v29, v28, v28
	v_fmac_f32_e32 v27, v26, v26
	v_add_f32_e32 v26, v29, v27
	v_fmamk_f32 v27, v24, 0xbc800000, v21
	v_fmamk_f32 v29, v24, 0xbc800000, v23
	v_add_f32_e32 v25, v26, v25
	v_fmamk_f32 v26, v24, 0xbc800000, v20
	v_fmamk_f32 v28, v24, 0xbc800000, v22
	v_mul_f32_e32 v29, v29, v29
	v_mul_f32_e32 v27, v27, v27
	v_fmac_f32_e32 v29, v28, v28
	v_fmac_f32_e32 v27, v26, v26
	v_add_f32_e32 v26, v29, v27
	v_add_f32_e32 v25, v26, v25
	v_mov_b32_e32 v26, v25
	v_mov_b32_e32 v210, v25
	s_nop 1
	v_permlane16_swap_b32_e32 v26, v210
	v_cndmask_b32_e64 v26, v210, v26, s[100:101]
	s_waitcnt lgkmcnt(0)
	v_add_f32_e32 v25, v25, v26
	v_mov_b32_e32 v26, v25
	v_mov_b32_e32 v210, v25
	s_nop 1
	v_permlane32_swap_b32_e32 v26, v210
	v_cndmask_b32_e64 v26, v210, v26, s[98:99]
	s_and_saveexec_b64 s[8:9], vcc
	s_cbranch_execz .LBB0_421
	s_lshl_b32 s3, s22, 11
	s_add_i32 s3, s12, s3
	v_mul_f32_e32 v24, 0x3c800000, v24
	s_waitcnt lgkmcnt(0)
	v_add_f32_e32 v25, v25, v26
	v_lshl_add_u32 v26, v178, 5, s3
	ds_write_b64 v26, v[24:25] offset:512
.LBB0_421:
	s_or_b64 exec, exec, s[8:9]
	v_max_f32_e64 v24, |v151|, |v151|
	v_max_f32_e64 v25, |v150|, |v150|
	v_max_f32_e32 v24, v25, v24
	v_max_f32_e64 v25, |v145|, |v145|
	s_waitcnt lgkmcnt(0)
	v_max_f32_e64 v26, |v144|, |v144|
	v_max_f32_e32 v25, v26, v25
	v_max3_f32 v24, |v148|, |v149|, v24
	v_max3_f32 v25, |v146|, |v147|, v25
	v_max3_f32 v24, v24, 0, v25
	v_max_f32_e64 v25, |v135|, |v135|
	v_max_f32_e64 v26, |v134|, |v134|
	v_max_f32_e32 v25, v26, v25
	v_max_f32_e64 v26, |v21|, |v21|
	v_max_f32_e64 v27, |v20|, |v20|
	v_max_f32_e32 v26, v27, v26
	v_max3_f32 v25, |v132|, |v133|, v25
	v_max3_f32 v26, |v22|, |v23|, v26
	v_max3_f32 v24, v24, v25, v26
	v_mov_b32_e32 v25, v24
	v_mov_b32_e32 v210, v24
	s_nop 1
	v_permlane16_swap_b32_e32 v25, v210
	v_cndmask_b32_e64 v25, v210, v25, s[100:101]
	s_waitcnt lgkmcnt(0)
	v_max_f32_e32 v25, v25, v25
	v_max_f32_e32 v24, v24, v25
	v_mov_b32_e32 v25, v24
	v_mov_b32_e32 v210, v24
	s_nop 1
	v_permlane32_swap_b32_e32 v25, v210
	v_cndmask_b32_e64 v25, v210, v25, s[98:99]
	s_and_saveexec_b64 s[8:9], vcc
	s_cbranch_execz .LBB0_423
	s_lshl_b32 s3, s22, 10
	s_waitcnt lgkmcnt(0)
	v_max_f32_e32 v25, v25, v25
	v_max_f32_e32 v24, v24, v24
	s_add_i32 s3, s11, s3
	v_max_f32_e32 v24, v24, v25
	v_lshl_add_u32 v25, v178, 4, s3
	ds_write_b32 v25, v24 offset:16640
.LBB0_423:
	s_or_b64 exec, exec, s[8:9]
	v_pk_add_f32 v[126:127], v[6:7], v[126:127]
	v_pk_add_f32 v[124:125], v[4:5], v[124:125]
	v_pk_add_f32 v[122:123], v[2:3], v[122:123]
	v_pk_add_f32 v[120:121], v[0:1], v[120:121]
	v_pk_add_f32 v[118:119], v[14:15], v[118:119]
	v_pk_add_f32 v[116:117], v[12:13], v[116:117]
	v_pk_add_f32 v[26:27], v[10:11], v[114:115]
	s_waitcnt lgkmcnt(0)
	v_pk_add_f32 v[24:25], v[8:9], v[112:113]
	v_pk_mov_b32 v[28:29], v[124:125], v[126:127] op_sel:[1,0]
	v_mov_b32_e32 v30, v124
	v_mov_b32_e32 v31, v127
	v_pk_add_f32 v[28:29], v[28:29], v[30:31]
	v_pk_mov_b32 v[30:31], v[120:121], v[122:123] op_sel:[1,0]
	v_mov_b32_e32 v112, v120
	v_mov_b32_e32 v113, v123
	v_pk_add_f32 v[30:31], v[30:31], v[112:113]
	v_add_f32_e32 v28, v28, v29
	v_pk_add_f32 v[30:31], v[30:31], v[30:31] op_sel_hi:[0,1]
	v_add_f32_e32 v29, 0, v28
	v_add_f32_e32 v113, v116, v117
	v_add_f32_e32 v115, v118, v119
	v_mov_b32_e32 v112, v24
	v_mov_b32_e32 v114, v25
	v_mov_b32_e32 v30, v26
	v_mov_b32_e32 v28, v27
	v_pk_add_f32 v[112:113], v[112:113], v[114:115]
	v_pk_add_f32 v[28:29], v[30:31], v[28:29]
	s_nop 0
	v_pk_add_f32 v[28:29], v[112:113], v[28:29]
	s_nop 0
	v_add_f32_e32 v28, v28, v29
	v_mov_b32_e32 v29, v28
	v_mov_b32_e32 v210, v28
	s_nop 1
	v_permlane16_swap_b32_e32 v29, v210
	v_cndmask_b32_e64 v29, v210, v29, s[100:101]
	s_waitcnt lgkmcnt(0)
	v_add_f32_e32 v28, v28, v29
	v_mov_b32_e32 v29, v28
	v_mov_b32_e32 v210, v28
	s_nop 1
	v_permlane32_swap_b32_e32 v29, v210
	v_cndmask_b32_e64 v29, v210, v29, s[98:99]
	s_waitcnt lgkmcnt(0)
	v_add_f32_e32 v28, v28, v29
	v_fmamk_f32 v30, v28, 0xbc800000, v127
	v_fmamk_f32 v112, v28, 0xbc800000, v125
	v_fmamk_f32 v29, v28, 0xbc800000, v126
	v_fmamk_f32 v31, v28, 0xbc800000, v124
	v_mul_f32_e32 v112, v112, v112
	v_mul_f32_e32 v30, v30, v30
	v_fmac_f32_e32 v112, v31, v31
	v_fmac_f32_e32 v30, v29, v29
	v_fmamk_f32 v31, v28, 0xbc800000, v123
	v_fmamk_f32 v113, v28, 0xbc800000, v121
	v_add_f32_e32 v29, v112, v30
	v_fmamk_f32 v30, v28, 0xbc800000, v122
	v_fmamk_f32 v112, v28, 0xbc800000, v120
	v_mul_f32_e32 v113, v113, v113
	v_mul_f32_e32 v31, v31, v31
	v_fmac_f32_e32 v113, v112, v112
	v_fmac_f32_e32 v31, v30, v30
	v_add_f32_e32 v30, v113, v31
	v_fmamk_f32 v31, v28, 0xbc800000, v119
	v_fmamk_f32 v113, v28, 0xbc800000, v117
	v_add_f32_e32 v29, v29, v30
	v_fmamk_f32 v30, v28, 0xbc800000, v118
	v_fmamk_f32 v112, v28, 0xbc800000, v116
	v_mul_f32_e32 v113, v113, v113
	v_mul_f32_e32 v31, v31, v31
	v_fmac_f32_e32 v113, v112, v112
	v_fmac_f32_e32 v31, v30, v30
	v_add_f32_e32 v30, v113, v31
	v_fmamk_f32 v31, v28, 0xbc800000, v27
	v_fmamk_f32 v113, v28, 0xbc800000, v25
	v_add_f32_e32 v29, v30, v29
	v_fmamk_f32 v30, v28, 0xbc800000, v26
	v_fmamk_f32 v112, v28, 0xbc800000, v24
	v_mul_f32_e32 v113, v113, v113
	v_mul_f32_e32 v31, v31, v31
	v_fmac_f32_e32 v113, v112, v112
	v_fmac_f32_e32 v31, v30, v30
	v_add_f32_e32 v30, v113, v31
	v_add_f32_e32 v29, v30, v29
	v_mov_b32_e32 v30, v29
	v_mov_b32_e32 v210, v29
	s_nop 1
	v_permlane16_swap_b32_e32 v30, v210
	v_cndmask_b32_e64 v30, v210, v30, s[100:101]
	s_waitcnt lgkmcnt(0)
	v_add_f32_e32 v29, v29, v30
	v_mov_b32_e32 v30, v29
	v_mov_b32_e32 v210, v29
	s_nop 1
	v_permlane32_swap_b32_e32 v30, v210
	v_cndmask_b32_e64 v30, v210, v30, s[98:99]
	s_and_saveexec_b64 s[8:9], vcc
	s_cbranch_execz .LBB0_425
	s_lshl_b32 s3, s22, 11
	s_add_i32 s3, s12, s3
	v_mul_f32_e32 v28, 0x3c800000, v28
	s_waitcnt lgkmcnt(0)
	v_add_f32_e32 v29, v29, v30
	v_lshl_add_u32 v30, v178, 5, s3
	ds_write_b64 v30, v[28:29] offset:1024
.LBB0_425:
	s_or_b64 exec, exec, s[8:9]
	v_max_f32_e64 v28, |v127|, |v127|
	v_max_f32_e64 v29, |v126|, |v126|
	v_max_f32_e32 v28, v29, v28
	v_max_f32_e64 v29, |v123|, |v123|
	s_waitcnt lgkmcnt(0)
	v_max_f32_e64 v30, |v122|, |v122|
	v_max_f32_e32 v29, v30, v29
	v_max3_f32 v28, |v124|, |v125|, v28
	v_max3_f32 v29, |v120|, |v121|, v29
	v_max3_f32 v28, v28, 0, v29
	v_max_f32_e64 v29, |v119|, |v119|
	v_max_f32_e64 v30, |v118|, |v118|
	v_max_f32_e32 v29, v30, v29
	v_max_f32_e64 v30, |v27|, |v27|
	v_max_f32_e64 v31, |v26|, |v26|
	v_max_f32_e32 v30, v31, v30
	v_max3_f32 v29, |v116|, |v117|, v29
	v_max3_f32 v30, |v24|, |v25|, v30
	v_max3_f32 v28, v28, v29, v30
	v_mov_b32_e32 v29, v28
	v_mov_b32_e32 v210, v28
	s_nop 1
	v_permlane16_swap_b32_e32 v29, v210
	v_cndmask_b32_e64 v29, v210, v29, s[100:101]
	s_waitcnt lgkmcnt(0)
	v_max_f32_e32 v29, v29, v29
	v_max_f32_e32 v28, v28, v29
	v_mov_b32_e32 v29, v28
	v_mov_b32_e32 v210, v28
	s_nop 1
	v_permlane32_swap_b32_e32 v29, v210
	v_cndmask_b32_e64 v29, v210, v29, s[98:99]
	s_and_saveexec_b64 s[8:9], vcc
	s_cbranch_execz .LBB0_427
	s_lshl_b32 s3, s22, 10
	s_waitcnt lgkmcnt(0)
	v_max_f32_e32 v29, v29, v29
	v_max_f32_e32 v28, v28, v28
	s_add_i32 s3, s11, s3
	v_max_f32_e32 v28, v28, v29
	v_lshl_add_u32 v29, v178, 4, s3
	ds_write_b32 v29, v28 offset:16896
.LBB0_427:
	s_or_b64 exec, exec, s[8:9]
	v_pk_add_f32 v[110:111], v[6:7], v[110:111]
	v_pk_add_f32 v[108:109], v[4:5], v[108:109]
	v_pk_add_f32 v[106:107], v[2:3], v[106:107]
	v_pk_add_f32 v[104:105], v[0:1], v[104:105]
	v_pk_add_f32 v[102:103], v[14:15], v[102:103]
	v_pk_add_f32 v[100:101], v[12:13], v[100:101]
	s_waitcnt lgkmcnt(0)
	v_pk_add_f32 v[28:29], v[10:11], v[98:99]
	v_pk_add_f32 v[30:31], v[8:9], v[96:97]
	v_pk_mov_b32 v[96:97], v[108:109], v[110:111] op_sel:[1,0]
	v_mov_b32_e32 v98, v108
	v_mov_b32_e32 v99, v111
	v_pk_add_f32 v[96:97], v[96:97], v[98:99]
	v_pk_mov_b32 v[98:99], v[104:105], v[106:107] op_sel:[1,0]
	v_mov_b32_e32 v112, v104
	v_mov_b32_e32 v113, v107
	v_pk_add_f32 v[98:99], v[98:99], v[112:113]
	v_add_f32_e32 v96, v96, v97
	v_pk_add_f32 v[98:99], v[98:99], v[98:99] op_sel_hi:[0,1]
	v_add_f32_e32 v97, 0, v96
	v_add_f32_e32 v113, v100, v101
	v_add_f32_e32 v115, v102, v103
	v_mov_b32_e32 v112, v30
	v_mov_b32_e32 v114, v31
	v_mov_b32_e32 v98, v28
	v_mov_b32_e32 v96, v29
	v_pk_add_f32 v[112:113], v[112:113], v[114:115]
	v_pk_add_f32 v[96:97], v[98:99], v[96:97]
	s_nop 0
	v_pk_add_f32 v[96:97], v[112:113], v[96:97]
	s_nop 0
	v_add_f32_e32 v96, v96, v97
	v_mov_b32_e32 v97, v96
	v_mov_b32_e32 v210, v96
	s_nop 1
	v_permlane16_swap_b32_e32 v97, v210
	v_cndmask_b32_e64 v97, v210, v97, s[100:101]
	s_waitcnt lgkmcnt(0)
	v_add_f32_e32 v96, v96, v97
	v_mov_b32_e32 v97, v96
	v_mov_b32_e32 v210, v96
	s_nop 1
	v_permlane32_swap_b32_e32 v97, v210
	v_cndmask_b32_e64 v97, v210, v97, s[98:99]
	s_waitcnt lgkmcnt(0)
	v_add_f32_e32 v96, v96, v97
	v_fmamk_f32 v98, v96, 0xbc800000, v111
	v_fmamk_f32 v112, v96, 0xbc800000, v109
	v_fmamk_f32 v97, v96, 0xbc800000, v110
	v_fmamk_f32 v99, v96, 0xbc800000, v108
	v_mul_f32_e32 v112, v112, v112
	v_mul_f32_e32 v98, v98, v98
	v_fmac_f32_e32 v112, v99, v99
	v_fmac_f32_e32 v98, v97, v97
	v_fmamk_f32 v99, v96, 0xbc800000, v107
	v_fmamk_f32 v113, v96, 0xbc800000, v105
	v_add_f32_e32 v97, v112, v98
	v_fmamk_f32 v98, v96, 0xbc800000, v106
	v_fmamk_f32 v112, v96, 0xbc800000, v104
	v_mul_f32_e32 v113, v113, v113
	v_mul_f32_e32 v99, v99, v99
	v_fmac_f32_e32 v113, v112, v112
	v_fmac_f32_e32 v99, v98, v98
	v_add_f32_e32 v98, v113, v99
	v_fmamk_f32 v99, v96, 0xbc800000, v103
	v_fmamk_f32 v113, v96, 0xbc800000, v101
	v_add_f32_e32 v97, v97, v98
	v_fmamk_f32 v98, v96, 0xbc800000, v102
	v_fmamk_f32 v112, v96, 0xbc800000, v100
	v_mul_f32_e32 v113, v113, v113
	v_mul_f32_e32 v99, v99, v99
	v_fmac_f32_e32 v113, v112, v112
	v_fmac_f32_e32 v99, v98, v98
	v_add_f32_e32 v98, v113, v99
	v_fmamk_f32 v99, v96, 0xbc800000, v29
	v_fmamk_f32 v113, v96, 0xbc800000, v31
	v_add_f32_e32 v97, v98, v97
	v_fmamk_f32 v98, v96, 0xbc800000, v28
	v_fmamk_f32 v112, v96, 0xbc800000, v30
	v_mul_f32_e32 v113, v113, v113
	v_mul_f32_e32 v99, v99, v99
	v_fmac_f32_e32 v113, v112, v112
	v_fmac_f32_e32 v99, v98, v98
	v_add_f32_e32 v98, v113, v99
	v_add_f32_e32 v97, v98, v97
	v_mov_b32_e32 v98, v97
	v_mov_b32_e32 v210, v97
	s_nop 1
	v_permlane16_swap_b32_e32 v98, v210
	v_cndmask_b32_e64 v98, v210, v98, s[100:101]
	s_waitcnt lgkmcnt(0)
	v_add_f32_e32 v97, v97, v98
	v_mov_b32_e32 v98, v97
	v_mov_b32_e32 v210, v97
	s_nop 1
	v_permlane32_swap_b32_e32 v98, v210
	v_cndmask_b32_e64 v98, v210, v98, s[98:99]
	s_and_saveexec_b64 s[8:9], vcc
	s_cbranch_execz .LBB0_429
	s_lshl_b32 s3, s22, 11
	s_add_i32 s3, s12, s3
	v_mul_f32_e32 v96, 0x3c800000, v96
	s_waitcnt lgkmcnt(0)
	v_add_f32_e32 v97, v97, v98
	v_lshl_add_u32 v98, v178, 5, s3
	ds_write_b64 v98, v[96:97] offset:1536
.LBB0_429:
	s_or_b64 exec, exec, s[8:9]
	v_max_f32_e64 v96, |v111|, |v111|
	v_max_f32_e64 v97, |v110|, |v110|
	v_max_f32_e32 v96, v97, v96
	v_max_f32_e64 v97, |v107|, |v107|
	s_waitcnt lgkmcnt(0)
	v_max_f32_e64 v98, |v106|, |v106|
	v_max_f32_e32 v97, v98, v97
	v_max3_f32 v96, |v108|, |v109|, v96
	v_max3_f32 v97, |v104|, |v105|, v97
	v_max3_f32 v96, v96, 0, v97
	v_max_f32_e64 v97, |v103|, |v103|
	v_max_f32_e64 v98, |v102|, |v102|
	v_max_f32_e32 v97, v98, v97
	v_max_f32_e64 v98, |v29|, |v29|
	v_max_f32_e64 v99, |v28|, |v28|
	v_max_f32_e32 v98, v99, v98
	v_max3_f32 v97, |v100|, |v101|, v97
	v_max3_f32 v98, |v30|, |v31|, v98
	v_max3_f32 v96, v96, v97, v98
	v_mov_b32_e32 v97, v96
	v_mov_b32_e32 v210, v96
	s_nop 1
	v_permlane16_swap_b32_e32 v97, v210
	v_cndmask_b32_e64 v97, v210, v97, s[100:101]
	s_waitcnt lgkmcnt(0)
	v_max_f32_e32 v97, v97, v97
	v_max_f32_e32 v96, v96, v97
	v_mov_b32_e32 v97, v96
	v_mov_b32_e32 v210, v96
	s_nop 1
	v_permlane32_swap_b32_e32 v97, v210
	v_cndmask_b32_e64 v97, v210, v97, s[98:99]
	s_and_saveexec_b64 s[8:9], vcc
	s_cbranch_execz .LBB0_431
	s_lshl_b32 s3, s22, 10
	s_waitcnt lgkmcnt(0)
	v_max_f32_e32 v97, v97, v97
	v_max_f32_e32 v96, v96, v96
	s_add_i32 s3, s11, s3
	v_max_f32_e32 v96, v96, v97
	v_lshl_add_u32 v97, v178, 4, s3
	ds_write_b32 v97, v96 offset:17152
.LBB0_431:
	s_or_b64 exec, exec, s[8:9]
	v_pk_add_f32 v[94:95], v[6:7], v[94:95]
	v_pk_add_f32 v[92:93], v[4:5], v[92:93]
	v_pk_add_f32 v[90:91], v[2:3], v[90:91]
	v_pk_add_f32 v[88:89], v[0:1], v[88:89]
	v_pk_add_f32 v[86:87], v[14:15], v[86:87]
	v_pk_add_f32 v[84:85], v[12:13], v[84:85]
	v_pk_add_f32 v[82:83], v[10:11], v[82:83]
	v_pk_add_f32 v[80:81], v[8:9], v[80:81]
	s_waitcnt lgkmcnt(0)
	v_pk_mov_b32 v[96:97], v[92:93], v[94:95] op_sel:[1,0]
	v_mov_b32_e32 v98, v92
	v_mov_b32_e32 v99, v95
	v_pk_add_f32 v[96:97], v[96:97], v[98:99]
	v_pk_mov_b32 v[98:99], v[88:89], v[90:91] op_sel:[1,0]
	v_mov_b32_e32 v112, v88
	v_mov_b32_e32 v113, v91
	v_pk_add_f32 v[98:99], v[98:99], v[112:113]
	v_add_f32_e32 v96, v96, v97
	v_pk_add_f32 v[98:99], v[98:99], v[98:99] op_sel_hi:[0,1]
	v_add_f32_e32 v97, 0, v96
	v_add_f32_e32 v113, v84, v85
	v_add_f32_e32 v115, v86, v87
	v_mov_b32_e32 v112, v80
	v_mov_b32_e32 v114, v81
	v_mov_b32_e32 v98, v82
	v_mov_b32_e32 v96, v83
	v_pk_add_f32 v[112:113], v[112:113], v[114:115]
	v_pk_add_f32 v[96:97], v[98:99], v[96:97]
	s_nop 0
	v_pk_add_f32 v[96:97], v[112:113], v[96:97]
	s_nop 0
	v_add_f32_e32 v96, v96, v97
	v_mov_b32_e32 v97, v96
	v_mov_b32_e32 v210, v96
	s_nop 1
	v_permlane16_swap_b32_e32 v97, v210
	v_cndmask_b32_e64 v97, v210, v97, s[100:101]
	s_waitcnt lgkmcnt(0)
	v_add_f32_e32 v96, v96, v97
	v_mov_b32_e32 v97, v96
	v_mov_b32_e32 v210, v96
	s_nop 1
	v_permlane32_swap_b32_e32 v97, v210
	v_cndmask_b32_e64 v97, v210, v97, s[98:99]
	s_waitcnt lgkmcnt(0)
	v_add_f32_e32 v96, v96, v97
	v_fmamk_f32 v98, v96, 0xbc800000, v95
	v_fmamk_f32 v112, v96, 0xbc800000, v93
	v_fmamk_f32 v97, v96, 0xbc800000, v94
	v_fmamk_f32 v99, v96, 0xbc800000, v92
	v_mul_f32_e32 v112, v112, v112
	v_mul_f32_e32 v98, v98, v98
	v_fmac_f32_e32 v112, v99, v99
	v_fmac_f32_e32 v98, v97, v97
	v_fmamk_f32 v99, v96, 0xbc800000, v91
	v_fmamk_f32 v113, v96, 0xbc800000, v89
	v_add_f32_e32 v97, v112, v98
	v_fmamk_f32 v98, v96, 0xbc800000, v90
	v_fmamk_f32 v112, v96, 0xbc800000, v88
	v_mul_f32_e32 v113, v113, v113
	v_mul_f32_e32 v99, v99, v99
	v_fmac_f32_e32 v113, v112, v112
	v_fmac_f32_e32 v99, v98, v98
	v_add_f32_e32 v98, v113, v99
	v_fmamk_f32 v99, v96, 0xbc800000, v87
	v_fmamk_f32 v113, v96, 0xbc800000, v85
	v_add_f32_e32 v97, v97, v98
	v_fmamk_f32 v98, v96, 0xbc800000, v86
	v_fmamk_f32 v112, v96, 0xbc800000, v84
	v_mul_f32_e32 v113, v113, v113
	v_mul_f32_e32 v99, v99, v99
	v_fmac_f32_e32 v113, v112, v112
	v_fmac_f32_e32 v99, v98, v98
	v_add_f32_e32 v98, v113, v99
	v_fmamk_f32 v99, v96, 0xbc800000, v83
	v_fmamk_f32 v113, v96, 0xbc800000, v81
	v_add_f32_e32 v97, v98, v97
	v_fmamk_f32 v98, v96, 0xbc800000, v82
	v_fmamk_f32 v112, v96, 0xbc800000, v80
	v_mul_f32_e32 v113, v113, v113
	v_mul_f32_e32 v99, v99, v99
	v_fmac_f32_e32 v113, v112, v112
	v_fmac_f32_e32 v99, v98, v98
	v_add_f32_e32 v98, v113, v99
	v_add_f32_e32 v97, v98, v97
	v_mov_b32_e32 v98, v97
	v_mov_b32_e32 v210, v97
	s_nop 1
	v_permlane16_swap_b32_e32 v98, v210
	v_cndmask_b32_e64 v98, v210, v98, s[100:101]
	s_waitcnt lgkmcnt(0)
	v_add_f32_e32 v97, v97, v98
	v_mov_b32_e32 v98, v97
	v_mov_b32_e32 v210, v97
	s_nop 1
	v_permlane32_swap_b32_e32 v98, v210
	v_cndmask_b32_e64 v98, v210, v98, s[98:99]
	s_and_saveexec_b64 s[8:9], vcc
	s_cbranch_execz .LBB0_433
	s_lshl_b32 s3, s22, 11
	s_add_i32 s3, s12, s3
	v_mul_f32_e32 v96, 0x3c800000, v96
	s_waitcnt lgkmcnt(0)
	v_add_f32_e32 v97, v97, v98
	v_lshl_add_u32 v98, v178, 5, s3
	ds_write_b64 v98, v[96:97] offset:4096
.LBB0_433:
	s_or_b64 exec, exec, s[8:9]
	v_max_f32_e64 v96, |v95|, |v95|
	v_max_f32_e64 v97, |v94|, |v94|
	v_max_f32_e32 v96, v97, v96
	v_max_f32_e64 v97, |v91|, |v91|
	s_waitcnt lgkmcnt(0)
	v_max_f32_e64 v98, |v90|, |v90|
	v_max_f32_e32 v97, v98, v97
	v_max3_f32 v96, |v92|, |v93|, v96
	v_max3_f32 v97, |v88|, |v89|, v97
	v_max3_f32 v96, v96, 0, v97
	v_max_f32_e64 v97, |v87|, |v87|
	v_max_f32_e64 v98, |v86|, |v86|
	v_max_f32_e32 v97, v98, v97
	v_max_f32_e64 v98, |v83|, |v83|
	v_max_f32_e64 v99, |v82|, |v82|
	v_max_f32_e32 v98, v99, v98
	v_max3_f32 v97, |v84|, |v85|, v97
	v_max3_f32 v98, |v80|, |v81|, v98
	v_max3_f32 v96, v96, v97, v98
	v_mov_b32_e32 v97, v96
	v_mov_b32_e32 v210, v96
	s_nop 1
	v_permlane16_swap_b32_e32 v97, v210
	v_cndmask_b32_e64 v97, v210, v97, s[100:101]
	s_waitcnt lgkmcnt(0)
	v_max_f32_e32 v97, v97, v97
	v_max_f32_e32 v96, v96, v97
	v_mov_b32_e32 v97, v96
	v_mov_b32_e32 v210, v96
	s_nop 1
	v_permlane32_swap_b32_e32 v97, v210
	v_cndmask_b32_e64 v97, v210, v97, s[98:99]
	s_and_saveexec_b64 s[8:9], vcc
	s_cbranch_execz .LBB0_435
	s_lshl_b32 s3, s22, 10
	s_waitcnt lgkmcnt(0)
	v_max_f32_e32 v97, v97, v97
	v_max_f32_e32 v96, v96, v96
	s_add_i32 s3, s11, s3
	v_max_f32_e32 v96, v96, v97
	v_lshl_add_u32 v97, v178, 4, s3
	ds_write_b32 v97, v96 offset:18432
.LBB0_435:
	s_or_b64 exec, exec, s[8:9]
	v_pk_add_f32 v[78:79], v[6:7], v[78:79]
	v_pk_add_f32 v[76:77], v[4:5], v[76:77]
	v_pk_add_f32 v[74:75], v[2:3], v[74:75]
	v_pk_add_f32 v[72:73], v[0:1], v[72:73]
	v_pk_add_f32 v[70:71], v[14:15], v[70:71]
	v_pk_add_f32 v[68:69], v[12:13], v[68:69]
	v_pk_add_f32 v[66:67], v[10:11], v[66:67]
	v_pk_add_f32 v[64:65], v[8:9], v[64:65]
	s_waitcnt lgkmcnt(0)
	v_pk_mov_b32 v[96:97], v[76:77], v[78:79] op_sel:[1,0]
	v_mov_b32_e32 v98, v76
	v_mov_b32_e32 v99, v79
	v_pk_add_f32 v[96:97], v[96:97], v[98:99]
	v_pk_mov_b32 v[98:99], v[72:73], v[74:75] op_sel:[1,0]
	v_mov_b32_e32 v112, v72
	v_mov_b32_e32 v113, v75
	v_pk_add_f32 v[98:99], v[98:99], v[112:113]
	v_add_f32_e32 v96, v96, v97
	v_pk_add_f32 v[98:99], v[98:99], v[98:99] op_sel_hi:[0,1]
	v_add_f32_e32 v97, 0, v96
	v_add_f32_e32 v113, v68, v69
	v_add_f32_e32 v115, v70, v71
	v_mov_b32_e32 v112, v64
	v_mov_b32_e32 v114, v65
	v_mov_b32_e32 v98, v66
	v_mov_b32_e32 v96, v67
	v_pk_add_f32 v[112:113], v[112:113], v[114:115]
	v_pk_add_f32 v[96:97], v[98:99], v[96:97]
	s_nop 0
	v_pk_add_f32 v[96:97], v[112:113], v[96:97]
	s_nop 0
	v_add_f32_e32 v96, v96, v97
	v_mov_b32_e32 v97, v96
	v_mov_b32_e32 v210, v96
	s_nop 1
	v_permlane16_swap_b32_e32 v97, v210
	v_cndmask_b32_e64 v97, v210, v97, s[100:101]
	s_waitcnt lgkmcnt(0)
	v_add_f32_e32 v96, v96, v97
	v_mov_b32_e32 v97, v96
	v_mov_b32_e32 v210, v96
	s_nop 1
	v_permlane32_swap_b32_e32 v97, v210
	v_cndmask_b32_e64 v97, v210, v97, s[98:99]
	s_waitcnt lgkmcnt(0)
	v_add_f32_e32 v96, v96, v97
	v_fmamk_f32 v98, v96, 0xbc800000, v79
	v_fmamk_f32 v112, v96, 0xbc800000, v77
	v_fmamk_f32 v97, v96, 0xbc800000, v78
	v_fmamk_f32 v99, v96, 0xbc800000, v76
	v_mul_f32_e32 v112, v112, v112
	v_mul_f32_e32 v98, v98, v98
	v_fmac_f32_e32 v112, v99, v99
	v_fmac_f32_e32 v98, v97, v97
	v_fmamk_f32 v99, v96, 0xbc800000, v75
	v_fmamk_f32 v113, v96, 0xbc800000, v73
	v_add_f32_e32 v97, v112, v98
	v_fmamk_f32 v98, v96, 0xbc800000, v74
	v_fmamk_f32 v112, v96, 0xbc800000, v72
	v_mul_f32_e32 v113, v113, v113
	v_mul_f32_e32 v99, v99, v99
	v_fmac_f32_e32 v113, v112, v112
	v_fmac_f32_e32 v99, v98, v98
	v_add_f32_e32 v98, v113, v99
	v_fmamk_f32 v99, v96, 0xbc800000, v71
	v_fmamk_f32 v113, v96, 0xbc800000, v69
	v_add_f32_e32 v97, v97, v98
	v_fmamk_f32 v98, v96, 0xbc800000, v70
	v_fmamk_f32 v112, v96, 0xbc800000, v68
	v_mul_f32_e32 v113, v113, v113
	v_mul_f32_e32 v99, v99, v99
	v_fmac_f32_e32 v113, v112, v112
	v_fmac_f32_e32 v99, v98, v98
	v_add_f32_e32 v98, v113, v99
	v_fmamk_f32 v99, v96, 0xbc800000, v67
	v_fmamk_f32 v113, v96, 0xbc800000, v65
	v_add_f32_e32 v97, v98, v97
	v_fmamk_f32 v98, v96, 0xbc800000, v66
	v_fmamk_f32 v112, v96, 0xbc800000, v64
	v_mul_f32_e32 v113, v113, v113
	v_mul_f32_e32 v99, v99, v99
	v_fmac_f32_e32 v113, v112, v112
	v_fmac_f32_e32 v99, v98, v98
	v_add_f32_e32 v98, v113, v99
	v_add_f32_e32 v97, v98, v97
	v_mov_b32_e32 v98, v97
	v_mov_b32_e32 v210, v97
	s_nop 1
	v_permlane16_swap_b32_e32 v98, v210
	v_cndmask_b32_e64 v98, v210, v98, s[100:101]
	s_waitcnt lgkmcnt(0)
	v_add_f32_e32 v97, v97, v98
	v_mov_b32_e32 v98, v97
	v_mov_b32_e32 v210, v97
	s_nop 1
	v_permlane32_swap_b32_e32 v98, v210
	v_cndmask_b32_e64 v98, v210, v98, s[98:99]
	s_and_saveexec_b64 s[8:9], vcc
	s_cbranch_execz .LBB0_437
	s_lshl_b32 s3, s22, 11
	s_add_i32 s3, s12, s3
	v_mul_f32_e32 v96, 0x3c800000, v96
	s_waitcnt lgkmcnt(0)
	v_add_f32_e32 v97, v97, v98
	v_lshl_add_u32 v98, v178, 5, s3
	ds_write_b64 v98, v[96:97] offset:4608
.LBB0_437:
	s_or_b64 exec, exec, s[8:9]
	v_max_f32_e64 v96, |v79|, |v79|
	v_max_f32_e64 v97, |v78|, |v78|
	v_max_f32_e32 v96, v97, v96
	v_max_f32_e64 v97, |v75|, |v75|
	s_waitcnt lgkmcnt(0)
	v_max_f32_e64 v98, |v74|, |v74|
	v_max_f32_e32 v97, v98, v97
	v_max3_f32 v96, |v76|, |v77|, v96
	v_max3_f32 v97, |v72|, |v73|, v97
	v_max3_f32 v96, v96, 0, v97
	v_max_f32_e64 v97, |v71|, |v71|
	v_max_f32_e64 v98, |v70|, |v70|
	v_max_f32_e32 v97, v98, v97
	v_max_f32_e64 v98, |v67|, |v67|
	v_max_f32_e64 v99, |v66|, |v66|
	v_max_f32_e32 v98, v99, v98
	v_max3_f32 v97, |v68|, |v69|, v97
	v_max3_f32 v98, |v64|, |v65|, v98
	v_max3_f32 v96, v96, v97, v98
	v_mov_b32_e32 v97, v96
	v_mov_b32_e32 v210, v96
	s_nop 1
	v_permlane16_swap_b32_e32 v97, v210
	v_cndmask_b32_e64 v97, v210, v97, s[100:101]
	s_waitcnt lgkmcnt(0)
	v_max_f32_e32 v97, v97, v97
	v_max_f32_e32 v96, v96, v97
	v_mov_b32_e32 v97, v96
	v_mov_b32_e32 v210, v96
	s_nop 1
	v_permlane32_swap_b32_e32 v97, v210
	v_cndmask_b32_e64 v97, v210, v97, s[98:99]
	s_and_saveexec_b64 s[8:9], vcc
	s_cbranch_execz .LBB0_439
	s_lshl_b32 s3, s22, 10
	s_waitcnt lgkmcnt(0)
	v_max_f32_e32 v97, v97, v97
	v_max_f32_e32 v96, v96, v96
	s_add_i32 s3, s11, s3
	v_max_f32_e32 v96, v96, v97
	v_lshl_add_u32 v97, v178, 4, s3
	ds_write_b32 v97, v96 offset:18688
.LBB0_439:
	s_or_b64 exec, exec, s[8:9]
	v_pk_add_f32 v[62:63], v[6:7], v[62:63]
	v_pk_add_f32 v[60:61], v[4:5], v[60:61]
	v_pk_add_f32 v[58:59], v[2:3], v[58:59]
	v_pk_add_f32 v[56:57], v[0:1], v[56:57]
	v_pk_add_f32 v[54:55], v[14:15], v[54:55]
	v_pk_add_f32 v[52:53], v[12:13], v[52:53]
	v_pk_add_f32 v[50:51], v[10:11], v[50:51]
	v_pk_add_f32 v[48:49], v[8:9], v[48:49]
	s_waitcnt lgkmcnt(0)
	v_pk_mov_b32 v[96:97], v[60:61], v[62:63] op_sel:[1,0]
	v_mov_b32_e32 v98, v60
	v_mov_b32_e32 v99, v63
	v_pk_add_f32 v[96:97], v[96:97], v[98:99]
	v_pk_mov_b32 v[98:99], v[56:57], v[58:59] op_sel:[1,0]
	v_mov_b32_e32 v112, v56
	v_mov_b32_e32 v113, v59
	v_pk_add_f32 v[98:99], v[98:99], v[112:113]
	v_add_f32_e32 v96, v96, v97
	v_pk_add_f32 v[98:99], v[98:99], v[98:99] op_sel_hi:[0,1]
	v_add_f32_e32 v97, 0, v96
	v_add_f32_e32 v113, v52, v53
	v_add_f32_e32 v115, v54, v55
	v_mov_b32_e32 v112, v48
	v_mov_b32_e32 v114, v49
	v_mov_b32_e32 v98, v50
	v_mov_b32_e32 v96, v51
	v_pk_add_f32 v[112:113], v[112:113], v[114:115]
	v_pk_add_f32 v[96:97], v[98:99], v[96:97]
	s_nop 0
	v_pk_add_f32 v[96:97], v[112:113], v[96:97]
	s_nop 0
	v_add_f32_e32 v96, v96, v97
	v_mov_b32_e32 v97, v96
	v_mov_b32_e32 v210, v96
	s_nop 1
	v_permlane16_swap_b32_e32 v97, v210
	v_cndmask_b32_e64 v97, v210, v97, s[100:101]
	s_waitcnt lgkmcnt(0)
	v_add_f32_e32 v96, v96, v97
	v_mov_b32_e32 v97, v96
	v_mov_b32_e32 v210, v96
	s_nop 1
	v_permlane32_swap_b32_e32 v97, v210
	v_cndmask_b32_e64 v97, v210, v97, s[98:99]
	s_waitcnt lgkmcnt(0)
	v_add_f32_e32 v96, v96, v97
	v_fmamk_f32 v98, v96, 0xbc800000, v63
	v_fmamk_f32 v112, v96, 0xbc800000, v61
	v_fmamk_f32 v97, v96, 0xbc800000, v62
	v_fmamk_f32 v99, v96, 0xbc800000, v60
	v_mul_f32_e32 v112, v112, v112
	v_mul_f32_e32 v98, v98, v98
	v_fmac_f32_e32 v112, v99, v99
	v_fmac_f32_e32 v98, v97, v97
	v_fmamk_f32 v99, v96, 0xbc800000, v59
	v_fmamk_f32 v113, v96, 0xbc800000, v57
	v_add_f32_e32 v97, v112, v98
	v_fmamk_f32 v98, v96, 0xbc800000, v58
	v_fmamk_f32 v112, v96, 0xbc800000, v56
	v_mul_f32_e32 v113, v113, v113
	v_mul_f32_e32 v99, v99, v99
	v_fmac_f32_e32 v113, v112, v112
	v_fmac_f32_e32 v99, v98, v98
	v_add_f32_e32 v98, v113, v99
	v_fmamk_f32 v99, v96, 0xbc800000, v55
	v_fmamk_f32 v113, v96, 0xbc800000, v53
	v_add_f32_e32 v97, v97, v98
	v_fmamk_f32 v98, v96, 0xbc800000, v54
	v_fmamk_f32 v112, v96, 0xbc800000, v52
	v_mul_f32_e32 v113, v113, v113
	v_mul_f32_e32 v99, v99, v99
	v_fmac_f32_e32 v113, v112, v112
	v_fmac_f32_e32 v99, v98, v98
	v_add_f32_e32 v98, v113, v99
	v_fmamk_f32 v99, v96, 0xbc800000, v51
	v_fmamk_f32 v113, v96, 0xbc800000, v49
	v_add_f32_e32 v97, v98, v97
	v_fmamk_f32 v98, v96, 0xbc800000, v50
	v_fmamk_f32 v112, v96, 0xbc800000, v48
	v_mul_f32_e32 v113, v113, v113
	v_mul_f32_e32 v99, v99, v99
	v_fmac_f32_e32 v113, v112, v112
	v_fmac_f32_e32 v99, v98, v98
	v_add_f32_e32 v98, v113, v99
	v_add_f32_e32 v97, v98, v97
	v_mov_b32_e32 v98, v97
	v_mov_b32_e32 v210, v97
	s_nop 1
	v_permlane16_swap_b32_e32 v98, v210
	v_cndmask_b32_e64 v98, v210, v98, s[100:101]
	s_waitcnt lgkmcnt(0)
	v_add_f32_e32 v97, v97, v98
	v_mov_b32_e32 v98, v97
	v_mov_b32_e32 v210, v97
	s_nop 1
	v_permlane32_swap_b32_e32 v98, v210
	v_cndmask_b32_e64 v98, v210, v98, s[98:99]
	s_and_saveexec_b64 s[8:9], vcc
	s_cbranch_execz .LBB0_441
	s_lshl_b32 s3, s22, 11
	s_add_i32 s3, s12, s3
	v_mul_f32_e32 v96, 0x3c800000, v96
	s_waitcnt lgkmcnt(0)
	v_add_f32_e32 v97, v97, v98
	v_lshl_add_u32 v98, v178, 5, s3
	ds_write_b64 v98, v[96:97] offset:5120
.LBB0_441:
	s_or_b64 exec, exec, s[8:9]
	v_max_f32_e64 v96, |v63|, |v63|
	v_max_f32_e64 v97, |v62|, |v62|
	v_max_f32_e32 v96, v97, v96
	v_max_f32_e64 v97, |v59|, |v59|
	s_waitcnt lgkmcnt(0)
	v_max_f32_e64 v98, |v58|, |v58|
	v_max_f32_e32 v97, v98, v97
	v_max3_f32 v96, |v60|, |v61|, v96
	v_max3_f32 v97, |v56|, |v57|, v97
	v_max3_f32 v96, v96, 0, v97
	v_max_f32_e64 v97, |v55|, |v55|
	v_max_f32_e64 v98, |v54|, |v54|
	v_max_f32_e32 v97, v98, v97
	v_max_f32_e64 v98, |v51|, |v51|
	v_max_f32_e64 v99, |v50|, |v50|
	v_max_f32_e32 v98, v99, v98
	v_max3_f32 v97, |v52|, |v53|, v97
	v_max3_f32 v98, |v48|, |v49|, v98
	v_max3_f32 v96, v96, v97, v98
	v_mov_b32_e32 v97, v96
	v_mov_b32_e32 v210, v96
	s_nop 1
	v_permlane16_swap_b32_e32 v97, v210
	v_cndmask_b32_e64 v97, v210, v97, s[100:101]
	s_waitcnt lgkmcnt(0)
	v_max_f32_e32 v97, v97, v97
	v_max_f32_e32 v96, v96, v97
	v_mov_b32_e32 v97, v96
	v_mov_b32_e32 v210, v96
	s_nop 1
	v_permlane32_swap_b32_e32 v97, v210
	v_cndmask_b32_e64 v97, v210, v97, s[98:99]
	s_and_saveexec_b64 s[8:9], vcc
	s_cbranch_execz .LBB0_443
	s_lshl_b32 s3, s22, 10
	s_waitcnt lgkmcnt(0)
	v_max_f32_e32 v97, v97, v97
	v_max_f32_e32 v96, v96, v96
	s_add_i32 s3, s11, s3
	v_max_f32_e32 v96, v96, v97
	v_lshl_add_u32 v97, v178, 4, s3
	ds_write_b32 v97, v96 offset:18944
.LBB0_443:
	s_or_b64 exec, exec, s[8:9]
	v_pk_add_f32 v[128:129], v[6:7], v[46:47]
	v_pk_add_f32 v[130:131], v[4:5], v[44:45]
	v_pk_add_f32 v[42:43], v[2:3], v[42:43]
	v_pk_add_f32 v[40:41], v[0:1], v[40:41]
	v_pk_add_f32 v[14:15], v[14:15], v[38:39]
	v_pk_add_f32 v[12:13], v[12:13], v[36:37]
	v_pk_add_f32 v[10:11], v[10:11], v[34:35]
	v_pk_add_f32 v[8:9], v[8:9], v[32:33]
	v_pk_mov_b32 v[0:1], v[130:131], v[128:129] op_sel:[1,0]
	v_mov_b32_e32 v2, v130
	v_mov_b32_e32 v3, v129
	v_pk_add_f32 v[0:1], v[0:1], v[2:3]
	v_pk_mov_b32 v[2:3], v[40:41], v[42:43] op_sel:[1,0]
	v_mov_b32_e32 v4, v40
	v_mov_b32_e32 v5, v43
	v_pk_add_f32 v[2:3], v[2:3], v[4:5]
	v_add_f32_e32 v0, v0, v1
	v_pk_add_f32 v[2:3], v[2:3], v[2:3] op_sel_hi:[0,1]
	v_add_f32_e32 v1, 0, v0
	v_add_f32_e32 v5, v12, v13
	v_add_f32_e32 v7, v14, v15
	v_mov_b32_e32 v4, v8
	v_mov_b32_e32 v6, v9
	v_mov_b32_e32 v2, v10
	v_mov_b32_e32 v0, v11
	v_pk_add_f32 v[4:5], v[4:5], v[6:7]
	v_pk_add_f32 v[0:1], v[2:3], v[0:1]
	s_nop 0
	v_pk_add_f32 v[0:1], v[4:5], v[0:1]
	s_nop 0
	v_add_f32_e32 v0, v0, v1
	v_mov_b32_e32 v1, v0
	v_mov_b32_e32 v210, v0
	s_nop 1
	v_permlane16_swap_b32_e32 v1, v210
	v_cndmask_b32_e64 v1, v210, v1, s[100:101]
	s_waitcnt lgkmcnt(0)
	v_add_f32_e32 v0, v0, v1
	v_mov_b32_e32 v1, v0
	v_mov_b32_e32 v210, v0
	s_nop 1
	v_permlane32_swap_b32_e32 v1, v210
	v_cndmask_b32_e64 v1, v210, v1, s[98:99]
	s_waitcnt lgkmcnt(0)
	v_add_f32_e32 v0, v0, v1
	v_fmamk_f32 v2, v0, 0xbc800000, v129
	v_fmamk_f32 v4, v0, 0xbc800000, v131
	v_fmamk_f32 v1, v0, 0xbc800000, v128
	v_fmamk_f32 v3, v0, 0xbc800000, v130
	v_mul_f32_e32 v4, v4, v4
	v_mul_f32_e32 v2, v2, v2
	v_fmac_f32_e32 v4, v3, v3
	v_fmac_f32_e32 v2, v1, v1
	v_fmamk_f32 v3, v0, 0xbc800000, v43
	v_fmamk_f32 v5, v0, 0xbc800000, v41
	v_add_f32_e32 v1, v4, v2
	v_fmamk_f32 v2, v0, 0xbc800000, v42
	v_fmamk_f32 v4, v0, 0xbc800000, v40
	v_mul_f32_e32 v5, v5, v5
	v_mul_f32_e32 v3, v3, v3
	v_fmac_f32_e32 v5, v4, v4
	v_fmac_f32_e32 v3, v2, v2
	v_add_f32_e32 v2, v5, v3
	v_fmamk_f32 v3, v0, 0xbc800000, v15
	v_fmamk_f32 v5, v0, 0xbc800000, v13
	v_add_f32_e32 v1, v1, v2
	v_fmamk_f32 v2, v0, 0xbc800000, v14
	v_fmamk_f32 v4, v0, 0xbc800000, v12
	v_mul_f32_e32 v5, v5, v5
	v_mul_f32_e32 v3, v3, v3
	v_fmac_f32_e32 v5, v4, v4
	v_fmac_f32_e32 v3, v2, v2
	v_add_f32_e32 v2, v5, v3
	v_fmamk_f32 v3, v0, 0xbc800000, v11
	v_fmamk_f32 v5, v0, 0xbc800000, v9
	v_add_f32_e32 v1, v2, v1
	v_fmamk_f32 v2, v0, 0xbc800000, v10
	v_fmamk_f32 v4, v0, 0xbc800000, v8
	v_mul_f32_e32 v5, v5, v5
	v_mul_f32_e32 v3, v3, v3
	v_fmac_f32_e32 v5, v4, v4
	v_fmac_f32_e32 v3, v2, v2
	v_add_f32_e32 v2, v5, v3
	v_add_f32_e32 v1, v2, v1
	v_mov_b32_e32 v2, v1
	v_mov_b32_e32 v210, v1
	s_nop 1
	v_permlane16_swap_b32_e32 v2, v210
	v_cndmask_b32_e64 v2, v210, v2, s[100:101]
	s_waitcnt lgkmcnt(0)
	v_add_f32_e32 v1, v1, v2
	v_mov_b32_e32 v2, v1
	v_mov_b32_e32 v210, v1
	s_nop 1
	v_permlane32_swap_b32_e32 v2, v210
	v_cndmask_b32_e64 v2, v210, v2, s[98:99]
	s_and_saveexec_b64 s[8:9], vcc
	s_cbranch_execz .LBB0_445
	s_lshl_b32 s3, s22, 11
	s_add_i32 s12, s12, s3
	v_mul_f32_e32 v0, 0x3c800000, v0
	s_waitcnt lgkmcnt(0)
	v_add_f32_e32 v1, v1, v2
	v_lshl_add_u32 v2, v178, 5, s12
	ds_write_b64 v2, v[0:1] offset:5632
.LBB0_445:
	s_or_b64 exec, exec, s[8:9]
	v_max_f32_e64 v0, |v129|, |v129|
	v_max_f32_e64 v1, |v128|, |v128|
	v_max_f32_e32 v0, v1, v0
	v_max_f32_e64 v1, |v43|, |v43|
	s_waitcnt lgkmcnt(0)
	v_max_f32_e64 v2, |v42|, |v42|
	v_max_f32_e32 v1, v2, v1
	v_max3_f32 v0, |v130|, |v131|, v0
	v_max3_f32 v1, |v40|, |v41|, v1
	v_max3_f32 v0, v0, 0, v1
	v_max_f32_e64 v1, |v15|, |v15|
	v_max_f32_e64 v2, |v14|, |v14|
	v_max_f32_e32 v1, v2, v1
	v_max_f32_e64 v2, |v11|, |v11|
	v_max_f32_e64 v3, |v10|, |v10|
	v_max_f32_e32 v2, v3, v2
	v_max3_f32 v1, |v12|, |v13|, v1
	v_max3_f32 v2, |v8|, |v9|, v2
	v_max3_f32 v0, v0, v1, v2
	v_mov_b32_e32 v1, v0
	v_mov_b32_e32 v210, v0
	s_nop 1
	v_permlane16_swap_b32_e32 v1, v210
	v_cndmask_b32_e64 v1, v210, v1, s[100:101]
	s_waitcnt lgkmcnt(0)
	v_max_f32_e32 v1, v1, v1
	v_max_f32_e32 v0, v0, v1
	v_mov_b32_e32 v1, v0
	v_mov_b32_e32 v210, v0
	s_nop 1
	v_permlane32_swap_b32_e32 v1, v210
	v_cndmask_b32_e64 v1, v210, v1, s[98:99]
	s_and_saveexec_b64 s[8:9], vcc
	s_cbranch_execz .LBB0_447
	s_lshl_b32 s3, s22, 10
	s_waitcnt lgkmcnt(0)
	v_max_f32_e32 v1, v1, v1
	v_max_f32_e32 v0, v0, v0
	s_add_i32 s11, s11, s3
	v_max_f32_e32 v0, v0, v1
	v_lshl_add_u32 v1, v178, 4, s11
	ds_write_b32 v1, v0 offset:19200

.LBB0_495:
	s_barrier
	v_mbcnt_lo_u32_b32 v143, -1, 0
	v_mbcnt_hi_u32_b32 v143, -1, v143
	s_lshl_b32 s10, s23, 5
	v_mbcnt_lo_u32_b32 v142, -1, 0
	v_mbcnt_hi_u32_b32 v142, -1, v142
	v_readlane_b32 s3, v254, 17
	s_add_i32 s3, s3, s10
	v_ashrrev_i32_e32 v148, 5, v142
	v_add_u32_e32 v120, s3, v148
	v_and_b32_e32 v146, 31, v142
	v_ashrrev_i32_e32 v121, 31, v120
	v_readlane_b32 s8, v253, 47
	v_lshlrev_b64 v[120:121], 11, v[120:121]
	v_readlane_b32 s9, v253, 48
	s_lshl_b32 s3, s23, 14
	v_bitop3_b32 v122, v148, v146, 15 bitop3:0x6c
	v_lshl_add_u64 v[120:121], s[8:9], 0, v[120:121]
	s_add_i32 s3, s3, 0
	v_lshlrev_b32_e32 v230, 4, v122
	v_lshl_add_u64 v[122:123], v[120:121], 0, v[230:231]
	s_mov_b32 m0, s3
	s_mov_b64 s[8:9], 0x1000
	global_load_lds_dwordx4 v[122:123], off
	v_add_u32_e32 v122, 2, v148
	v_bitop3_b32 v122, v122, v146, 15 bitop3:0x6c
	v_lshl_add_u64 v[120:121], v[120:121], 0, s[8:9]
	v_lshlrev_b32_e32 v122, 4, v122
	v_mov_b32_e32 v123, v231
	s_add_i32 m0, s3, 0x400
	v_lshl_add_u64 v[132:133], v[120:121], 0, v[122:123]
	global_load_lds_dwordx4 v[132:133], off
	v_add_u32_e32 v132, 4, v148
	v_bitop3_b32 v132, v132, v146, 15 bitop3:0x6c
	v_lshl_add_u64 v[120:121], v[120:121], 0, s[8:9]
	v_lshlrev_b32_e32 v132, 4, v132
	v_mov_b32_e32 v133, v231
	s_add_i32 m0, s3, 0x800
	v_lshl_add_u64 v[134:135], v[120:121], 0, v[132:133]
	global_load_lds_dwordx4 v[134:135], off
	v_add_u32_e32 v134, 6, v148
	v_bitop3_b32 v134, v134, v146, 15 bitop3:0x6c
	v_lshl_add_u64 v[120:121], v[120:121], 0, s[8:9]
	v_lshlrev_b32_e32 v134, 4, v134
	v_mov_b32_e32 v135, v231
	s_add_i32 m0, s3, 0xc00
	v_lshl_add_u64 v[136:137], v[120:121], 0, v[134:135]
	global_load_lds_dwordx4 v[136:137], off
	v_lshl_add_u64 v[120:121], v[120:121], 0, s[8:9]
	v_xor_b32_e32 v136, 0x80, v230
	v_mov_b32_e32 v137, v231
	s_add_i32 m0, s3, 0x1000
	v_lshl_add_u64 v[138:139], v[120:121], 0, v[136:137]
	global_load_lds_dwordx4 v[138:139], off
	v_add_u32_e32 v138, 10, v148
	v_bitop3_b32 v138, v138, v146, 15 bitop3:0x6c
	v_lshl_add_u64 v[120:121], v[120:121], 0, s[8:9]
	v_lshlrev_b32_e32 v138, 4, v138
	v_mov_b32_e32 v139, v231
	s_add_i32 m0, s3, 0x1400
	v_lshl_add_u64 v[140:141], v[120:121], 0, v[138:139]
	global_load_lds_dwordx4 v[140:141], off
	v_add_u32_e32 v140, 12, v148
	v_bitop3_b32 v140, v140, v146, 15 bitop3:0x6c
	v_lshl_add_u64 v[120:121], v[120:121], 0, s[8:9]
	v_lshlrev_b32_e32 v140, 4, v140
	v_mov_b32_e32 v141, v231
	s_add_i32 m0, s3, 0x1800
	v_lshl_add_u64 v[144:145], v[120:121], 0, v[140:141]
	global_load_lds_dwordx4 v[144:145], off
	v_add_u32_e32 v144, 14, v148
	v_lshl_add_u64 v[120:121], v[120:121], 0, s[8:9]
	v_bitop3_b32 v144, v144, v146, 15 bitop3:0x6c
	v_lshlrev_b32_e32 v144, 4, v144
	v_mov_b32_e32 v145, v231
	v_lshl_add_u64 v[146:147], v[120:121], 0, v[144:145]
	s_add_i32 m0, s3, 0x1c00
	v_lshl_add_u64 v[120:121], v[120:121], 0, s[8:9]
	global_load_lds_dwordx4 v[146:147], off
	s_add_i32 m0, s3, 0x2000
	v_lshl_add_u64 v[146:147], v[120:121], 0, v[230:231]
	v_lshl_add_u64 v[120:121], v[120:121], 0, s[8:9]
	global_load_lds_dwordx4 v[146:147], off
	s_add_i32 m0, s3, 0x2400
	v_lshl_add_u64 v[122:123], v[120:121], 0, v[122:123]
	v_lshl_add_u64 v[120:121], v[120:121], 0, s[8:9]
	global_load_lds_dwordx4 v[122:123], off
	s_add_i32 m0, s3, 0x2800
	v_lshl_add_u64 v[122:123], v[120:121], 0, v[132:133]
	v_lshl_add_u64 v[120:121], v[120:121], 0, s[8:9]
	global_load_lds_dwordx4 v[122:123], off
	s_add_i32 m0, s3, 0x2c00
	v_lshl_add_u64 v[122:123], v[120:121], 0, v[134:135]
	v_lshl_add_u64 v[120:121], v[120:121], 0, s[8:9]
	global_load_lds_dwordx4 v[122:123], off
	s_add_i32 m0, s3, 0x3000
	v_lshl_add_u64 v[122:123], v[120:121], 0, v[136:137]
	v_lshl_add_u64 v[120:121], v[120:121], 0, s[8:9]
	global_load_lds_dwordx4 v[122:123], off
	s_add_i32 m0, s3, 0x3400
	v_lshl_add_u64 v[122:123], v[120:121], 0, v[138:139]
	v_lshl_add_u64 v[120:121], v[120:121], 0, s[8:9]
	global_load_lds_dwordx4 v[122:123], off
	s_add_i32 m0, s3, 0x3800
	v_lshl_add_u64 v[122:123], v[120:121], 0, v[140:141]
	v_lshl_add_u64 v[120:121], v[120:121], 0, s[8:9]
	global_load_lds_dwordx4 v[122:123], off
	s_add_i32 m0, s3, 0x3c00
	v_lshl_add_u64 v[122:123], v[120:121], 0, v[144:145]
	v_lshl_add_u64 v[120:121], v[120:121], 0, s[8:9]
	global_load_lds_dwordx4 v[122:123], off
	v_lshrrev_b32_e32 v122, 1, v142
	v_lshlrev_b32_e32 v121, 9, v142
	s_lshl_b32 s11, s5, 2
	v_and_b32_e32 v121, 0x200, v121
	v_and_b32_e32 v122, 8, v122
	v_add_u32_e32 v136, s11, v148
	v_and_b32_e32 v120, 15, v142
	v_add3_u32 v137, 0, v121, v122
	v_add_u32_e32 v121, 16, v136
	v_bitop3_b32 v121, v121, v142, 15 bitop3:0x78
	s_lshl_b32 s3, s22, 15
	v_lshlrev_b32_e32 v120, 9, v120
	v_lshlrev_b32_e32 v132, 4, v121
	v_or_b32_e32 v138, s3, v120
	v_mov_b32_e32 v121, s3
	s_movk_i32 s3, 0x9c00
	v_bitop3_b32 v120, v120, s3, v121 bitop3:0xc8
	v_add_u32_e32 v133, v137, v120
	v_bitop3_b32 v120, v136, v142, 15 bitop3:0x78
	v_lshlrev_b32_e32 v134, 4, v120
	s_waitcnt vmcnt(0)
	s_barrier
	v_add_u32_e32 v139, v133, v134
	ds_read_b64 v[120:121], v139
	s_mov_b32 s8, 0x3fd744fd
	v_add_u32_e32 v141, v133, v132
	s_lshl_b32 s3, s5, 3
	v_cmp_gt_u32_e32 vcc, 16, v143
	s_waitcnt lgkmcnt(0)
	v_cvt_f32_f16_e32 v122, v120
	v_cvt_f32_f16_sdwa v123, v120 dst_sel:DWORD dst_unused:UNUSED_PAD src0_sel:WORD_1
	v_cvt_f32_f16_e32 v120, v121
	v_cvt_f32_f16_sdwa v121, v121 dst_sel:DWORD dst_unused:UNUSED_PAD src0_sel:WORD_1
	s_add_i32 s12, s3, 0
	v_pk_fma_f32 v[68:69], v[122:123], s[8:9], v[68:69] op_sel_hi:[1,0,1]
	v_pk_fma_f32 v[70:71], v[120:121], s[8:9], v[70:71] op_sel_hi:[1,0,1]
	v_add_u32_e32 v120, 2, v136
	v_bitop3_b32 v120, v120, v142, 15 bitop3:0x78
	v_lshlrev_b32_e32 v135, 4, v120
	v_add_u32_e32 v140, v133, v135
	ds_read_b64 v[120:121], v140
	s_waitcnt lgkmcnt(0)
	v_cvt_f32_f16_e32 v122, v120
	v_cvt_f32_f16_sdwa v123, v120 dst_sel:DWORD dst_unused:UNUSED_PAD src0_sel:WORD_1
	v_cvt_f32_f16_e32 v120, v121
	v_cvt_f32_f16_sdwa v121, v121 dst_sel:DWORD dst_unused:UNUSED_PAD src0_sel:WORD_1
	v_pk_fma_f32 v[80:81], v[122:123], s[8:9], v[80:81] op_sel_hi:[1,0,1]
	v_pk_fma_f32 v[82:83], v[120:121], s[8:9], v[82:83] op_sel_hi:[1,0,1]
	ds_read_b64 v[120:121], v141
	s_waitcnt lgkmcnt(0)
	v_cvt_f32_f16_e32 v122, v120
	v_cvt_f32_f16_sdwa v123, v120 dst_sel:DWORD dst_unused:UNUSED_PAD src0_sel:WORD_1
	v_cvt_f32_f16_e32 v120, v121
	v_cvt_f32_f16_sdwa v121, v121 dst_sel:DWORD dst_unused:UNUSED_PAD src0_sel:WORD_1
	v_pk_fma_f32 v[92:93], v[122:123], s[8:9], v[92:93] op_sel_hi:[1,0,1]
	v_pk_fma_f32 v[94:95], v[120:121], s[8:9], v[94:95] op_sel_hi:[1,0,1]
	v_add_u32_e32 v120, 18, v136
	v_bitop3_b32 v120, v120, v142, 15 bitop3:0x78
	v_lshlrev_b32_e32 v136, 4, v120
	v_add_u32_e32 v142, v133, v136
	ds_read_b64 v[120:121], v142
	s_waitcnt lgkmcnt(0)
	v_cvt_f32_f16_e32 v144, v120
	v_cvt_f32_f16_sdwa v145, v120 dst_sel:DWORD dst_unused:UNUSED_PAD src0_sel:WORD_1
	v_cvt_f32_f16_e32 v120, v121
	v_cvt_f32_f16_sdwa v121, v121 dst_sel:DWORD dst_unused:UNUSED_PAD src0_sel:WORD_1
	v_pk_fma_f32 v[122:123], v[120:121], s[8:9], v[74:75] op_sel_hi:[1,0,1]
	v_pk_fma_f32 v[120:121], v[144:145], s[8:9], v[72:73] op_sel_hi:[1,0,1]
	s_nop 0
	ds_read_b64 v[72:73], v139 offset:8192
	s_waitcnt lgkmcnt(0)
	v_cvt_f32_f16_e32 v144, v72
	v_cvt_f32_f16_sdwa v145, v72 dst_sel:DWORD dst_unused:UNUSED_PAD src0_sel:WORD_1
	v_cvt_f32_f16_e32 v72, v73
	v_cvt_f32_f16_sdwa v73, v73 dst_sel:DWORD dst_unused:UNUSED_PAD src0_sel:WORD_1
	v_pk_fma_f32 v[74:75], v[72:73], s[8:9], v[118:119] op_sel_hi:[1,0,1]
	v_pk_fma_f32 v[72:73], v[144:145], s[8:9], v[116:117] op_sel_hi:[1,0,1]
	ds_read_b64 v[116:117], v140 offset:8192
	s_waitcnt lgkmcnt(0)
	v_cvt_f32_f16_e32 v118, v116
	v_cvt_f32_f16_sdwa v119, v116 dst_sel:DWORD dst_unused:UNUSED_PAD src0_sel:WORD_1
	v_cvt_f32_f16_e32 v116, v117
	v_cvt_f32_f16_sdwa v117, v117 dst_sel:DWORD dst_unused:UNUSED_PAD src0_sel:WORD_1
	v_pk_fma_f32 v[76:77], v[118:119], s[8:9], v[76:77] op_sel_hi:[1,0,1]
	v_pk_fma_f32 v[78:79], v[116:117], s[8:9], v[78:79] op_sel_hi:[1,0,1]
	ds_read_b64 v[116:117], v141 offset:8192
	s_waitcnt lgkmcnt(0)
	v_cvt_f32_f16_e32 v118, v116
	v_cvt_f32_f16_sdwa v119, v116 dst_sel:DWORD dst_unused:UNUSED_PAD src0_sel:WORD_1
	v_cvt_f32_f16_e32 v116, v117
	v_cvt_f32_f16_sdwa v117, v117 dst_sel:DWORD dst_unused:UNUSED_PAD src0_sel:WORD_1
	v_pk_fma_f32 v[84:85], v[118:119], s[8:9], v[84:85] op_sel_hi:[1,0,1]
	v_pk_fma_f32 v[86:87], v[116:117], s[8:9], v[86:87] op_sel_hi:[1,0,1]
	ds_read_b64 v[116:117], v142 offset:8192
	s_waitcnt lgkmcnt(0)
	v_cvt_f32_f16_e32 v144, v116
	v_cvt_f32_f16_sdwa v145, v116 dst_sel:DWORD dst_unused:UNUSED_PAD src0_sel:WORD_1
	v_cvt_f32_f16_e32 v116, v117
	v_cvt_f32_f16_sdwa v117, v117 dst_sel:DWORD dst_unused:UNUSED_PAD src0_sel:WORD_1
	v_pk_fma_f32 v[118:119], v[116:117], s[8:9], v[90:91] op_sel_hi:[1,0,1]
	v_pk_fma_f32 v[116:117], v[144:145], s[8:9], v[88:89] op_sel_hi:[1,0,1]
	s_nop 0
	ds_read_b64 v[88:89], v139 offset:16384
	s_waitcnt lgkmcnt(0)
	v_cvt_f32_f16_e32 v144, v88
	v_cvt_f32_f16_sdwa v145, v88 dst_sel:DWORD dst_unused:UNUSED_PAD src0_sel:WORD_1
	v_cvt_f32_f16_e32 v88, v89
	v_cvt_f32_f16_sdwa v89, v89 dst_sel:DWORD dst_unused:UNUSED_PAD src0_sel:WORD_1
	v_pk_fma_f32 v[90:91], v[88:89], s[8:9], v[130:131] op_sel_hi:[1,0,1]
	v_pk_fma_f32 v[88:89], v[144:145], s[8:9], v[128:129] op_sel_hi:[1,0,1]
	ds_read_b64 v[128:129], v140 offset:16384
	s_waitcnt lgkmcnt(0)
	v_cvt_f32_f16_e32 v130, v128
	v_cvt_f32_f16_sdwa v131, v128 dst_sel:DWORD dst_unused:UNUSED_PAD src0_sel:WORD_1
	v_cvt_f32_f16_e32 v128, v129
	v_cvt_f32_f16_sdwa v129, v129 dst_sel:DWORD dst_unused:UNUSED_PAD src0_sel:WORD_1
	v_pk_fma_f32 v[96:97], v[130:131], s[8:9], v[96:97] op_sel_hi:[1,0,1]
	v_pk_fma_f32 v[98:99], v[128:129], s[8:9], v[98:99] op_sel_hi:[1,0,1]
	ds_read_b64 v[128:129], v141 offset:16384
	s_waitcnt lgkmcnt(0)
	v_cvt_f32_f16_e32 v130, v128
	v_cvt_f32_f16_sdwa v131, v128 dst_sel:DWORD dst_unused:UNUSED_PAD src0_sel:WORD_1
	v_cvt_f32_f16_e32 v128, v129
	v_cvt_f32_f16_sdwa v129, v129 dst_sel:DWORD dst_unused:UNUSED_PAD src0_sel:WORD_1
	v_pk_fma_f32 v[104:105], v[130:131], s[8:9], v[104:105] op_sel_hi:[1,0,1]
	v_pk_fma_f32 v[106:107], v[128:129], s[8:9], v[106:107] op_sel_hi:[1,0,1]
	ds_read_b64 v[128:129], v142 offset:16384
	s_waitcnt lgkmcnt(0)
	v_cvt_f32_f16_e32 v144, v128
	v_cvt_f32_f16_sdwa v145, v128 dst_sel:DWORD dst_unused:UNUSED_PAD src0_sel:WORD_1
	v_cvt_f32_f16_e32 v128, v129
	v_cvt_f32_f16_sdwa v129, v129 dst_sel:DWORD dst_unused:UNUSED_PAD src0_sel:WORD_1
	v_pk_fma_f32 v[130:131], v[128:129], s[8:9], v[110:111] op_sel_hi:[1,0,1]
	v_pk_fma_f32 v[128:129], v[144:145], s[8:9], v[108:109] op_sel_hi:[1,0,1]
	s_nop 0
	ds_read_b64 v[108:109], v139 offset:24576
	v_add_u32_e32 v139, 0x10000, v133
	s_waitcnt lgkmcnt(0)
	v_cvt_f32_f16_e32 v144, v108
	v_cvt_f32_f16_sdwa v145, v108 dst_sel:DWORD dst_unused:UNUSED_PAD src0_sel:WORD_1
	v_cvt_f32_f16_e32 v108, v109
	v_cvt_f32_f16_sdwa v109, v109 dst_sel:DWORD dst_unused:UNUSED_PAD src0_sel:WORD_1
	v_pk_fma_f32 v[110:111], v[108:109], s[8:9], v[126:127] op_sel_hi:[1,0,1]
	v_pk_fma_f32 v[108:109], v[144:145], s[8:9], v[124:125] op_sel_hi:[1,0,1]
	ds_read_b64 v[124:125], v140 offset:24576
	s_waitcnt lgkmcnt(0)
	v_cvt_f32_f16_e32 v126, v124
	v_cvt_f32_f16_sdwa v127, v124 dst_sel:DWORD dst_unused:UNUSED_PAD src0_sel:WORD_1
	v_cvt_f32_f16_e32 v124, v125
	v_cvt_f32_f16_sdwa v125, v125 dst_sel:DWORD dst_unused:UNUSED_PAD src0_sel:WORD_1
	v_pk_fma_f32 v[112:113], v[126:127], s[8:9], v[112:113] op_sel_hi:[1,0,1]
	v_pk_fma_f32 v[114:115], v[124:125], s[8:9], v[114:115] op_sel_hi:[1,0,1]
	ds_read_b64 v[124:125], v141 offset:24576
	s_waitcnt lgkmcnt(0)
	v_cvt_f32_f16_e32 v126, v124
	v_cvt_f32_f16_sdwa v127, v124 dst_sel:DWORD dst_unused:UNUSED_PAD src0_sel:WORD_1
	v_cvt_f32_f16_e32 v124, v125
	v_cvt_f32_f16_sdwa v125, v125 dst_sel:DWORD dst_unused:UNUSED_PAD src0_sel:WORD_1
	v_pk_fma_f32 v[100:101], v[126:127], s[8:9], v[100:101] op_sel_hi:[1,0,1]
	v_pk_fma_f32 v[102:103], v[124:125], s[8:9], v[102:103] op_sel_hi:[1,0,1]
	ds_read_b64 v[124:125], v142 offset:24576
	s_waitcnt lgkmcnt(0)
	v_cvt_f32_f16_e32 v126, v124
	v_cvt_f32_f16_sdwa v127, v124 dst_sel:DWORD dst_unused:UNUSED_PAD src0_sel:WORD_1
	v_cvt_f32_f16_e32 v124, v125
	v_cvt_f32_f16_sdwa v125, v125 dst_sel:DWORD dst_unused:UNUSED_PAD src0_sel:WORD_1
	v_pk_fma_f32 v[64:65], v[126:127], s[8:9], v[64:65] op_sel_hi:[1,0,1]
	v_pk_fma_f32 v[66:67], v[124:125], s[8:9], v[66:67] op_sel_hi:[1,0,1]
	v_add_u32_e32 v124, v139, v134
	ds_read_b64 v[124:125], v124
	s_waitcnt lgkmcnt(0)
	v_cvt_f32_f16_e32 v126, v124
	v_cvt_f32_f16_sdwa v127, v124 dst_sel:DWORD dst_unused:UNUSED_PAD src0_sel:WORD_1
	v_cvt_f32_f16_e32 v124, v125
	v_cvt_f32_f16_sdwa v125, v125 dst_sel:DWORD dst_unused:UNUSED_PAD src0_sel:WORD_1
	v_pk_fma_f32 v[60:61], v[126:127], s[8:9], v[60:61] op_sel_hi:[1,0,1]
	v_pk_fma_f32 v[62:63], v[124:125], s[8:9], v[62:63] op_sel_hi:[1,0,1]
	v_add_u32_e32 v124, v139, v135
	ds_read_b64 v[124:125], v124
	s_waitcnt lgkmcnt(0)
	v_cvt_f32_f16_e32 v126, v124
	v_cvt_f32_f16_sdwa v127, v124 dst_sel:DWORD dst_unused:UNUSED_PAD src0_sel:WORD_1
	v_cvt_f32_f16_e32 v124, v125
	v_cvt_f32_f16_sdwa v125, v125 dst_sel:DWORD dst_unused:UNUSED_PAD src0_sel:WORD_1
	v_pk_fma_f32 v[56:57], v[126:127], s[8:9], v[56:57] op_sel_hi:[1,0,1]
	v_pk_fma_f32 v[58:59], v[124:125], s[8:9], v[58:59] op_sel_hi:[1,0,1]
	v_add_u32_e32 v124, v139, v132
	ds_read_b64 v[124:125], v124
	s_waitcnt lgkmcnt(0)
	v_cvt_f32_f16_e32 v126, v124
	v_cvt_f32_f16_sdwa v127, v124 dst_sel:DWORD dst_unused:UNUSED_PAD src0_sel:WORD_1
	v_cvt_f32_f16_e32 v124, v125
	v_cvt_f32_f16_sdwa v125, v125 dst_sel:DWORD dst_unused:UNUSED_PAD src0_sel:WORD_1
	v_pk_fma_f32 v[52:53], v[126:127], s[8:9], v[52:53] op_sel_hi:[1,0,1]
	v_pk_fma_f32 v[54:55], v[124:125], s[8:9], v[54:55] op_sel_hi:[1,0,1]
	v_add_u32_e32 v124, v139, v136
	ds_read_b64 v[124:125], v124
	s_waitcnt lgkmcnt(0)
	v_cvt_f32_f16_e32 v126, v124
	v_cvt_f32_f16_sdwa v127, v124 dst_sel:DWORD dst_unused:UNUSED_PAD src0_sel:WORD_1
	v_cvt_f32_f16_e32 v124, v125
	v_cvt_f32_f16_sdwa v125, v125 dst_sel:DWORD dst_unused:UNUSED_PAD src0_sel:WORD_1
	v_pk_fma_f32 v[48:49], v[126:127], s[8:9], v[48:49] op_sel_hi:[1,0,1]
	v_pk_fma_f32 v[50:51], v[124:125], s[8:9], v[50:51] op_sel_hi:[1,0,1]
	v_add_u32_e32 v124, 0x12000, v138
	v_and_b32_e32 v124, 0xffffbc00, v124
	v_add_u32_e32 v137, v137, v124
	v_add_u32_e32 v124, v137, v134
	ds_read_b64 v[124:125], v124
	s_waitcnt lgkmcnt(0)
	v_cvt_f32_f16_e32 v126, v124
	v_cvt_f32_f16_sdwa v127, v124 dst_sel:DWORD dst_unused:UNUSED_PAD src0_sel:WORD_1
	v_cvt_f32_f16_e32 v124, v125
	v_cvt_f32_f16_sdwa v125, v125 dst_sel:DWORD dst_unused:UNUSED_PAD src0_sel:WORD_1
	v_pk_fma_f32 v[44:45], v[126:127], s[8:9], v[44:45] op_sel_hi:[1,0,1]
	v_pk_fma_f32 v[46:47], v[124:125], s[8:9], v[46:47] op_sel_hi:[1,0,1]
	v_add_u32_e32 v124, v137, v135
	ds_read_b64 v[124:125], v124
	s_waitcnt lgkmcnt(0)
	v_cvt_f32_f16_e32 v126, v124
	v_cvt_f32_f16_sdwa v127, v124 dst_sel:DWORD dst_unused:UNUSED_PAD src0_sel:WORD_1
	v_cvt_f32_f16_e32 v124, v125
	v_cvt_f32_f16_sdwa v125, v125 dst_sel:DWORD dst_unused:UNUSED_PAD src0_sel:WORD_1
	v_pk_fma_f32 v[40:41], v[126:127], s[8:9], v[40:41] op_sel_hi:[1,0,1]
	v_pk_fma_f32 v[42:43], v[124:125], s[8:9], v[42:43] op_sel_hi:[1,0,1]
	v_add_u32_e32 v124, v137, v132
	ds_read_b64 v[124:125], v124
	s_waitcnt lgkmcnt(0)
	v_cvt_f32_f16_e32 v126, v124
	v_cvt_f32_f16_sdwa v127, v124 dst_sel:DWORD dst_unused:UNUSED_PAD src0_sel:WORD_1
	v_cvt_f32_f16_e32 v124, v125
	v_cvt_f32_f16_sdwa v125, v125 dst_sel:DWORD dst_unused:UNUSED_PAD src0_sel:WORD_1
	v_pk_fma_f32 v[36:37], v[126:127], s[8:9], v[36:37] op_sel_hi:[1,0,1]
	v_pk_fma_f32 v[38:39], v[124:125], s[8:9], v[38:39] op_sel_hi:[1,0,1]
	v_add_u32_e32 v124, v137, v136
	ds_read_b64 v[124:125], v124
	v_add_u32_e32 v137, 0x14000, v133
	v_add_u32_e32 v133, 0x16000, v133
	s_waitcnt lgkmcnt(0)
	v_cvt_f32_f16_e32 v126, v124
	v_cvt_f32_f16_sdwa v127, v124 dst_sel:DWORD dst_unused:UNUSED_PAD src0_sel:WORD_1
	v_cvt_f32_f16_e32 v124, v125
	v_cvt_f32_f16_sdwa v125, v125 dst_sel:DWORD dst_unused:UNUSED_PAD src0_sel:WORD_1
	v_pk_fma_f32 v[32:33], v[126:127], s[8:9], v[32:33] op_sel_hi:[1,0,1]
	v_pk_fma_f32 v[34:35], v[124:125], s[8:9], v[34:35] op_sel_hi:[1,0,1]
	v_add_u32_e32 v124, v137, v134
	ds_read_b64 v[124:125], v124
	s_waitcnt lgkmcnt(0)
	v_cvt_f32_f16_e32 v126, v124
	v_cvt_f32_f16_sdwa v127, v124 dst_sel:DWORD dst_unused:UNUSED_PAD src0_sel:WORD_1
	v_cvt_f32_f16_e32 v124, v125
	v_cvt_f32_f16_sdwa v125, v125 dst_sel:DWORD dst_unused:UNUSED_PAD src0_sel:WORD_1
	v_pk_fma_f32 v[28:29], v[126:127], s[8:9], v[28:29] op_sel_hi:[1,0,1]
	v_pk_fma_f32 v[30:31], v[124:125], s[8:9], v[30:31] op_sel_hi:[1,0,1]
	v_add_u32_e32 v124, v137, v135
	ds_read_b64 v[124:125], v124
	s_waitcnt lgkmcnt(0)
	v_cvt_f32_f16_e32 v126, v124
	v_cvt_f32_f16_sdwa v127, v124 dst_sel:DWORD dst_unused:UNUSED_PAD src0_sel:WORD_1
	v_cvt_f32_f16_e32 v124, v125
	v_cvt_f32_f16_sdwa v125, v125 dst_sel:DWORD dst_unused:UNUSED_PAD src0_sel:WORD_1
	v_pk_fma_f32 v[24:25], v[126:127], s[8:9], v[24:25] op_sel_hi:[1,0,1]
	v_pk_fma_f32 v[26:27], v[124:125], s[8:9], v[26:27] op_sel_hi:[1,0,1]
	v_add_u32_e32 v124, v137, v132
	ds_read_b64 v[124:125], v124
	s_waitcnt lgkmcnt(0)
	v_cvt_f32_f16_e32 v126, v124
	v_cvt_f32_f16_sdwa v127, v124 dst_sel:DWORD dst_unused:UNUSED_PAD src0_sel:WORD_1
	v_cvt_f32_f16_e32 v124, v125
	v_cvt_f32_f16_sdwa v125, v125 dst_sel:DWORD dst_unused:UNUSED_PAD src0_sel:WORD_1
	v_pk_fma_f32 v[20:21], v[126:127], s[8:9], v[20:21] op_sel_hi:[1,0,1]
	v_pk_fma_f32 v[22:23], v[124:125], s[8:9], v[22:23] op_sel_hi:[1,0,1]
	v_add_u32_e32 v124, v137, v136
	ds_read_b64 v[124:125], v124
	s_waitcnt lgkmcnt(0)
	v_cvt_f32_f16_e32 v126, v124
	v_cvt_f32_f16_sdwa v127, v124 dst_sel:DWORD dst_unused:UNUSED_PAD src0_sel:WORD_1
	v_cvt_f32_f16_e32 v124, v125
	v_cvt_f32_f16_sdwa v125, v125 dst_sel:DWORD dst_unused:UNUSED_PAD src0_sel:WORD_1
	v_pk_fma_f32 v[16:17], v[126:127], s[8:9], v[16:17] op_sel_hi:[1,0,1]
	v_pk_fma_f32 v[18:19], v[124:125], s[8:9], v[18:19] op_sel_hi:[1,0,1]
	v_add_u32_e32 v124, v133, v134
	ds_read_b64 v[124:125], v124
	s_waitcnt lgkmcnt(0)
	v_cvt_f32_f16_e32 v126, v124
	v_cvt_f32_f16_sdwa v127, v124 dst_sel:DWORD dst_unused:UNUSED_PAD src0_sel:WORD_1
	v_cvt_f32_f16_e32 v124, v125
	v_cvt_f32_f16_sdwa v125, v125 dst_sel:DWORD dst_unused:UNUSED_PAD src0_sel:WORD_1
	v_pk_fma_f32 v[12:13], v[126:127], s[8:9], v[12:13] op_sel_hi:[1,0,1]
	v_pk_fma_f32 v[14:15], v[124:125], s[8:9], v[14:15] op_sel_hi:[1,0,1]
	v_add_u32_e32 v124, v133, v135
	ds_read_b64 v[124:125], v124
	v_pk_add_f32 v[134:135], v[70:71], 0 op_sel_hi:[1,0]
	v_pk_add_f32 v[70:71], v[122:123], 0 op_sel_hi:[1,0]
	s_waitcnt lgkmcnt(0)
	v_cvt_f32_f16_e32 v126, v124
	v_cvt_f32_f16_sdwa v127, v124 dst_sel:DWORD dst_unused:UNUSED_PAD src0_sel:WORD_1
	v_cvt_f32_f16_e32 v124, v125
	v_cvt_f32_f16_sdwa v125, v125 dst_sel:DWORD dst_unused:UNUSED_PAD src0_sel:WORD_1
	v_pk_fma_f32 v[8:9], v[126:127], s[8:9], v[8:9] op_sel_hi:[1,0,1]
	v_pk_fma_f32 v[10:11], v[124:125], s[8:9], v[10:11] op_sel_hi:[1,0,1]
	v_add_u32_e32 v124, v133, v132
	ds_read_b64 v[124:125], v124
	s_waitcnt lgkmcnt(0)
	v_cvt_f32_f16_e32 v126, v124
	v_cvt_f32_f16_sdwa v127, v124 dst_sel:DWORD dst_unused:UNUSED_PAD src0_sel:WORD_1
	v_cvt_f32_f16_e32 v124, v125
	v_cvt_f32_f16_sdwa v125, v125 dst_sel:DWORD dst_unused:UNUSED_PAD src0_sel:WORD_1
	v_pk_fma_f32 v[4:5], v[126:127], s[8:9], v[4:5] op_sel_hi:[1,0,1]
	v_pk_fma_f32 v[6:7], v[124:125], s[8:9], v[6:7] op_sel_hi:[1,0,1]
	v_add_u32_e32 v124, v133, v136
	ds_read_b64 v[124:125], v124
	v_pk_add_f32 v[132:133], v[68:69], 0 op_sel_hi:[1,0]
	v_pk_add_f32 v[68:69], v[120:121], 0 op_sel_hi:[1,0]
	s_waitcnt lgkmcnt(0)
	v_cvt_f32_f16_e32 v126, v124
	v_cvt_f32_f16_sdwa v127, v124 dst_sel:DWORD dst_unused:UNUSED_PAD src0_sel:WORD_1
	v_cvt_f32_f16_e32 v124, v125
	v_cvt_f32_f16_sdwa v125, v125 dst_sel:DWORD dst_unused:UNUSED_PAD src0_sel:WORD_1
	v_mov_b32_e32 v122, v69
	v_pk_fma_f32 v[0:1], v[126:127], s[8:9], v[0:1] op_sel_hi:[1,0,1]
	v_pk_add_f32 v[126:127], v[82:83], 0 op_sel_hi:[1,0]
	v_pk_fma_f32 v[2:3], v[124:125], s[8:9], v[2:3] op_sel_hi:[1,0,1]
	v_pk_add_f32 v[124:125], v[80:81], 0 op_sel_hi:[1,0]
	v_pk_add_f32 v[80:81], v[92:93], 0 op_sel_hi:[1,0]
	v_lshlrev_b32_e32 v92, 2, v143
	v_pk_add_f32 v[82:83], v[94:95], 0 op_sel_hi:[1,0]
	v_xor_b32_e32 v148, 64, v92
	v_xor_b32_e32 v142, 0x80, v92
	v_pk_mov_b32 v[92:93], v[132:133], v[134:135] op_sel:[1,0]
	v_mov_b32_e32 v94, v132
	v_mov_b32_e32 v95, v135
	v_pk_add_f32 v[92:93], v[92:93], v[94:95]
	v_pk_mov_b32 v[94:95], v[124:125], v[126:127] op_sel:[1,0]
	v_mov_b32_e32 v120, v124
	v_mov_b32_e32 v121, v127
	v_pk_add_f32 v[94:95], v[94:95], v[120:121]
	v_pk_add_f32 v[92:93], v[92:93], v[92:93] op_sel_hi:[0,1]
	v_pk_add_f32 v[94:95], v[94:95], v[94:95] op_sel_hi:[0,1]
	v_add_f32_e32 v121, v80, v81
	v_add_f32_e32 v123, v82, v83
	v_mov_b32_e32 v120, v68
	v_mov_b32_e32 v92, v70
	v_mov_b32_e32 v94, v71
	v_pk_add_f32 v[120:121], v[120:121], v[122:123]
	v_pk_add_f32 v[92:93], v[92:93], v[94:95]
	s_waitcnt lgkmcnt(0)
	s_barrier
	v_pk_add_f32 v[92:93], v[120:121], v[92:93]
	s_nop 0
	v_add_f32_e32 v92, v92, v93
	s_mov_b32 s100, 0xffff0000
	s_mov_b32 s101, 0xffff0000
	s_mov_b32 s98, 0
	s_mov_b32 s99, -1
	v_mov_b32_e32 v93, v92
	v_mov_b32_e32 v210, v92
	s_nop 1
	v_permlane16_swap_b32_e32 v93, v210
	v_cndmask_b32_e64 v93, v210, v93, s[100:101]
	s_waitcnt lgkmcnt(0)
	v_add_f32_e32 v92, v92, v93
	v_mov_b32_e32 v93, v92
	v_mov_b32_e32 v210, v92
	s_nop 1
	v_permlane32_swap_b32_e32 v93, v210
	v_cndmask_b32_e64 v93, v210, v93, s[98:99]
	s_waitcnt lgkmcnt(0)
	v_add_f32_e32 v92, v92, v93
	v_fmamk_f32 v94, v92, 0xbc800000, v135
	v_fmamk_f32 v120, v92, 0xbc800000, v133
	v_fmamk_f32 v93, v92, 0xbc800000, v134
	v_fmamk_f32 v95, v92, 0xbc800000, v132
	v_mul_f32_e32 v120, v120, v120
	v_mul_f32_e32 v94, v94, v94
	v_fmac_f32_e32 v120, v95, v95
	v_fmac_f32_e32 v94, v93, v93
	v_fmamk_f32 v95, v92, 0xbc800000, v127
	v_fmamk_f32 v121, v92, 0xbc800000, v125
	v_add_f32_e32 v93, v120, v94
	v_fmamk_f32 v94, v92, 0xbc800000, v126
	v_fmamk_f32 v120, v92, 0xbc800000, v124
	v_mul_f32_e32 v121, v121, v121
	v_mul_f32_e32 v95, v95, v95
	v_fmac_f32_e32 v121, v120, v120
	v_fmac_f32_e32 v95, v94, v94
	v_add_f32_e32 v94, v121, v95
	v_fmamk_f32 v95, v92, 0xbc800000, v83
	v_fmamk_f32 v121, v92, 0xbc800000, v81
	v_add_f32_e32 v93, v93, v94
	v_fmamk_f32 v94, v92, 0xbc800000, v82
	v_fmamk_f32 v120, v92, 0xbc800000, v80
	v_mul_f32_e32 v121, v121, v121
	v_mul_f32_e32 v95, v95, v95
	v_fmac_f32_e32 v121, v120, v120
	v_fmac_f32_e32 v95, v94, v94
	v_add_f32_e32 v94, v121, v95
	v_fmamk_f32 v95, v92, 0xbc800000, v71
	v_fmamk_f32 v121, v92, 0xbc800000, v69
	v_add_f32_e32 v93, v94, v93
	v_fmamk_f32 v94, v92, 0xbc800000, v70
	v_fmamk_f32 v120, v92, 0xbc800000, v68
	v_mul_f32_e32 v121, v121, v121
	v_mul_f32_e32 v95, v95, v95
	v_fmac_f32_e32 v121, v120, v120
	v_fmac_f32_e32 v95, v94, v94
	v_add_f32_e32 v94, v121, v95
	v_add_f32_e32 v93, v94, v93
	v_mov_b32_e32 v94, v93
	v_mov_b32_e32 v210, v93
	s_nop 1
	v_permlane16_swap_b32_e32 v94, v210
	v_cndmask_b32_e64 v94, v210, v94, s[100:101]
	s_waitcnt lgkmcnt(0)
	v_add_f32_e32 v93, v93, v94
	v_mov_b32_e32 v94, v93
	v_mov_b32_e32 v210, v93
	s_nop 1
	v_permlane32_swap_b32_e32 v94, v210
	v_cndmask_b32_e64 v94, v210, v94, s[98:99]
	s_and_saveexec_b64 s[8:9], vcc
	s_cbranch_execz .LBB0_497
	s_lshl_b32 s3, s22, 11
	s_add_i32 s3, s12, s3
	v_mul_f32_e32 v92, 0x3c800000, v92
	s_waitcnt lgkmcnt(0)
	v_add_f32_e32 v93, v93, v94
	v_lshl_add_u32 v94, v143, 5, s3
	ds_write_b64 v94, v[92:93]
.LBB0_497:
	s_or_b64 exec, exec, s[8:9]
	v_max_f32_e64 v92, |v135|, |v135|
	v_max_f32_e64 v93, |v134|, |v134|
	v_max_f32_e32 v92, v93, v92
	v_max_f32_e64 v93, |v127|, |v127|
	s_waitcnt lgkmcnt(0)
	v_max_f32_e64 v94, |v126|, |v126|
	v_max_f32_e32 v93, v94, v93
	v_max3_f32 v92, |v132|, |v133|, v92
	v_max3_f32 v93, |v124|, |v125|, v93
	v_max3_f32 v92, v92, 0, v93
	v_max_f32_e64 v93, |v83|, |v83|
	v_max_f32_e64 v94, |v82|, |v82|
	v_max_f32_e32 v93, v94, v93
	v_max_f32_e64 v94, |v71|, |v71|
	v_max_f32_e64 v95, |v70|, |v70|
	v_max_f32_e32 v94, v95, v94
	v_max3_f32 v93, |v80|, |v81|, v93
	v_max3_f32 v94, |v68|, |v69|, v94
	v_max3_f32 v92, v92, v93, v94
	v_mov_b32_e32 v93, v92
	v_mov_b32_e32 v210, v92
	s_nop 1
	v_permlane16_swap_b32_e32 v93, v210
	v_cndmask_b32_e64 v93, v210, v93, s[100:101]
	s_sub_i32 s11, s12, s11
	s_waitcnt lgkmcnt(0)
	v_max_f32_e32 v93, v93, v93
	v_max_f32_e32 v92, v92, v93
	v_mov_b32_e32 v93, v92
	v_mov_b32_e32 v210, v92
	s_nop 1
	v_permlane32_swap_b32_e32 v93, v210
	v_cndmask_b32_e64 v93, v210, v93, s[98:99]
	s_and_saveexec_b64 s[8:9], vcc
	s_cbranch_execz .LBB0_499
	s_lshl_b32 s3, s22, 10
	s_waitcnt lgkmcnt(0)
	v_max_f32_e32 v93, v93, v93
	v_max_f32_e32 v92, v92, v92
	s_add_i32 s3, s11, s3
	v_max_f32_e32 v92, v92, v93
	v_lshl_add_u32 v93, v143, 4, s3
	ds_write_b32 v93, v92 offset:16384
.LBB0_499:
	s_or_b64 exec, exec, s[8:9]
	v_pk_add_f32 v[138:139], v[74:75], 0 op_sel_hi:[1,0]
	v_pk_add_f32 v[136:137], v[72:73], 0 op_sel_hi:[1,0]
	v_pk_add_f32 v[120:121], v[78:79], 0 op_sel_hi:[1,0]
	v_pk_add_f32 v[122:123], v[76:77], 0 op_sel_hi:[1,0]
	v_pk_add_f32 v[86:87], v[86:87], 0 op_sel_hi:[1,0]
	v_pk_add_f32 v[84:85], v[84:85], 0 op_sel_hi:[1,0]
	v_pk_add_f32 v[72:73], v[118:119], 0 op_sel_hi:[1,0]
	v_pk_add_f32 v[74:75], v[116:117], 0 op_sel_hi:[1,0]
	v_pk_mov_b32 v[76:77], v[136:137], v[138:139] op_sel:[1,0]
	v_mov_b32_e32 v78, v136
	v_mov_b32_e32 v79, v139
	v_pk_add_f32 v[76:77], v[76:77], v[78:79]
	v_pk_mov_b32 v[78:79], v[122:123], v[120:121] op_sel:[1,0]
	v_mov_b32_e32 v92, v122
	s_waitcnt lgkmcnt(0)
	v_mov_b32_e32 v93, v121
	v_pk_add_f32 v[78:79], v[78:79], v[92:93]
	v_pk_add_f32 v[76:77], v[76:77], v[76:77] op_sel_hi:[0,1]
	v_pk_add_f32 v[78:79], v[78:79], v[78:79] op_sel_hi:[0,1]
	v_add_f32_e32 v93, v84, v85
	v_add_f32_e32 v95, v86, v87
	v_mov_b32_e32 v92, v74
	v_mov_b32_e32 v94, v75
	v_mov_b32_e32 v76, v72
	v_mov_b32_e32 v78, v73
	v_pk_add_f32 v[92:93], v[92:93], v[94:95]
	v_pk_add_f32 v[76:77], v[76:77], v[78:79]
	s_nop 0
	v_pk_add_f32 v[76:77], v[92:93], v[76:77]
	s_nop 0
	v_add_f32_e32 v76, v76, v77
	v_mov_b32_e32 v77, v76
	v_mov_b32_e32 v210, v76
	s_nop 1
	v_permlane16_swap_b32_e32 v77, v210
	v_cndmask_b32_e64 v77, v210, v77, s[100:101]
	s_waitcnt lgkmcnt(0)
	v_add_f32_e32 v76, v76, v77
	v_mov_b32_e32 v77, v76
	v_mov_b32_e32 v210, v76
	s_nop 1
	v_permlane32_swap_b32_e32 v77, v210
	v_cndmask_b32_e64 v77, v210, v77, s[98:99]
	s_waitcnt lgkmcnt(0)
	v_add_f32_e32 v76, v76, v77
	v_fmamk_f32 v78, v76, 0xbc800000, v139
	v_fmamk_f32 v92, v76, 0xbc800000, v137
	v_fmamk_f32 v77, v76, 0xbc800000, v138
	v_fmamk_f32 v79, v76, 0xbc800000, v136
	v_mul_f32_e32 v92, v92, v92
	v_mul_f32_e32 v78, v78, v78
	v_fmac_f32_e32 v92, v79, v79
	v_fmac_f32_e32 v78, v77, v77
	v_fmamk_f32 v79, v76, 0xbc800000, v121
	v_fmamk_f32 v93, v76, 0xbc800000, v123
	v_add_f32_e32 v77, v92, v78
	v_fmamk_f32 v78, v76, 0xbc800000, v120
	v_fmamk_f32 v92, v76, 0xbc800000, v122
	v_mul_f32_e32 v93, v93, v93
	v_mul_f32_e32 v79, v79, v79
	v_fmac_f32_e32 v93, v92, v92
	v_fmac_f32_e32 v79, v78, v78
	v_add_f32_e32 v78, v93, v79
	v_fmamk_f32 v79, v76, 0xbc800000, v87
	v_fmamk_f32 v93, v76, 0xbc800000, v85
	v_add_f32_e32 v77, v77, v78
	v_fmamk_f32 v78, v76, 0xbc800000, v86
	v_fmamk_f32 v92, v76, 0xbc800000, v84
	v_mul_f32_e32 v93, v93, v93
	v_mul_f32_e32 v79, v79, v79
	v_fmac_f32_e32 v93, v92, v92
	v_fmac_f32_e32 v79, v78, v78
	v_add_f32_e32 v78, v93, v79
	v_fmamk_f32 v79, v76, 0xbc800000, v73
	v_fmamk_f32 v93, v76, 0xbc800000, v75
	v_add_f32_e32 v77, v78, v77
	v_fmamk_f32 v78, v76, 0xbc800000, v72
	v_fmamk_f32 v92, v76, 0xbc800000, v74
	v_mul_f32_e32 v93, v93, v93
	v_mul_f32_e32 v79, v79, v79
	v_fmac_f32_e32 v93, v92, v92
	v_fmac_f32_e32 v79, v78, v78
	v_add_f32_e32 v78, v93, v79
	v_add_f32_e32 v77, v78, v77
	v_mov_b32_e32 v78, v77
	v_mov_b32_e32 v210, v77
	s_nop 1
	v_permlane16_swap_b32_e32 v78, v210
	v_cndmask_b32_e64 v78, v210, v78, s[100:101]
	s_waitcnt lgkmcnt(0)
	v_add_f32_e32 v77, v77, v78
	v_mov_b32_e32 v78, v77
	v_mov_b32_e32 v210, v77
	s_nop 1
	v_permlane32_swap_b32_e32 v78, v210
	v_cndmask_b32_e64 v78, v210, v78, s[98:99]
	s_and_saveexec_b64 s[8:9], vcc
	s_cbranch_execz .LBB0_501
	s_lshl_b32 s3, s22, 11
	s_add_i32 s3, s12, s3
	v_mul_f32_e32 v76, 0x3c800000, v76
	s_waitcnt lgkmcnt(0)
	v_add_f32_e32 v77, v77, v78
	v_lshl_add_u32 v78, v143, 5, s3
	ds_write_b64 v78, v[76:77] offset:512
.LBB0_501:
	s_or_b64 exec, exec, s[8:9]
	v_max_f32_e64 v76, |v139|, |v139|
	v_max_f32_e64 v77, |v138|, |v138|
	v_max_f32_e32 v76, v77, v76
	v_max_f32_e64 v77, |v121|, |v121|
	s_waitcnt lgkmcnt(0)
	v_max_f32_e64 v78, |v120|, |v120|
	v_max_f32_e32 v77, v78, v77
	v_max3_f32 v76, |v136|, |v137|, v76
	v_max3_f32 v77, |v122|, |v123|, v77
	v_max3_f32 v76, v76, 0, v77
	v_max_f32_e64 v77, |v87|, |v87|
	v_max_f32_e64 v78, |v86|, |v86|
	v_max_f32_e32 v77, v78, v77
	v_max_f32_e64 v78, |v73|, |v73|
	v_max_f32_e64 v79, |v72|, |v72|
	v_max_f32_e32 v78, v79, v78
	v_max3_f32 v77, |v84|, |v85|, v77
	v_max3_f32 v78, |v74|, |v75|, v78
	v_max3_f32 v76, v76, v77, v78
	v_mov_b32_e32 v77, v76
	v_mov_b32_e32 v210, v76
	s_nop 1
	v_permlane16_swap_b32_e32 v77, v210
	v_cndmask_b32_e64 v77, v210, v77, s[100:101]
	s_waitcnt lgkmcnt(0)
	v_max_f32_e32 v77, v77, v77
	v_max_f32_e32 v76, v76, v77
	v_mov_b32_e32 v77, v76
	v_mov_b32_e32 v210, v76
	s_nop 1
	v_permlane32_swap_b32_e32 v77, v210
	v_cndmask_b32_e64 v77, v210, v77, s[98:99]
	s_and_saveexec_b64 s[8:9], vcc
	s_cbranch_execz .LBB0_503
	s_lshl_b32 s3, s22, 10
	s_waitcnt lgkmcnt(0)
	v_max_f32_e32 v77, v77, v77
	v_max_f32_e32 v76, v76, v76
	s_add_i32 s3, s11, s3
	v_max_f32_e32 v76, v76, v77
	v_lshl_add_u32 v77, v143, 4, s3
	ds_write_b32 v77, v76 offset:16640
.LBB0_503:
	s_or_b64 exec, exec, s[8:9]
	v_pk_add_f32 v[118:119], v[90:91], 0 op_sel_hi:[1,0]
	v_pk_add_f32 v[116:117], v[88:89], 0 op_sel_hi:[1,0]
	v_pk_add_f32 v[98:99], v[98:99], 0 op_sel_hi:[1,0]
	v_pk_add_f32 v[96:97], v[96:97], 0 op_sel_hi:[1,0]
	v_pk_add_f32 v[90:91], v[106:107], 0 op_sel_hi:[1,0]
	v_pk_add_f32 v[88:89], v[104:105], 0 op_sel_hi:[1,0]
	v_pk_add_f32 v[78:79], v[130:131], 0 op_sel_hi:[1,0]
	s_waitcnt lgkmcnt(0)
	v_pk_add_f32 v[76:77], v[128:129], 0 op_sel_hi:[1,0]
	v_pk_mov_b32 v[92:93], v[116:117], v[118:119] op_sel:[1,0]
	v_mov_b32_e32 v94, v116
	v_mov_b32_e32 v95, v119
	v_pk_add_f32 v[92:93], v[92:93], v[94:95]
	v_pk_mov_b32 v[94:95], v[96:97], v[98:99] op_sel:[1,0]
	v_mov_b32_e32 v104, v96
	v_mov_b32_e32 v105, v99
	v_pk_add_f32 v[94:95], v[94:95], v[104:105]
	v_pk_add_f32 v[92:93], v[92:93], v[92:93] op_sel_hi:[0,1]
	v_pk_add_f32 v[94:95], v[94:95], v[94:95] op_sel_hi:[0,1]
	v_add_f32_e32 v105, v88, v89
	v_add_f32_e32 v107, v90, v91
	v_mov_b32_e32 v104, v76
	v_mov_b32_e32 v106, v77
	v_mov_b32_e32 v92, v78
	v_mov_b32_e32 v94, v79
	v_pk_add_f32 v[104:105], v[104:105], v[106:107]
	v_pk_add_f32 v[92:93], v[92:93], v[94:95]
	s_nop 0
	v_pk_add_f32 v[92:93], v[104:105], v[92:93]
	s_nop 0
	v_add_f32_e32 v92, v92, v93
	v_mov_b32_e32 v93, v92
	v_mov_b32_e32 v210, v92
	s_nop 1
	v_permlane16_swap_b32_e32 v93, v210
	v_cndmask_b32_e64 v93, v210, v93, s[100:101]
	s_waitcnt lgkmcnt(0)
	v_add_f32_e32 v92, v92, v93
	v_mov_b32_e32 v93, v92
	v_mov_b32_e32 v210, v92
	s_nop 1
	v_permlane32_swap_b32_e32 v93, v210
	v_cndmask_b32_e64 v93, v210, v93, s[98:99]
	s_waitcnt lgkmcnt(0)
	v_add_f32_e32 v92, v92, v93
	v_fmamk_f32 v94, v92, 0xbc800000, v119
	v_fmamk_f32 v104, v92, 0xbc800000, v117
	v_fmamk_f32 v93, v92, 0xbc800000, v118
	v_fmamk_f32 v95, v92, 0xbc800000, v116
	v_mul_f32_e32 v104, v104, v104
	v_mul_f32_e32 v94, v94, v94
	v_fmac_f32_e32 v104, v95, v95
	v_fmac_f32_e32 v94, v93, v93
	v_fmamk_f32 v95, v92, 0xbc800000, v99
	v_fmamk_f32 v105, v92, 0xbc800000, v97
	v_add_f32_e32 v93, v104, v94
	v_fmamk_f32 v94, v92, 0xbc800000, v98
	v_fmamk_f32 v104, v92, 0xbc800000, v96
	v_mul_f32_e32 v105, v105, v105
	v_mul_f32_e32 v95, v95, v95
	v_fmac_f32_e32 v105, v104, v104
	v_fmac_f32_e32 v95, v94, v94
	v_add_f32_e32 v94, v105, v95
	v_fmamk_f32 v95, v92, 0xbc800000, v91
	v_fmamk_f32 v105, v92, 0xbc800000, v89
	v_add_f32_e32 v93, v93, v94
	v_fmamk_f32 v94, v92, 0xbc800000, v90
	v_fmamk_f32 v104, v92, 0xbc800000, v88
	v_mul_f32_e32 v105, v105, v105
	v_mul_f32_e32 v95, v95, v95
	v_fmac_f32_e32 v105, v104, v104
	v_fmac_f32_e32 v95, v94, v94
	v_add_f32_e32 v94, v105, v95
	v_fmamk_f32 v95, v92, 0xbc800000, v79
	v_fmamk_f32 v105, v92, 0xbc800000, v77
	v_add_f32_e32 v93, v94, v93
	v_fmamk_f32 v94, v92, 0xbc800000, v78
	v_fmamk_f32 v104, v92, 0xbc800000, v76
	v_mul_f32_e32 v105, v105, v105
	v_mul_f32_e32 v95, v95, v95
	v_fmac_f32_e32 v105, v104, v104
	v_fmac_f32_e32 v95, v94, v94
	v_add_f32_e32 v94, v105, v95
	v_add_f32_e32 v93, v94, v93
	v_mov_b32_e32 v94, v93
	v_mov_b32_e32 v210, v93
	s_nop 1
	v_permlane16_swap_b32_e32 v94, v210
	v_cndmask_b32_e64 v94, v210, v94, s[100:101]
	s_waitcnt lgkmcnt(0)
	v_add_f32_e32 v93, v93, v94
	v_mov_b32_e32 v94, v93
	v_mov_b32_e32 v210, v93
	s_nop 1
	v_permlane32_swap_b32_e32 v94, v210
	v_cndmask_b32_e64 v94, v210, v94, s[98:99]
	s_and_saveexec_b64 s[8:9], vcc
	s_cbranch_execz .LBB0_505
	s_lshl_b32 s3, s22, 11
	s_add_i32 s3, s12, s3
	v_mul_f32_e32 v92, 0x3c800000, v92
	s_waitcnt lgkmcnt(0)
	v_add_f32_e32 v93, v93, v94
	v_lshl_add_u32 v94, v143, 5, s3
	ds_write_b64 v94, v[92:93] offset:1024
.LBB0_505:
	s_or_b64 exec, exec, s[8:9]
	v_max_f32_e64 v92, |v119|, |v119|
	v_max_f32_e64 v93, |v118|, |v118|
	v_max_f32_e32 v92, v93, v92
	v_max_f32_e64 v93, |v99|, |v99|
	s_waitcnt lgkmcnt(0)
	v_max_f32_e64 v94, |v98|, |v98|
	v_max_f32_e32 v93, v94, v93
	v_max3_f32 v92, |v116|, |v117|, v92
	v_max3_f32 v93, |v96|, |v97|, v93
	v_max3_f32 v92, v92, 0, v93
	v_max_f32_e64 v93, |v91|, |v91|
	v_max_f32_e64 v94, |v90|, |v90|
	v_max_f32_e32 v93, v94, v93
	v_max_f32_e64 v94, |v79|, |v79|
	v_max_f32_e64 v95, |v78|, |v78|
	v_max_f32_e32 v94, v95, v94
	v_max3_f32 v93, |v88|, |v89|, v93
	v_max3_f32 v94, |v76|, |v77|, v94
	v_max3_f32 v92, v92, v93, v94
	v_mov_b32_e32 v93, v92
	v_mov_b32_e32 v210, v92
	s_nop 1
	v_permlane16_swap_b32_e32 v93, v210
	v_cndmask_b32_e64 v93, v210, v93, s[100:101]
	s_waitcnt lgkmcnt(0)
	v_max_f32_e32 v93, v93, v93
	v_max_f32_e32 v92, v92, v93
	v_mov_b32_e32 v93, v92
	v_mov_b32_e32 v210, v92
	s_nop 1
	v_permlane32_swap_b32_e32 v93, v210
	v_cndmask_b32_e64 v93, v210, v93, s[98:99]
	s_and_saveexec_b64 s[8:9], vcc
	s_cbranch_execz .LBB0_507
	s_lshl_b32 s3, s22, 10
	s_waitcnt lgkmcnt(0)
	v_max_f32_e32 v93, v93, v93
	v_max_f32_e32 v92, v92, v92
	s_add_i32 s3, s11, s3
	v_max_f32_e32 v92, v92, v93
	v_lshl_add_u32 v93, v143, 4, s3
	ds_write_b32 v93, v92 offset:16896
.LBB0_507:
	s_or_b64 exec, exec, s[8:9]
	v_pk_add_f32 v[110:111], v[110:111], 0 op_sel_hi:[1,0]
	v_pk_add_f32 v[108:109], v[108:109], 0 op_sel_hi:[1,0]
	v_pk_add_f32 v[104:105], v[114:115], 0 op_sel_hi:[1,0]
	v_pk_add_f32 v[106:107], v[112:113], 0 op_sel_hi:[1,0]
	s_waitcnt lgkmcnt(0)
	v_pk_add_f32 v[92:93], v[102:103], 0 op_sel_hi:[1,0]
	v_pk_add_f32 v[94:95], v[100:101], 0 op_sel_hi:[1,0]
	v_pk_add_f32 v[66:67], v[66:67], 0 op_sel_hi:[1,0]
	v_pk_add_f32 v[64:65], v[64:65], 0 op_sel_hi:[1,0]
	v_pk_mov_b32 v[100:101], v[108:109], v[110:111] op_sel:[1,0]
	v_mov_b32_e32 v102, v108
	v_mov_b32_e32 v103, v111
	v_pk_add_f32 v[100:101], v[100:101], v[102:103]
	v_pk_mov_b32 v[102:103], v[106:107], v[104:105] op_sel:[1,0]
	v_mov_b32_e32 v112, v106
	v_mov_b32_e32 v113, v105
	v_pk_add_f32 v[102:103], v[102:103], v[112:113]
	v_pk_add_f32 v[100:101], v[100:101], v[100:101] op_sel_hi:[0,1]
	v_pk_add_f32 v[102:103], v[102:103], v[102:103] op_sel_hi:[0,1]
	v_add_f32_e32 v113, v94, v95
	v_add_f32_e32 v115, v92, v93
	v_mov_b32_e32 v112, v64
	v_mov_b32_e32 v114, v65
	v_mov_b32_e32 v100, v66
	v_mov_b32_e32 v102, v67
	v_pk_add_f32 v[112:113], v[112:113], v[114:115]
	v_pk_add_f32 v[100:101], v[100:101], v[102:103]
	s_nop 0
	v_pk_add_f32 v[100:101], v[112:113], v[100:101]
	s_nop 0
	v_add_f32_e32 v100, v100, v101
	v_mov_b32_e32 v101, v100
	v_mov_b32_e32 v210, v100
	s_nop 1
	v_permlane16_swap_b32_e32 v101, v210
	v_cndmask_b32_e64 v101, v210, v101, s[100:101]
	s_waitcnt lgkmcnt(0)
	v_add_f32_e32 v100, v100, v101
	v_mov_b32_e32 v101, v100
	v_mov_b32_e32 v210, v100
	s_nop 1
	v_permlane32_swap_b32_e32 v101, v210
	v_cndmask_b32_e64 v101, v210, v101, s[98:99]
	s_waitcnt lgkmcnt(0)
	v_add_f32_e32 v100, v100, v101
	v_fmamk_f32 v102, v100, 0xbc800000, v111
	v_fmamk_f32 v112, v100, 0xbc800000, v109
	v_fmamk_f32 v101, v100, 0xbc800000, v110
	v_fmamk_f32 v103, v100, 0xbc800000, v108
	v_mul_f32_e32 v112, v112, v112
	v_mul_f32_e32 v102, v102, v102
	v_fmac_f32_e32 v112, v103, v103
	v_fmac_f32_e32 v102, v101, v101
	v_fmamk_f32 v103, v100, 0xbc800000, v105
	v_fmamk_f32 v113, v100, 0xbc800000, v107
	v_add_f32_e32 v101, v112, v102
	v_fmamk_f32 v102, v100, 0xbc800000, v104
	v_fmamk_f32 v112, v100, 0xbc800000, v106
	v_mul_f32_e32 v113, v113, v113
	v_mul_f32_e32 v103, v103, v103
	v_fmac_f32_e32 v113, v112, v112
	v_fmac_f32_e32 v103, v102, v102
	v_add_f32_e32 v102, v113, v103
	v_fmamk_f32 v103, v100, 0xbc800000, v93
	v_fmamk_f32 v113, v100, 0xbc800000, v95
	v_add_f32_e32 v101, v101, v102
	v_fmamk_f32 v102, v100, 0xbc800000, v92
	v_fmamk_f32 v112, v100, 0xbc800000, v94
	v_mul_f32_e32 v113, v113, v113
	v_mul_f32_e32 v103, v103, v103
	v_fmac_f32_e32 v113, v112, v112
	v_fmac_f32_e32 v103, v102, v102
	v_add_f32_e32 v102, v113, v103
	v_fmamk_f32 v103, v100, 0xbc800000, v67
	v_fmamk_f32 v113, v100, 0xbc800000, v65
	v_add_f32_e32 v101, v102, v101
	v_fmamk_f32 v102, v100, 0xbc800000, v66
	v_fmamk_f32 v112, v100, 0xbc800000, v64
	v_mul_f32_e32 v113, v113, v113
	v_mul_f32_e32 v103, v103, v103
	v_fmac_f32_e32 v113, v112, v112
	v_fmac_f32_e32 v103, v102, v102
	v_add_f32_e32 v102, v113, v103
	v_add_f32_e32 v101, v102, v101
	v_mov_b32_e32 v102, v101
	v_mov_b32_e32 v210, v101
	s_nop 1
	v_permlane16_swap_b32_e32 v102, v210
	v_cndmask_b32_e64 v102, v210, v102, s[100:101]
	s_waitcnt lgkmcnt(0)
	v_add_f32_e32 v101, v101, v102
	v_mov_b32_e32 v102, v101
	v_mov_b32_e32 v210, v101
	s_nop 1
	v_permlane32_swap_b32_e32 v102, v210
	v_cndmask_b32_e64 v102, v210, v102, s[98:99]
	s_and_saveexec_b64 s[8:9], vcc
	s_cbranch_execz .LBB0_509
	s_lshl_b32 s3, s22, 11
	s_add_i32 s3, s12, s3
	v_mul_f32_e32 v100, 0x3c800000, v100
	s_waitcnt lgkmcnt(0)
	v_add_f32_e32 v101, v101, v102
	v_lshl_add_u32 v102, v143, 5, s3
	ds_write_b64 v102, v[100:101] offset:1536
.LBB0_509:
	s_or_b64 exec, exec, s[8:9]
	v_max_f32_e64 v100, |v111|, |v111|
	v_max_f32_e64 v101, |v110|, |v110|
	v_max_f32_e32 v100, v101, v100
	v_max_f32_e64 v101, |v105|, |v105|
	s_waitcnt lgkmcnt(0)
	v_max_f32_e64 v102, |v104|, |v104|
	v_max_f32_e32 v101, v102, v101
	v_max3_f32 v100, |v108|, |v109|, v100
	v_max3_f32 v101, |v106|, |v107|, v101
	v_max3_f32 v100, v100, 0, v101
	v_max_f32_e64 v101, |v93|, |v93|
	v_max_f32_e64 v102, |v92|, |v92|
	v_max_f32_e32 v101, v102, v101
	v_max_f32_e64 v102, |v67|, |v67|
	v_max_f32_e64 v103, |v66|, |v66|
	v_max_f32_e32 v102, v103, v102
	v_max3_f32 v101, |v94|, |v95|, v101
	v_max3_f32 v102, |v64|, |v65|, v102
	v_max3_f32 v100, v100, v101, v102
	v_mov_b32_e32 v101, v100
	v_mov_b32_e32 v210, v100
	s_nop 1
	v_permlane16_swap_b32_e32 v101, v210
	v_cndmask_b32_e64 v101, v210, v101, s[100:101]
	s_waitcnt lgkmcnt(0)
	v_max_f32_e32 v101, v101, v101
	v_max_f32_e32 v100, v100, v101
	v_mov_b32_e32 v101, v100
	v_mov_b32_e32 v210, v100
	s_nop 1
	v_permlane32_swap_b32_e32 v101, v210
	v_cndmask_b32_e64 v101, v210, v101, s[98:99]
	s_and_saveexec_b64 s[8:9], vcc
	s_cbranch_execz .LBB0_511
	s_lshl_b32 s3, s22, 10
	s_waitcnt lgkmcnt(0)
	v_max_f32_e32 v101, v101, v101
	v_max_f32_e32 v100, v100, v100
	s_add_i32 s3, s11, s3
	v_max_f32_e32 v100, v100, v101
	v_lshl_add_u32 v101, v143, 4, s3
	ds_write_b32 v101, v100 offset:17152
.LBB0_511:
	s_or_b64 exec, exec, s[8:9]
	v_pk_add_f32 v[62:63], v[62:63], 0 op_sel_hi:[1,0]
	v_pk_add_f32 v[60:61], v[60:61], 0 op_sel_hi:[1,0]
	v_pk_add_f32 v[58:59], v[58:59], 0 op_sel_hi:[1,0]
	v_pk_add_f32 v[56:57], v[56:57], 0 op_sel_hi:[1,0]
	v_pk_add_f32 v[54:55], v[54:55], 0 op_sel_hi:[1,0]
	v_pk_add_f32 v[52:53], v[52:53], 0 op_sel_hi:[1,0]
	v_pk_add_f32 v[50:51], v[50:51], 0 op_sel_hi:[1,0]
	v_pk_add_f32 v[48:49], v[48:49], 0 op_sel_hi:[1,0]
	s_waitcnt lgkmcnt(0)
	v_pk_mov_b32 v[100:101], v[60:61], v[62:63] op_sel:[1,0]
	v_mov_b32_e32 v102, v60
	v_mov_b32_e32 v103, v63
	v_pk_add_f32 v[100:101], v[100:101], v[102:103]
	v_pk_mov_b32 v[102:103], v[56:57], v[58:59] op_sel:[1,0]
	v_mov_b32_e32 v112, v56
	v_mov_b32_e32 v113, v59
	v_pk_add_f32 v[102:103], v[102:103], v[112:113]
	v_pk_add_f32 v[100:101], v[100:101], v[100:101] op_sel_hi:[0,1]
	v_pk_add_f32 v[102:103], v[102:103], v[102:103] op_sel_hi:[0,1]
	v_add_f32_e32 v113, v52, v53
	v_add_f32_e32 v115, v54, v55
	v_mov_b32_e32 v112, v48
	v_mov_b32_e32 v114, v49
	v_mov_b32_e32 v100, v50
	v_mov_b32_e32 v102, v51
	v_pk_add_f32 v[112:113], v[112:113], v[114:115]
	v_pk_add_f32 v[100:101], v[100:101], v[102:103]
	s_nop 0
	v_pk_add_f32 v[100:101], v[112:113], v[100:101]
	s_nop 0
	v_add_f32_e32 v100, v100, v101
	v_mov_b32_e32 v101, v100
	v_mov_b32_e32 v210, v100
	s_nop 1
	v_permlane16_swap_b32_e32 v101, v210
	v_cndmask_b32_e64 v101, v210, v101, s[100:101]
	s_waitcnt lgkmcnt(0)
	v_add_f32_e32 v100, v100, v101
	v_mov_b32_e32 v101, v100
	v_mov_b32_e32 v210, v100
	s_nop 1
	v_permlane32_swap_b32_e32 v101, v210
	v_cndmask_b32_e64 v101, v210, v101, s[98:99]
	s_waitcnt lgkmcnt(0)
	v_add_f32_e32 v100, v100, v101
	v_fmamk_f32 v102, v100, 0xbc800000, v63
	v_fmamk_f32 v112, v100, 0xbc800000, v61
	v_fmamk_f32 v101, v100, 0xbc800000, v62
	v_fmamk_f32 v103, v100, 0xbc800000, v60
	v_mul_f32_e32 v112, v112, v112
	v_mul_f32_e32 v102, v102, v102
	v_fmac_f32_e32 v112, v103, v103
	v_fmac_f32_e32 v102, v101, v101
	v_fmamk_f32 v103, v100, 0xbc800000, v59
	v_fmamk_f32 v113, v100, 0xbc800000, v57
	v_add_f32_e32 v101, v112, v102
	v_fmamk_f32 v102, v100, 0xbc800000, v58
	v_fmamk_f32 v112, v100, 0xbc800000, v56
	v_mul_f32_e32 v113, v113, v113
	v_mul_f32_e32 v103, v103, v103
	v_fmac_f32_e32 v113, v112, v112
	v_fmac_f32_e32 v103, v102, v102
	v_add_f32_e32 v102, v113, v103
	v_fmamk_f32 v103, v100, 0xbc800000, v55
	v_fmamk_f32 v113, v100, 0xbc800000, v53
	v_add_f32_e32 v101, v101, v102
	v_fmamk_f32 v102, v100, 0xbc800000, v54
	v_fmamk_f32 v112, v100, 0xbc800000, v52
	v_mul_f32_e32 v113, v113, v113
	v_mul_f32_e32 v103, v103, v103
	v_fmac_f32_e32 v113, v112, v112
	v_fmac_f32_e32 v103, v102, v102
	v_add_f32_e32 v102, v113, v103
	v_fmamk_f32 v103, v100, 0xbc800000, v51
	v_fmamk_f32 v113, v100, 0xbc800000, v49
	v_add_f32_e32 v101, v102, v101
	v_fmamk_f32 v102, v100, 0xbc800000, v50
	v_fmamk_f32 v112, v100, 0xbc800000, v48
	v_mul_f32_e32 v113, v113, v113
	v_mul_f32_e32 v103, v103, v103
	v_fmac_f32_e32 v113, v112, v112
	v_fmac_f32_e32 v103, v102, v102
	v_add_f32_e32 v102, v113, v103
	v_add_f32_e32 v101, v102, v101
	v_mov_b32_e32 v102, v101
	v_mov_b32_e32 v210, v101
	s_nop 1
	v_permlane16_swap_b32_e32 v102, v210
	v_cndmask_b32_e64 v102, v210, v102, s[100:101]
	s_waitcnt lgkmcnt(0)
	v_add_f32_e32 v101, v101, v102
	v_mov_b32_e32 v102, v101
	v_mov_b32_e32 v210, v101
	s_nop 1
	v_permlane32_swap_b32_e32 v102, v210
	v_cndmask_b32_e64 v102, v210, v102, s[98:99]
	s_and_saveexec_b64 s[8:9], vcc
	s_cbranch_execz .LBB0_513
	s_lshl_b32 s3, s22, 11
	s_add_i32 s3, s12, s3
	v_mul_f32_e32 v100, 0x3c800000, v100
	s_waitcnt lgkmcnt(0)
	v_add_f32_e32 v101, v101, v102
	v_lshl_add_u32 v102, v143, 5, s3
	ds_write_b64 v102, v[100:101] offset:4096
.LBB0_513:
	s_or_b64 exec, exec, s[8:9]
	v_max_f32_e64 v100, |v63|, |v63|
	v_max_f32_e64 v101, |v62|, |v62|
	v_max_f32_e32 v100, v101, v100
	v_max_f32_e64 v101, |v59|, |v59|
	s_waitcnt lgkmcnt(0)
	v_max_f32_e64 v102, |v58|, |v58|
	v_max_f32_e32 v101, v102, v101
	v_max3_f32 v100, |v60|, |v61|, v100
	v_max3_f32 v101, |v56|, |v57|, v101
	v_max3_f32 v100, v100, 0, v101
	v_max_f32_e64 v101, |v55|, |v55|
	v_max_f32_e64 v102, |v54|, |v54|
	v_max_f32_e32 v101, v102, v101
	v_max_f32_e64 v102, |v51|, |v51|
	v_max_f32_e64 v103, |v50|, |v50|
	v_max_f32_e32 v102, v103, v102
	v_max3_f32 v101, |v52|, |v53|, v101
	v_max3_f32 v102, |v48|, |v49|, v102
	v_max3_f32 v100, v100, v101, v102
	v_mov_b32_e32 v101, v100
	v_mov_b32_e32 v210, v100
	s_nop 1
	v_permlane16_swap_b32_e32 v101, v210
	v_cndmask_b32_e64 v101, v210, v101, s[100:101]
	s_waitcnt lgkmcnt(0)
	v_max_f32_e32 v101, v101, v101
	v_max_f32_e32 v100, v100, v101
	v_mov_b32_e32 v101, v100
	v_mov_b32_e32 v210, v100
	s_nop 1
	v_permlane32_swap_b32_e32 v101, v210
	v_cndmask_b32_e64 v101, v210, v101, s[98:99]
	s_and_saveexec_b64 s[8:9], vcc
	s_cbranch_execz .LBB0_515
	s_lshl_b32 s3, s22, 10
	s_waitcnt lgkmcnt(0)
	v_max_f32_e32 v101, v101, v101
	v_max_f32_e32 v100, v100, v100
	s_add_i32 s3, s11, s3
	v_max_f32_e32 v100, v100, v101
	v_lshl_add_u32 v101, v143, 4, s3
	ds_write_b32 v101, v100 offset:18432
.LBB0_515:
	s_or_b64 exec, exec, s[8:9]
	v_pk_add_f32 v[140:141], v[46:47], 0 op_sel_hi:[1,0]
	v_pk_add_f32 v[130:131], v[44:45], 0 op_sel_hi:[1,0]
	v_pk_add_f32 v[42:43], v[42:43], 0 op_sel_hi:[1,0]
	v_pk_add_f32 v[40:41], v[40:41], 0 op_sel_hi:[1,0]
	v_pk_add_f32 v[38:39], v[38:39], 0 op_sel_hi:[1,0]
	v_pk_add_f32 v[36:37], v[36:37], 0 op_sel_hi:[1,0]
	v_pk_add_f32 v[34:35], v[34:35], 0 op_sel_hi:[1,0]
	v_pk_add_f32 v[32:33], v[32:33], 0 op_sel_hi:[1,0]
	v_pk_mov_b32 v[44:45], v[130:131], v[140:141] op_sel:[1,0]
	v_mov_b32_e32 v46, v130
	v_mov_b32_e32 v47, v141
	v_pk_add_f32 v[44:45], v[44:45], v[46:47]
	v_pk_mov_b32 v[46:47], v[40:41], v[42:43] op_sel:[1,0]
	v_mov_b32_e32 v100, v40
	s_waitcnt lgkmcnt(0)
	v_mov_b32_e32 v101, v43
	v_pk_add_f32 v[46:47], v[46:47], v[100:101]
	v_pk_add_f32 v[44:45], v[44:45], v[44:45] op_sel_hi:[0,1]
	v_pk_add_f32 v[46:47], v[46:47], v[46:47] op_sel_hi:[0,1]
	v_add_f32_e32 v101, v36, v37
	v_add_f32_e32 v103, v38, v39
	v_mov_b32_e32 v100, v32
	v_mov_b32_e32 v102, v33
	v_mov_b32_e32 v44, v34
	v_mov_b32_e32 v46, v35
	v_pk_add_f32 v[100:101], v[100:101], v[102:103]
	v_pk_add_f32 v[44:45], v[44:45], v[46:47]
	s_nop 0
	v_pk_add_f32 v[44:45], v[100:101], v[44:45]
	s_nop 0
	v_add_f32_e32 v44, v44, v45
	v_mov_b32_e32 v45, v44
	v_mov_b32_e32 v210, v44
	s_nop 1
	v_permlane16_swap_b32_e32 v45, v210
	v_cndmask_b32_e64 v45, v210, v45, s[100:101]
	s_waitcnt lgkmcnt(0)
	v_add_f32_e32 v44, v44, v45
	v_mov_b32_e32 v45, v44
	v_mov_b32_e32 v210, v44
	s_nop 1
	v_permlane32_swap_b32_e32 v45, v210
	v_cndmask_b32_e64 v45, v210, v45, s[98:99]
	s_waitcnt lgkmcnt(0)
	v_add_f32_e32 v44, v44, v45
	v_fmamk_f32 v46, v44, 0xbc800000, v141
	v_fmamk_f32 v100, v44, 0xbc800000, v131
	v_fmamk_f32 v45, v44, 0xbc800000, v140
	v_fmamk_f32 v47, v44, 0xbc800000, v130
	v_mul_f32_e32 v100, v100, v100
	v_mul_f32_e32 v46, v46, v46
	v_fmac_f32_e32 v100, v47, v47
	v_fmac_f32_e32 v46, v45, v45
	v_fmamk_f32 v47, v44, 0xbc800000, v43
	v_fmamk_f32 v101, v44, 0xbc800000, v41
	v_add_f32_e32 v45, v100, v46
	v_fmamk_f32 v46, v44, 0xbc800000, v42
	v_fmamk_f32 v100, v44, 0xbc800000, v40
	v_mul_f32_e32 v101, v101, v101
	v_mul_f32_e32 v47, v47, v47
	v_fmac_f32_e32 v101, v100, v100
	v_fmac_f32_e32 v47, v46, v46
	v_add_f32_e32 v46, v101, v47
	v_fmamk_f32 v47, v44, 0xbc800000, v39
	v_fmamk_f32 v101, v44, 0xbc800000, v37
	v_add_f32_e32 v45, v45, v46
	v_fmamk_f32 v46, v44, 0xbc800000, v38
	v_fmamk_f32 v100, v44, 0xbc800000, v36
	v_mul_f32_e32 v101, v101, v101
	v_mul_f32_e32 v47, v47, v47
	v_fmac_f32_e32 v101, v100, v100
	v_fmac_f32_e32 v47, v46, v46
	v_add_f32_e32 v46, v101, v47
	v_fmamk_f32 v47, v44, 0xbc800000, v35
	v_fmamk_f32 v101, v44, 0xbc800000, v33
	v_add_f32_e32 v45, v46, v45
	v_fmamk_f32 v46, v44, 0xbc800000, v34
	v_fmamk_f32 v100, v44, 0xbc800000, v32
	v_mul_f32_e32 v101, v101, v101
	v_mul_f32_e32 v47, v47, v47
	v_fmac_f32_e32 v101, v100, v100
	v_fmac_f32_e32 v47, v46, v46
	v_add_f32_e32 v46, v101, v47
	v_add_f32_e32 v45, v46, v45
	v_mov_b32_e32 v46, v45
	v_mov_b32_e32 v210, v45
	s_nop 1
	v_permlane16_swap_b32_e32 v46, v210
	v_cndmask_b32_e64 v46, v210, v46, s[100:101]
	s_waitcnt lgkmcnt(0)
	v_add_f32_e32 v45, v45, v46
	v_mov_b32_e32 v46, v45
	v_mov_b32_e32 v210, v45
	s_nop 1
	v_permlane32_swap_b32_e32 v46, v210
	v_cndmask_b32_e64 v46, v210, v46, s[98:99]
	s_and_saveexec_b64 s[8:9], vcc
	s_cbranch_execz .LBB0_517
	s_lshl_b32 s3, s22, 11
	s_add_i32 s3, s12, s3
	v_mul_f32_e32 v44, 0x3c800000, v44
	s_waitcnt lgkmcnt(0)
	v_add_f32_e32 v45, v45, v46
	v_lshl_add_u32 v46, v143, 5, s3
	ds_write_b64 v46, v[44:45] offset:4608
.LBB0_517:
	s_or_b64 exec, exec, s[8:9]
	v_max_f32_e64 v44, |v141|, |v141|
	v_max_f32_e64 v45, |v140|, |v140|
	v_max_f32_e32 v44, v45, v44
	v_max_f32_e64 v45, |v43|, |v43|
	s_waitcnt lgkmcnt(0)
	v_max_f32_e64 v46, |v42|, |v42|
	v_max_f32_e32 v45, v46, v45
	v_max3_f32 v44, |v130|, |v131|, v44
	v_max3_f32 v45, |v40|, |v41|, v45
	v_max3_f32 v44, v44, 0, v45
	v_max_f32_e64 v45, |v39|, |v39|
	v_max_f32_e64 v46, |v38|, |v38|
	v_max_f32_e32 v45, v46, v45
	v_max_f32_e64 v46, |v35|, |v35|
	v_max_f32_e64 v47, |v34|, |v34|
	v_max_f32_e32 v46, v47, v46
	v_max3_f32 v45, |v36|, |v37|, v45
	v_max3_f32 v46, |v32|, |v33|, v46
	v_max3_f32 v44, v44, v45, v46
	v_mov_b32_e32 v45, v44
	v_mov_b32_e32 v210, v44
	s_nop 1
	v_permlane16_swap_b32_e32 v45, v210
	v_cndmask_b32_e64 v45, v210, v45, s[100:101]
	s_waitcnt lgkmcnt(0)
	v_max_f32_e32 v45, v45, v45
	v_max_f32_e32 v44, v44, v45
	v_mov_b32_e32 v45, v44
	v_mov_b32_e32 v210, v44
	s_nop 1
	v_permlane32_swap_b32_e32 v45, v210
	v_cndmask_b32_e64 v45, v210, v45, s[98:99]
	s_and_saveexec_b64 s[8:9], vcc
	s_cbranch_execz .LBB0_519
	s_lshl_b32 s3, s22, 10
	s_waitcnt lgkmcnt(0)
	v_max_f32_e32 v45, v45, v45
	v_max_f32_e32 v44, v44, v44
	s_add_i32 s3, s11, s3
	v_max_f32_e32 v44, v44, v45
	v_lshl_add_u32 v45, v143, 4, s3
	ds_write_b32 v45, v44 offset:18688
.LBB0_519:
	s_or_b64 exec, exec, s[8:9]
	s_waitcnt lgkmcnt(0)
	v_pk_add_f32 v[44:45], v[30:31], 0 op_sel_hi:[1,0]
	v_pk_add_f32 v[46:47], v[28:29], 0 op_sel_hi:[1,0]
	v_pk_add_f32 v[26:27], v[26:27], 0 op_sel_hi:[1,0]
	v_pk_add_f32 v[24:25], v[24:25], 0 op_sel_hi:[1,0]
	v_pk_add_f32 v[22:23], v[22:23], 0 op_sel_hi:[1,0]
	v_pk_add_f32 v[20:21], v[20:21], 0 op_sel_hi:[1,0]
	v_pk_add_f32 v[18:19], v[18:19], 0 op_sel_hi:[1,0]
	v_pk_add_f32 v[16:17], v[16:17], 0 op_sel_hi:[1,0]
	v_pk_mov_b32 v[28:29], v[46:47], v[44:45] op_sel:[1,0]
	v_mov_b32_e32 v30, v46
	v_mov_b32_e32 v31, v45
	v_pk_add_f32 v[28:29], v[28:29], v[30:31]
	v_pk_mov_b32 v[30:31], v[24:25], v[26:27] op_sel:[1,0]
	v_mov_b32_e32 v100, v24
	v_mov_b32_e32 v101, v27
	v_pk_add_f32 v[30:31], v[30:31], v[100:101]
	v_pk_add_f32 v[28:29], v[28:29], v[28:29] op_sel_hi:[0,1]
	v_pk_add_f32 v[30:31], v[30:31], v[30:31] op_sel_hi:[0,1]
	v_add_f32_e32 v101, v20, v21
	v_add_f32_e32 v103, v22, v23
	v_mov_b32_e32 v100, v16
	v_mov_b32_e32 v102, v17
	v_mov_b32_e32 v28, v18
	v_mov_b32_e32 v30, v19
	v_pk_add_f32 v[100:101], v[100:101], v[102:103]
	v_pk_add_f32 v[28:29], v[28:29], v[30:31]
	s_nop 0
	v_pk_add_f32 v[28:29], v[100:101], v[28:29]
	s_nop 0
	v_add_f32_e32 v28, v28, v29
	v_mov_b32_e32 v29, v28
	v_mov_b32_e32 v210, v28
	s_nop 1
	v_permlane16_swap_b32_e32 v29, v210
	v_cndmask_b32_e64 v29, v210, v29, s[100:101]
	s_waitcnt lgkmcnt(0)
	v_add_f32_e32 v28, v28, v29
	v_mov_b32_e32 v29, v28
	v_mov_b32_e32 v210, v28
	s_nop 1
	v_permlane32_swap_b32_e32 v29, v210
	v_cndmask_b32_e64 v29, v210, v29, s[98:99]
	s_waitcnt lgkmcnt(0)
	v_add_f32_e32 v28, v28, v29
	v_fmamk_f32 v30, v28, 0xbc800000, v45
	v_fmamk_f32 v100, v28, 0xbc800000, v47
	v_fmamk_f32 v29, v28, 0xbc800000, v44
	v_fmamk_f32 v31, v28, 0xbc800000, v46
	v_mul_f32_e32 v100, v100, v100
	v_mul_f32_e32 v30, v30, v30
	v_fmac_f32_e32 v100, v31, v31
	v_fmac_f32_e32 v30, v29, v29
	v_fmamk_f32 v31, v28, 0xbc800000, v27
	v_fmamk_f32 v101, v28, 0xbc800000, v25
	v_add_f32_e32 v29, v100, v30
	v_fmamk_f32 v30, v28, 0xbc800000, v26
	v_fmamk_f32 v100, v28, 0xbc800000, v24
	v_mul_f32_e32 v101, v101, v101
	v_mul_f32_e32 v31, v31, v31
	v_fmac_f32_e32 v101, v100, v100
	v_fmac_f32_e32 v31, v30, v30
	v_add_f32_e32 v30, v101, v31
	v_fmamk_f32 v31, v28, 0xbc800000, v23
	v_fmamk_f32 v101, v28, 0xbc800000, v21
	v_add_f32_e32 v29, v29, v30
	v_fmamk_f32 v30, v28, 0xbc800000, v22
	v_fmamk_f32 v100, v28, 0xbc800000, v20
	v_mul_f32_e32 v101, v101, v101
	v_mul_f32_e32 v31, v31, v31
	v_fmac_f32_e32 v101, v100, v100
	v_fmac_f32_e32 v31, v30, v30
	v_add_f32_e32 v30, v101, v31
	v_fmamk_f32 v31, v28, 0xbc800000, v19
	v_fmamk_f32 v101, v28, 0xbc800000, v17
	v_add_f32_e32 v29, v30, v29
	v_fmamk_f32 v30, v28, 0xbc800000, v18
	v_fmamk_f32 v100, v28, 0xbc800000, v16
	v_mul_f32_e32 v101, v101, v101
	v_mul_f32_e32 v31, v31, v31
	v_fmac_f32_e32 v101, v100, v100
	v_fmac_f32_e32 v31, v30, v30
	v_add_f32_e32 v30, v101, v31
	v_add_f32_e32 v29, v30, v29
	v_mov_b32_e32 v30, v29
	v_mov_b32_e32 v210, v29
	s_nop 1
	v_permlane16_swap_b32_e32 v30, v210
	v_cndmask_b32_e64 v30, v210, v30, s[100:101]
	s_waitcnt lgkmcnt(0)
	v_add_f32_e32 v29, v29, v30
	v_mov_b32_e32 v30, v29
	v_mov_b32_e32 v210, v29
	s_nop 1
	v_permlane32_swap_b32_e32 v30, v210
	v_cndmask_b32_e64 v30, v210, v30, s[98:99]
	s_and_saveexec_b64 s[8:9], vcc
	s_cbranch_execz .LBB0_521
	s_lshl_b32 s3, s22, 11
	s_add_i32 s3, s12, s3
	v_mul_f32_e32 v28, 0x3c800000, v28
	s_waitcnt lgkmcnt(0)
	v_add_f32_e32 v29, v29, v30
	v_lshl_add_u32 v30, v143, 5, s3
	ds_write_b64 v30, v[28:29] offset:5120
.LBB0_521:
	s_or_b64 exec, exec, s[8:9]
	v_max_f32_e64 v28, |v45|, |v45|
	v_max_f32_e64 v29, |v44|, |v44|
	v_max_f32_e32 v28, v29, v28
	v_max_f32_e64 v29, |v27|, |v27|
	s_waitcnt lgkmcnt(0)
	v_max_f32_e64 v30, |v26|, |v26|
	v_max_f32_e32 v29, v30, v29
	v_max3_f32 v28, |v46|, |v47|, v28
	v_max3_f32 v29, |v24|, |v25|, v29
	v_max3_f32 v28, v28, 0, v29
	v_max_f32_e64 v29, |v23|, |v23|
	v_max_f32_e64 v30, |v22|, |v22|
	v_max_f32_e32 v29, v30, v29
	v_max_f32_e64 v30, |v19|, |v19|
	v_max_f32_e64 v31, |v18|, |v18|
	v_max_f32_e32 v30, v31, v30
	v_max3_f32 v29, |v20|, |v21|, v29
	v_max3_f32 v30, |v16|, |v17|, v30
	v_max3_f32 v28, v28, v29, v30
	v_mov_b32_e32 v29, v28
	v_mov_b32_e32 v210, v28
	s_nop 1
	v_permlane16_swap_b32_e32 v29, v210
	v_cndmask_b32_e64 v29, v210, v29, s[100:101]
	s_waitcnt lgkmcnt(0)
	v_max_f32_e32 v29, v29, v29
	v_max_f32_e32 v28, v28, v29
	v_mov_b32_e32 v29, v28
	v_mov_b32_e32 v210, v28
	s_nop 1
	v_permlane32_swap_b32_e32 v29, v210
	v_cndmask_b32_e64 v29, v210, v29, s[98:99]
	s_and_saveexec_b64 s[8:9], vcc
	s_cbranch_execz .LBB0_523
	s_lshl_b32 s3, s22, 10
	s_waitcnt lgkmcnt(0)
	v_max_f32_e32 v29, v29, v29
	v_max_f32_e32 v28, v28, v28
	s_add_i32 s3, s11, s3
	v_max_f32_e32 v28, v28, v29
	v_lshl_add_u32 v29, v143, 4, s3
	ds_write_b32 v29, v28 offset:18944
.LBB0_523:
	s_or_b64 exec, exec, s[8:9]
	v_pk_add_f32 v[144:145], v[14:15], 0 op_sel_hi:[1,0]
	v_pk_add_f32 v[146:147], v[12:13], 0 op_sel_hi:[1,0]
	s_waitcnt lgkmcnt(0)
	v_pk_add_f32 v[28:29], v[10:11], 0 op_sel_hi:[1,0]
	v_pk_add_f32 v[30:31], v[8:9], 0 op_sel_hi:[1,0]
	v_pk_add_f32 v[12:13], v[6:7], 0 op_sel_hi:[1,0]
	v_pk_add_f32 v[14:15], v[4:5], 0 op_sel_hi:[1,0]
	v_pk_add_f32 v[8:9], v[2:3], 0 op_sel_hi:[1,0]
	v_pk_add_f32 v[10:11], v[0:1], 0 op_sel_hi:[1,0]
	v_pk_mov_b32 v[0:1], v[146:147], v[144:145] op_sel:[1,0]
	v_mov_b32_e32 v2, v146
	v_mov_b32_e32 v3, v145
	v_pk_add_f32 v[0:1], v[0:1], v[2:3]
	v_pk_mov_b32 v[2:3], v[30:31], v[28:29] op_sel:[1,0]
	v_mov_b32_e32 v4, v30
	v_mov_b32_e32 v5, v29
	v_pk_add_f32 v[2:3], v[2:3], v[4:5]
	v_pk_add_f32 v[0:1], v[0:1], v[0:1] op_sel_hi:[0,1]
	v_pk_add_f32 v[2:3], v[2:3], v[2:3] op_sel_hi:[0,1]
	v_add_f32_e32 v5, v14, v15
	v_add_f32_e32 v7, v12, v13
	v_mov_b32_e32 v4, v10
	v_mov_b32_e32 v6, v11
	v_mov_b32_e32 v0, v8
	v_mov_b32_e32 v2, v9
	v_pk_add_f32 v[4:5], v[4:5], v[6:7]
	v_pk_add_f32 v[0:1], v[0:1], v[2:3]
	s_nop 0
	v_pk_add_f32 v[0:1], v[4:5], v[0:1]
	s_nop 0
	v_add_f32_e32 v0, v0, v1
	v_mov_b32_e32 v1, v0
	v_mov_b32_e32 v210, v0
	s_nop 1
	v_permlane16_swap_b32_e32 v1, v210
	v_cndmask_b32_e64 v1, v210, v1, s[100:101]
	s_waitcnt lgkmcnt(0)
	v_add_f32_e32 v0, v0, v1
	v_mov_b32_e32 v1, v0
	v_mov_b32_e32 v210, v0
	s_nop 1
	v_permlane32_swap_b32_e32 v1, v210
	v_cndmask_b32_e64 v1, v210, v1, s[98:99]
	s_waitcnt lgkmcnt(0)
	v_add_f32_e32 v0, v0, v1
	v_fmamk_f32 v2, v0, 0xbc800000, v145
	v_fmamk_f32 v4, v0, 0xbc800000, v147
	v_fmamk_f32 v1, v0, 0xbc800000, v144
	v_fmamk_f32 v3, v0, 0xbc800000, v146
	v_mul_f32_e32 v4, v4, v4
	v_mul_f32_e32 v2, v2, v2
	v_fmac_f32_e32 v4, v3, v3
	v_fmac_f32_e32 v2, v1, v1
	v_fmamk_f32 v3, v0, 0xbc800000, v29
	v_fmamk_f32 v5, v0, 0xbc800000, v31
	v_add_f32_e32 v1, v4, v2
	v_fmamk_f32 v2, v0, 0xbc800000, v28
	v_fmamk_f32 v4, v0, 0xbc800000, v30
	v_mul_f32_e32 v5, v5, v5
	v_mul_f32_e32 v3, v3, v3
	v_fmac_f32_e32 v5, v4, v4
	v_fmac_f32_e32 v3, v2, v2
	v_add_f32_e32 v2, v5, v3
	v_fmamk_f32 v3, v0, 0xbc800000, v13
	v_fmamk_f32 v5, v0, 0xbc800000, v15
	v_add_f32_e32 v1, v1, v2
	v_fmamk_f32 v2, v0, 0xbc800000, v12
	v_fmamk_f32 v4, v0, 0xbc800000, v14
	v_mul_f32_e32 v5, v5, v5
	v_mul_f32_e32 v3, v3, v3
	v_fmac_f32_e32 v5, v4, v4
	v_fmac_f32_e32 v3, v2, v2
	v_add_f32_e32 v2, v5, v3
	v_fmamk_f32 v3, v0, 0xbc800000, v9
	v_fmamk_f32 v5, v0, 0xbc800000, v11
	v_add_f32_e32 v1, v2, v1
	v_fmamk_f32 v2, v0, 0xbc800000, v8
	v_fmamk_f32 v4, v0, 0xbc800000, v10
	v_mul_f32_e32 v5, v5, v5
	v_mul_f32_e32 v3, v3, v3
	v_fmac_f32_e32 v5, v4, v4
	v_fmac_f32_e32 v3, v2, v2
	v_add_f32_e32 v2, v5, v3
	v_add_f32_e32 v1, v2, v1
	v_mov_b32_e32 v2, v1
	v_mov_b32_e32 v210, v1
	s_nop 1
	v_permlane16_swap_b32_e32 v2, v210
	v_cndmask_b32_e64 v2, v210, v2, s[100:101]
	s_waitcnt lgkmcnt(0)
	v_add_f32_e32 v1, v1, v2
	v_mov_b32_e32 v2, v1
	v_mov_b32_e32 v210, v1
	s_nop 1
	v_permlane32_swap_b32_e32 v2, v210
	v_cndmask_b32_e64 v2, v210, v2, s[98:99]
	s_and_saveexec_b64 s[8:9], vcc
	s_cbranch_execz .LBB0_525
	s_lshl_b32 s3, s22, 11
	s_add_i32 s12, s12, s3
	v_mul_f32_e32 v0, 0x3c800000, v0
	s_waitcnt lgkmcnt(0)
	v_add_f32_e32 v1, v1, v2
	v_lshl_add_u32 v2, v143, 5, s12
	ds_write_b64 v2, v[0:1] offset:5632
.LBB0_525:
	s_or_b64 exec, exec, s[8:9]
	v_max_f32_e64 v0, |v145|, |v145|
	v_max_f32_e64 v1, |v144|, |v144|
	v_max_f32_e32 v0, v1, v0
	v_max_f32_e64 v1, |v29|, |v29|
	s_waitcnt lgkmcnt(0)
	v_max_f32_e64 v2, |v28|, |v28|
	v_max_f32_e32 v1, v2, v1
	v_max3_f32 v0, |v146|, |v147|, v0
	v_max3_f32 v1, |v30|, |v31|, v1
	v_max3_f32 v0, v0, 0, v1
	v_max_f32_e64 v1, |v13|, |v13|
	v_max_f32_e64 v2, |v12|, |v12|
	v_max_f32_e32 v1, v2, v1
	v_max_f32_e64 v2, |v9|, |v9|
	v_max_f32_e64 v3, |v8|, |v8|
	v_max_f32_e32 v2, v3, v2
	v_max3_f32 v1, |v14|, |v15|, v1
	v_max3_f32 v2, |v10|, |v11|, v2
	v_max3_f32 v0, v0, v1, v2
	v_mov_b32_e32 v1, v0
	v_mov_b32_e32 v210, v0
	s_nop 1
	v_permlane16_swap_b32_e32 v1, v210
	v_cndmask_b32_e64 v1, v210, v1, s[100:101]
	s_waitcnt lgkmcnt(0)
	v_max_f32_e32 v1, v1, v1
	v_max_f32_e32 v0, v0, v1
	v_mov_b32_e32 v1, v0
	v_mov_b32_e32 v210, v0
	s_nop 1
	v_permlane32_swap_b32_e32 v1, v210
	v_cndmask_b32_e64 v1, v210, v1, s[98:99]
	s_and_saveexec_b64 s[8:9], vcc
	s_cbranch_execz .LBB0_527
	s_lshl_b32 s3, s22, 10
	s_waitcnt lgkmcnt(0)
	v_max_f32_e32 v1, v1, v1
	v_max_f32_e32 v0, v0, v0
	s_add_i32 s11, s11, s3
	v_max_f32_e32 v0, v0, v1
	v_lshl_add_u32 v1, v143, 4, s11
	ds_write_b32 v1, v0 offset:19200

.LBB0_851:
	v_lshl_add_u64 v[20:21], v[160:161], 2, s[18:19]
	global_load_dwordx4 v[196:199], v[20:21], off
	global_load_dwordx4 v[200:203], v[20:21], off offset:64
	global_load_dwordx4 v[204:207], v[20:21], off offset:512
	global_load_dwordx4 v[208:211], v[20:21], off offset:576
	s_mov_b32 s8, 0x3a800000
	s_lshl_b32 s10, s26, 5
	v_readlane_b32 s3, v254, 17
	s_add_i32 s3, s3, s10
	v_cmp_gt_u32_e32 vcc, 16, v178
	s_waitcnt vmcnt(0)
	v_pk_mul_f32 v[174:175], v[198:199], s[8:9] op_sel_hi:[1,0]
	v_pk_mul_f32 v[176:177], v[196:197], s[8:9] op_sel_hi:[1,0]
	v_pk_mul_f32 v[170:171], v[202:203], s[8:9] op_sel_hi:[1,0]
	v_pk_mul_f32 v[172:173], v[200:201], s[8:9] op_sel_hi:[1,0]
	v_pk_mul_f32 v[166:167], v[206:207], s[8:9] op_sel_hi:[1,0]
	v_pk_mul_f32 v[168:169], v[204:205], s[8:9] op_sel_hi:[1,0]
	v_mbcnt_lo_u32_b32 v185, -1, 0
	v_mbcnt_hi_u32_b32 v185, -1, v185
	v_pk_mul_f32 v[164:165], v[208:209], s[8:9] op_sel_hi:[1,0]
	v_pk_mul_f32 v[162:163], v[210:211], s[8:9] op_sel_hi:[1,0]
	v_ashrrev_i32_e32 v30, 5, v185
	v_add_u32_e32 v16, s3, v30
	v_and_b32_e32 v31, 31, v185
	v_ashrrev_i32_e32 v17, 31, v16
	v_readlane_b32 s8, v253, 47
	v_lshlrev_b64 v[16:17], 11, v[16:17]
	v_readlane_b32 s9, v253, 48
	s_lshl_b32 s3, s26, 14
	v_bitop3_b32 v18, v30, v31, 15 bitop3:0x6c
	v_lshl_add_u64 v[16:17], s[8:9], 0, v[16:17]
	s_add_i32 s3, s3, 0
	v_lshlrev_b32_e32 v230, 4, v18
	v_lshl_add_u64 v[18:19], v[16:17], 0, v[230:231]
	s_mov_b32 m0, s3
	s_mov_b64 s[8:9], 0x1000
	global_load_lds_dwordx4 v[18:19], off
	v_lshl_add_u64 v[18:19], v[16:17], 0, s[8:9]
	v_add_u32_e32 v16, 2, v30
	v_bitop3_b32 v16, v16, v31, 15 bitop3:0x6c
	v_lshlrev_b32_e32 v16, 4, v16
	v_mov_b32_e32 v17, v231
	s_add_i32 m0, s3, 0x400
	v_lshl_add_u64 v[20:21], v[18:19], 0, v[16:17]
	global_load_lds_dwordx4 v[20:21], off
	v_lshl_add_u64 v[20:21], v[18:19], 0, s[8:9]
	v_add_u32_e32 v18, 4, v30
	v_bitop3_b32 v18, v18, v31, 15 bitop3:0x6c
	v_lshlrev_b32_e32 v18, 4, v18
	v_mov_b32_e32 v19, v231
	s_add_i32 m0, s3, 0x800
	v_lshl_add_u64 v[22:23], v[20:21], 0, v[18:19]
	global_load_lds_dwordx4 v[22:23], off
	v_lshl_add_u64 v[22:23], v[20:21], 0, s[8:9]
	v_add_u32_e32 v20, 6, v30
	v_bitop3_b32 v20, v20, v31, 15 bitop3:0x6c
	v_lshlrev_b32_e32 v20, 4, v20
	v_mov_b32_e32 v21, v231
	s_add_i32 m0, s3, 0xc00
	v_lshl_add_u64 v[24:25], v[22:23], 0, v[20:21]
	global_load_lds_dwordx4 v[24:25], off
	v_lshl_add_u64 v[24:25], v[22:23], 0, s[8:9]
	v_xor_b32_e32 v22, 0x80, v230
	v_mov_b32_e32 v23, v231
	s_add_i32 m0, s3, 0x1000
	v_lshl_add_u64 v[26:27], v[24:25], 0, v[22:23]
	global_load_lds_dwordx4 v[26:27], off
	v_lshl_add_u64 v[26:27], v[24:25], 0, s[8:9]
	v_add_u32_e32 v24, 10, v30
	v_bitop3_b32 v24, v24, v31, 15 bitop3:0x6c
	v_lshlrev_b32_e32 v24, 4, v24
	v_mov_b32_e32 v25, v231
	s_add_i32 m0, s3, 0x1400
	v_lshl_add_u64 v[28:29], v[26:27], 0, v[24:25]
	global_load_lds_dwordx4 v[28:29], off
	v_add_u32_e32 v28, 12, v30
	v_bitop3_b32 v28, v28, v31, 15 bitop3:0x6c
	v_lshl_add_u64 v[26:27], v[26:27], 0, s[8:9]
	v_lshlrev_b32_e32 v28, 4, v28
	v_mov_b32_e32 v29, v231
	s_add_i32 m0, s3, 0x1800
	v_lshl_add_u64 v[180:181], v[26:27], 0, v[28:29]
	global_load_lds_dwordx4 v[180:181], off
	v_add_u32_e32 v180, 14, v30
	v_lshl_add_u64 v[26:27], v[26:27], 0, s[8:9]
	v_bitop3_b32 v31, v180, v31, 15 bitop3:0x6c
	v_lshlrev_b32_e32 v180, 4, v31
	v_mov_b32_e32 v181, v231
	v_lshl_add_u64 v[182:183], v[26:27], 0, v[180:181]
	s_add_i32 m0, s3, 0x1c00
	v_lshl_add_u64 v[26:27], v[26:27], 0, s[8:9]
	global_load_lds_dwordx4 v[182:183], off
	s_add_i32 m0, s3, 0x2000
	v_lshl_add_u64 v[182:183], v[26:27], 0, v[230:231]
	v_lshl_add_u64 v[26:27], v[26:27], 0, s[8:9]
	global_load_lds_dwordx4 v[182:183], off
	s_add_i32 m0, s3, 0x2400
	v_lshl_add_u64 v[16:17], v[26:27], 0, v[16:17]
	global_load_lds_dwordx4 v[16:17], off
	v_lshl_add_u64 v[16:17], v[26:27], 0, s[8:9]
	s_add_i32 m0, s3, 0x2800
	v_lshl_add_u64 v[18:19], v[16:17], 0, v[18:19]
	v_lshl_add_u64 v[16:17], v[16:17], 0, s[8:9]
	global_load_lds_dwordx4 v[18:19], off
	s_add_i32 m0, s3, 0x2c00
	v_lshl_add_u64 v[18:19], v[16:17], 0, v[20:21]
	v_lshl_add_u64 v[16:17], v[16:17], 0, s[8:9]
	global_load_lds_dwordx4 v[18:19], off
	s_add_i32 m0, s3, 0x3000
	v_lshl_add_u64 v[18:19], v[16:17], 0, v[22:23]
	v_lshl_add_u64 v[16:17], v[16:17], 0, s[8:9]
	global_load_lds_dwordx4 v[18:19], off
	s_add_i32 m0, s3, 0x3400
	v_lshl_add_u64 v[18:19], v[16:17], 0, v[24:25]
	v_lshl_add_u64 v[16:17], v[16:17], 0, s[8:9]
	global_load_lds_dwordx4 v[18:19], off
	s_add_i32 m0, s3, 0x3800
	v_lshl_add_u64 v[18:19], v[16:17], 0, v[28:29]
	v_lshl_add_u64 v[16:17], v[16:17], 0, s[8:9]
	global_load_lds_dwordx4 v[18:19], off
	s_add_i32 m0, s3, 0x3c00
	v_lshl_add_u64 v[18:19], v[16:17], 0, v[180:181]
	v_lshl_add_u64 v[16:17], v[16:17], 0, s[8:9]
	global_load_lds_dwordx4 v[18:19], off
	v_lshrrev_b32_e32 v18, 1, v185
	v_lshlrev_b32_e32 v17, 9, v185
	v_and_b32_e32 v17, 0x200, v17
	v_and_b32_e32 v18, 8, v18
	v_lshl_add_u32 v187, s25, 2, v30
	v_and_b32_e32 v16, 15, v185
	v_add3_u32 v183, 0, v17, v18
	v_add_u32_e32 v17, 16, v187
	v_bitop3_b32 v17, v17, v185, 15 bitop3:0x78
	s_lshl_b32 s3, s24, 15
	v_lshlrev_b32_e32 v16, 9, v16
	v_lshlrev_b32_e32 v180, 4, v17
	v_or_b32_e32 v184, s3, v16
	v_mov_b32_e32 v17, s3
	s_movk_i32 s3, 0x9c00
	v_bitop3_b32 v16, v16, s3, v17 bitop3:0xc8
	v_add_u32_e32 v181, v183, v16
	v_bitop3_b32 v16, v187, v185, 15 bitop3:0x78
	v_lshlrev_b32_e32 v182, 4, v16
	s_waitcnt vmcnt(0)
	s_barrier
	v_add_u32_e32 v186, v181, v182
	ds_read_b64 v[16:17], v186
	s_mov_b32 s8, 0x3fd744fd
	s_lshl_b32 s3, s25, 3
	s_add_i32 s11, s3, 0
	s_waitcnt lgkmcnt(0)
	v_cvt_f32_f16_e32 v18, v16
	v_cvt_f32_f16_sdwa v19, v16 dst_sel:DWORD dst_unused:UNUSED_PAD src0_sel:WORD_1
	v_cvt_f32_f16_e32 v16, v17
	v_cvt_f32_f16_sdwa v17, v17 dst_sel:DWORD dst_unused:UNUSED_PAD src0_sel:WORD_1
	v_pk_mul_f32 v[20:21], v[18:19], s[8:9] op_sel_hi:[1,0]
	v_pk_mul_f32 v[16:17], v[16:17], s[8:9] op_sel_hi:[1,0]
	s_nop 0
	v_pk_fma_f32 v[18:19], v[158:159], v[174:175], v[16:17]
	v_pk_fma_f32 v[16:17], v[156:157], v[176:177], v[20:21]
	v_add_u32_e32 v20, 2, v187
	v_bitop3_b32 v20, v20, v185, 15 bitop3:0x78
	v_lshlrev_b32_e32 v156, 4, v20
	v_add_u32_e32 v157, v181, v156
	ds_read_b64 v[20:21], v157
	s_waitcnt lgkmcnt(0)
	v_cvt_f32_f16_e32 v22, v20
	v_cvt_f32_f16_sdwa v23, v20 dst_sel:DWORD dst_unused:UNUSED_PAD src0_sel:WORD_1
	v_cvt_f32_f16_e32 v20, v21
	v_cvt_f32_f16_sdwa v21, v21 dst_sel:DWORD dst_unused:UNUSED_PAD src0_sel:WORD_1
	v_pk_mul_f32 v[24:25], v[22:23], s[8:9] op_sel_hi:[1,0]
	v_pk_mul_f32 v[20:21], v[20:21], s[8:9] op_sel_hi:[1,0]
	s_nop 0
	v_pk_fma_f32 v[22:23], v[154:155], v[170:171], v[20:21]
	v_pk_fma_f32 v[20:21], v[152:153], v[172:173], v[24:25]
	v_add_u32_e32 v152, v181, v180
	ds_read_b64 v[24:25], v152
	s_waitcnt lgkmcnt(0)
	v_cvt_f32_f16_e32 v26, v24
	v_cvt_f32_f16_sdwa v27, v24 dst_sel:DWORD dst_unused:UNUSED_PAD src0_sel:WORD_1
	v_cvt_f32_f16_e32 v24, v25
	v_cvt_f32_f16_sdwa v25, v25 dst_sel:DWORD dst_unused:UNUSED_PAD src0_sel:WORD_1
	v_pk_mul_f32 v[26:27], v[26:27], s[8:9] op_sel_hi:[1,0]
	s_nop 0
	v_pk_fma_f32 v[28:29], v[148:149], v[168:169], v[26:27]
	v_pk_mul_f32 v[24:25], v[24:25], s[8:9] op_sel_hi:[1,0]
	s_nop 0
	v_pk_fma_f32 v[30:31], v[150:151], v[166:167], v[24:25]
	v_add_u32_e32 v24, 18, v187
	v_bitop3_b32 v24, v24, v185, 15 bitop3:0x78
	v_lshlrev_b32_e32 v148, 4, v24
	v_add_u32_e32 v149, v181, v148
	ds_read_b64 v[24:25], v149
	s_waitcnt lgkmcnt(0)
	v_cvt_f32_f16_e32 v26, v24
	v_cvt_f32_f16_sdwa v27, v24 dst_sel:DWORD dst_unused:UNUSED_PAD src0_sel:WORD_1
	v_cvt_f32_f16_e32 v24, v25
	v_cvt_f32_f16_sdwa v25, v25 dst_sel:DWORD dst_unused:UNUSED_PAD src0_sel:WORD_1
	v_pk_mul_f32 v[26:27], v[26:27], s[8:9] op_sel_hi:[1,0]
	s_nop 0
	v_pk_fma_f32 v[144:145], v[144:145], v[164:165], v[26:27]
	v_pk_mul_f32 v[24:25], v[24:25], s[8:9] op_sel_hi:[1,0]
	s_nop 0
	v_pk_fma_f32 v[146:147], v[146:147], v[162:163], v[24:25]
	s_nop 0
	ds_read_b64 v[24:25], v186 offset:8192
	v_pk_add_f32 v[154:155], v[4:5], v[16:17]
	v_pk_add_f32 v[16:17], v[10:11], v[146:147]
	s_waitcnt lgkmcnt(0)
	v_cvt_f32_f16_e32 v26, v24
	v_cvt_f32_f16_sdwa v27, v24 dst_sel:DWORD dst_unused:UNUSED_PAD src0_sel:WORD_1
	v_cvt_f32_f16_e32 v24, v25
	v_cvt_f32_f16_sdwa v25, v25 dst_sel:DWORD dst_unused:UNUSED_PAD src0_sel:WORD_1
	v_pk_mul_f32 v[150:151], v[26:27], s[8:9] op_sel_hi:[1,0]
	v_pk_mul_f32 v[24:25], v[24:25], s[8:9] op_sel_hi:[1,0]
	s_nop 0
	v_pk_fma_f32 v[26:27], v[142:143], v[174:175], v[24:25]
	v_pk_fma_f32 v[24:25], v[140:141], v[176:177], v[150:151]
	ds_read_b64 v[140:141], v157 offset:8192
	v_pk_add_f32 v[150:151], v[0:1], v[20:21]
	v_lshlrev_b32_e32 v20, 2, v178
	s_waitcnt lgkmcnt(0)
	v_cvt_f32_f16_e32 v142, v140
	v_cvt_f32_f16_sdwa v143, v140 dst_sel:DWORD dst_unused:UNUSED_PAD src0_sel:WORD_1
	v_cvt_f32_f16_e32 v140, v141
	v_cvt_f32_f16_sdwa v141, v141 dst_sel:DWORD dst_unused:UNUSED_PAD src0_sel:WORD_1
	v_pk_mul_f32 v[142:143], v[142:143], s[8:9] op_sel_hi:[1,0]
	s_nop 0
	v_pk_fma_f32 v[136:137], v[136:137], v[172:173], v[142:143]
	v_pk_mul_f32 v[140:141], v[140:141], s[8:9] op_sel_hi:[1,0]
	s_nop 0
	v_pk_fma_f32 v[138:139], v[138:139], v[170:171], v[140:141]
	ds_read_b64 v[140:141], v152 offset:8192
	s_waitcnt lgkmcnt(0)
	v_cvt_f32_f16_e32 v142, v140
	v_cvt_f32_f16_sdwa v143, v140 dst_sel:DWORD dst_unused:UNUSED_PAD src0_sel:WORD_1
	v_cvt_f32_f16_e32 v140, v141
	v_cvt_f32_f16_sdwa v141, v141 dst_sel:DWORD dst_unused:UNUSED_PAD src0_sel:WORD_1
	v_pk_mul_f32 v[142:143], v[142:143], s[8:9] op_sel_hi:[1,0]
	s_nop 0
	v_pk_fma_f32 v[132:133], v[132:133], v[168:169], v[142:143]
	v_pk_mul_f32 v[140:141], v[140:141], s[8:9] op_sel_hi:[1,0]
	s_nop 0
	v_pk_fma_f32 v[134:135], v[134:135], v[166:167], v[140:141]
	ds_read_b64 v[140:141], v149 offset:8192
	s_waitcnt lgkmcnt(0)
	v_cvt_f32_f16_e32 v142, v140
	v_cvt_f32_f16_sdwa v143, v140 dst_sel:DWORD dst_unused:UNUSED_PAD src0_sel:WORD_1
	v_cvt_f32_f16_e32 v140, v141
	v_cvt_f32_f16_sdwa v141, v141 dst_sel:DWORD dst_unused:UNUSED_PAD src0_sel:WORD_1
	v_pk_mul_f32 v[142:143], v[142:143], s[8:9] op_sel_hi:[1,0]
	s_nop 0
	v_pk_fma_f32 v[128:129], v[128:129], v[164:165], v[142:143]
	v_pk_mul_f32 v[140:141], v[140:141], s[8:9] op_sel_hi:[1,0]
	s_nop 0
	v_pk_fma_f32 v[130:131], v[130:131], v[162:163], v[140:141]
	s_nop 0
	ds_read_b64 v[140:141], v186 offset:16384
	s_waitcnt lgkmcnt(0)
	v_cvt_f32_f16_e32 v142, v140
	v_cvt_f32_f16_sdwa v143, v140 dst_sel:DWORD dst_unused:UNUSED_PAD src0_sel:WORD_1
	v_cvt_f32_f16_e32 v140, v141
	v_cvt_f32_f16_sdwa v141, v141 dst_sel:DWORD dst_unused:UNUSED_PAD src0_sel:WORD_1
	v_pk_mul_f32 v[142:143], v[142:143], s[8:9] op_sel_hi:[1,0]
	s_nop 0
	v_pk_fma_f32 v[124:125], v[124:125], v[176:177], v[142:143]
	v_pk_mul_f32 v[140:141], v[140:141], s[8:9] op_sel_hi:[1,0]
	s_nop 0
	v_pk_fma_f32 v[126:127], v[126:127], v[174:175], v[140:141]
	ds_read_b64 v[140:141], v157 offset:16384
	s_waitcnt lgkmcnt(0)
	v_cvt_f32_f16_e32 v142, v140
	v_cvt_f32_f16_sdwa v143, v140 dst_sel:DWORD dst_unused:UNUSED_PAD src0_sel:WORD_1
	v_cvt_f32_f16_e32 v140, v141
	v_cvt_f32_f16_sdwa v141, v141 dst_sel:DWORD dst_unused:UNUSED_PAD src0_sel:WORD_1
	v_pk_mul_f32 v[142:143], v[142:143], s[8:9] op_sel_hi:[1,0]
	s_nop 0
	v_pk_fma_f32 v[120:121], v[120:121], v[172:173], v[142:143]
	v_pk_mul_f32 v[140:141], v[140:141], s[8:9] op_sel_hi:[1,0]
	s_nop 0
	v_pk_fma_f32 v[122:123], v[122:123], v[170:171], v[140:141]
	ds_read_b64 v[140:141], v152 offset:16384
	s_waitcnt lgkmcnt(0)
	v_cvt_f32_f16_e32 v142, v140
	v_cvt_f32_f16_sdwa v143, v140 dst_sel:DWORD dst_unused:UNUSED_PAD src0_sel:WORD_1
	v_cvt_f32_f16_e32 v140, v141
	v_cvt_f32_f16_sdwa v141, v141 dst_sel:DWORD dst_unused:UNUSED_PAD src0_sel:WORD_1
	v_pk_mul_f32 v[142:143], v[142:143], s[8:9] op_sel_hi:[1,0]
	s_nop 0
	v_pk_fma_f32 v[116:117], v[116:117], v[168:169], v[142:143]
	v_pk_mul_f32 v[140:141], v[140:141], s[8:9] op_sel_hi:[1,0]
	s_nop 0
	v_pk_fma_f32 v[118:119], v[118:119], v[166:167], v[140:141]
	ds_read_b64 v[140:141], v149 offset:16384
	s_waitcnt lgkmcnt(0)
	v_cvt_f32_f16_e32 v142, v140
	v_cvt_f32_f16_sdwa v143, v140 dst_sel:DWORD dst_unused:UNUSED_PAD src0_sel:WORD_1
	v_cvt_f32_f16_e32 v140, v141
	v_cvt_f32_f16_sdwa v141, v141 dst_sel:DWORD dst_unused:UNUSED_PAD src0_sel:WORD_1
	v_pk_mul_f32 v[142:143], v[142:143], s[8:9] op_sel_hi:[1,0]
	s_nop 0
	v_pk_fma_f32 v[112:113], v[112:113], v[164:165], v[142:143]
	v_pk_mul_f32 v[140:141], v[140:141], s[8:9] op_sel_hi:[1,0]
	s_nop 0
	v_pk_fma_f32 v[114:115], v[114:115], v[162:163], v[140:141]
	s_nop 0
	ds_read_b64 v[140:141], v186 offset:24576
	s_waitcnt lgkmcnt(0)
	v_cvt_f32_f16_e32 v142, v140
	v_cvt_f32_f16_sdwa v143, v140 dst_sel:DWORD dst_unused:UNUSED_PAD src0_sel:WORD_1
	v_cvt_f32_f16_e32 v140, v141
	v_cvt_f32_f16_sdwa v141, v141 dst_sel:DWORD dst_unused:UNUSED_PAD src0_sel:WORD_1
	v_pk_mul_f32 v[142:143], v[142:143], s[8:9] op_sel_hi:[1,0]
	s_nop 0
	v_pk_fma_f32 v[108:109], v[108:109], v[176:177], v[142:143]
	v_pk_mul_f32 v[140:141], v[140:141], s[8:9] op_sel_hi:[1,0]
	s_nop 0
	v_pk_fma_f32 v[110:111], v[110:111], v[174:175], v[140:141]
	ds_read_b64 v[140:141], v157 offset:24576
	s_waitcnt lgkmcnt(0)
	v_cvt_f32_f16_e32 v142, v140
	v_cvt_f32_f16_sdwa v143, v140 dst_sel:DWORD dst_unused:UNUSED_PAD src0_sel:WORD_1
	v_cvt_f32_f16_e32 v140, v141
	v_cvt_f32_f16_sdwa v141, v141 dst_sel:DWORD dst_unused:UNUSED_PAD src0_sel:WORD_1
	v_pk_mul_f32 v[142:143], v[142:143], s[8:9] op_sel_hi:[1,0]
	s_nop 0
	v_pk_fma_f32 v[104:105], v[104:105], v[172:173], v[142:143]
	v_pk_mul_f32 v[140:141], v[140:141], s[8:9] op_sel_hi:[1,0]
	s_nop 0
	v_pk_fma_f32 v[106:107], v[106:107], v[170:171], v[140:141]
	ds_read_b64 v[140:141], v152 offset:24576
	v_pk_add_f32 v[152:153], v[6:7], v[18:19]
	v_pk_add_f32 v[18:19], v[8:9], v[144:145]
	s_waitcnt lgkmcnt(0)
	v_cvt_f32_f16_e32 v142, v140
	v_cvt_f32_f16_sdwa v143, v140 dst_sel:DWORD dst_unused:UNUSED_PAD src0_sel:WORD_1
	v_cvt_f32_f16_e32 v140, v141
	v_cvt_f32_f16_sdwa v141, v141 dst_sel:DWORD dst_unused:UNUSED_PAD src0_sel:WORD_1
	v_pk_mul_f32 v[142:143], v[142:143], s[8:9] op_sel_hi:[1,0]
	s_nop 0
	v_pk_fma_f32 v[100:101], v[100:101], v[168:169], v[142:143]
	v_pk_mul_f32 v[140:141], v[140:141], s[8:9] op_sel_hi:[1,0]
	s_nop 0
	v_pk_fma_f32 v[102:103], v[102:103], v[166:167], v[140:141]
	ds_read_b64 v[140:141], v149 offset:24576
	v_add_u32_e32 v149, 0x10000, v181
	s_waitcnt lgkmcnt(0)
	v_cvt_f32_f16_e32 v142, v140
	v_cvt_f32_f16_sdwa v143, v140 dst_sel:DWORD dst_unused:UNUSED_PAD src0_sel:WORD_1
	v_cvt_f32_f16_e32 v140, v141
	v_cvt_f32_f16_sdwa v141, v141 dst_sel:DWORD dst_unused:UNUSED_PAD src0_sel:WORD_1
	v_pk_mul_f32 v[142:143], v[142:143], s[8:9] op_sel_hi:[1,0]
	s_nop 0
	v_pk_fma_f32 v[96:97], v[96:97], v[164:165], v[142:143]
	v_pk_mul_f32 v[140:141], v[140:141], s[8:9] op_sel_hi:[1,0]
	s_nop 0
	v_pk_fma_f32 v[98:99], v[98:99], v[162:163], v[140:141]
	v_add_u32_e32 v140, v149, v182
	ds_read_b64 v[140:141], v140
	s_waitcnt lgkmcnt(0)
	v_cvt_f32_f16_e32 v142, v140
	v_cvt_f32_f16_sdwa v143, v140 dst_sel:DWORD dst_unused:UNUSED_PAD src0_sel:WORD_1
	v_cvt_f32_f16_e32 v140, v141
	v_cvt_f32_f16_sdwa v141, v141 dst_sel:DWORD dst_unused:UNUSED_PAD src0_sel:WORD_1
	v_pk_mul_f32 v[142:143], v[142:143], s[8:9] op_sel_hi:[1,0]
	s_nop 0
	v_pk_fma_f32 v[92:93], v[92:93], v[176:177], v[142:143]
	v_pk_mul_f32 v[140:141], v[140:141], s[8:9] op_sel_hi:[1,0]
	s_nop 0
	v_pk_fma_f32 v[94:95], v[94:95], v[174:175], v[140:141]
	v_add_u32_e32 v140, v149, v156
	ds_read_b64 v[140:141], v140
	s_waitcnt lgkmcnt(0)
	v_cvt_f32_f16_e32 v142, v140
	v_cvt_f32_f16_sdwa v143, v140 dst_sel:DWORD dst_unused:UNUSED_PAD src0_sel:WORD_1
	v_cvt_f32_f16_e32 v140, v141
	v_cvt_f32_f16_sdwa v141, v141 dst_sel:DWORD dst_unused:UNUSED_PAD src0_sel:WORD_1
	v_pk_mul_f32 v[142:143], v[142:143], s[8:9] op_sel_hi:[1,0]
	s_nop 0
	v_pk_fma_f32 v[88:89], v[88:89], v[172:173], v[142:143]
	v_pk_mul_f32 v[140:141], v[140:141], s[8:9] op_sel_hi:[1,0]
	s_nop 0
	v_pk_fma_f32 v[90:91], v[90:91], v[170:171], v[140:141]
	v_add_u32_e32 v140, v149, v180
	ds_read_b64 v[140:141], v140
	s_waitcnt lgkmcnt(0)
	v_cvt_f32_f16_e32 v142, v140
	v_cvt_f32_f16_sdwa v143, v140 dst_sel:DWORD dst_unused:UNUSED_PAD src0_sel:WORD_1
	v_cvt_f32_f16_e32 v140, v141
	v_cvt_f32_f16_sdwa v141, v141 dst_sel:DWORD dst_unused:UNUSED_PAD src0_sel:WORD_1
	v_pk_mul_f32 v[142:143], v[142:143], s[8:9] op_sel_hi:[1,0]
	s_nop 0
	v_pk_fma_f32 v[84:85], v[84:85], v[168:169], v[142:143]
	v_pk_mul_f32 v[140:141], v[140:141], s[8:9] op_sel_hi:[1,0]
	s_nop 0
	v_pk_fma_f32 v[86:87], v[86:87], v[166:167], v[140:141]
	v_add_u32_e32 v140, v149, v148
	ds_read_b64 v[140:141], v140
	s_waitcnt lgkmcnt(0)
	v_cvt_f32_f16_e32 v142, v140
	v_cvt_f32_f16_sdwa v143, v140 dst_sel:DWORD dst_unused:UNUSED_PAD src0_sel:WORD_1
	v_cvt_f32_f16_e32 v140, v141
	v_cvt_f32_f16_sdwa v141, v141 dst_sel:DWORD dst_unused:UNUSED_PAD src0_sel:WORD_1
	v_pk_mul_f32 v[142:143], v[142:143], s[8:9] op_sel_hi:[1,0]
	s_nop 0
	v_pk_fma_f32 v[80:81], v[80:81], v[164:165], v[142:143]
	v_pk_mul_f32 v[140:141], v[140:141], s[8:9] op_sel_hi:[1,0]
	s_nop 0
	v_pk_fma_f32 v[82:83], v[82:83], v[162:163], v[140:141]
	v_add_u32_e32 v140, 0x12000, v184
	v_and_b32_e32 v140, 0xffffbc00, v140
	v_add_u32_e32 v149, v183, v140
	v_add_u32_e32 v140, v149, v182
	ds_read_b64 v[140:141], v140
	s_waitcnt lgkmcnt(0)
	v_cvt_f32_f16_e32 v142, v140
	v_cvt_f32_f16_sdwa v143, v140 dst_sel:DWORD dst_unused:UNUSED_PAD src0_sel:WORD_1
	v_cvt_f32_f16_e32 v140, v141
	v_cvt_f32_f16_sdwa v141, v141 dst_sel:DWORD dst_unused:UNUSED_PAD src0_sel:WORD_1
	v_pk_mul_f32 v[142:143], v[142:143], s[8:9] op_sel_hi:[1,0]
	s_nop 0
	v_pk_fma_f32 v[76:77], v[76:77], v[176:177], v[142:143]
	v_pk_mul_f32 v[140:141], v[140:141], s[8:9] op_sel_hi:[1,0]
	s_nop 0
	v_pk_fma_f32 v[78:79], v[78:79], v[174:175], v[140:141]
	v_add_u32_e32 v140, v149, v156
	ds_read_b64 v[140:141], v140
	s_waitcnt lgkmcnt(0)
	v_cvt_f32_f16_e32 v142, v140
	v_cvt_f32_f16_sdwa v143, v140 dst_sel:DWORD dst_unused:UNUSED_PAD src0_sel:WORD_1
	v_cvt_f32_f16_e32 v140, v141
	v_cvt_f32_f16_sdwa v141, v141 dst_sel:DWORD dst_unused:UNUSED_PAD src0_sel:WORD_1
	v_pk_mul_f32 v[142:143], v[142:143], s[8:9] op_sel_hi:[1,0]
	s_nop 0
	v_pk_fma_f32 v[72:73], v[72:73], v[172:173], v[142:143]
	v_pk_mul_f32 v[140:141], v[140:141], s[8:9] op_sel_hi:[1,0]
	s_nop 0
	v_pk_fma_f32 v[74:75], v[74:75], v[170:171], v[140:141]
	v_add_u32_e32 v140, v149, v180
	ds_read_b64 v[140:141], v140
	s_waitcnt lgkmcnt(0)
	v_cvt_f32_f16_e32 v142, v140
	v_cvt_f32_f16_sdwa v143, v140 dst_sel:DWORD dst_unused:UNUSED_PAD src0_sel:WORD_1
	v_cvt_f32_f16_e32 v140, v141
	v_cvt_f32_f16_sdwa v141, v141 dst_sel:DWORD dst_unused:UNUSED_PAD src0_sel:WORD_1
	v_pk_mul_f32 v[142:143], v[142:143], s[8:9] op_sel_hi:[1,0]
	s_nop 0
	v_pk_fma_f32 v[68:69], v[68:69], v[168:169], v[142:143]
	v_pk_mul_f32 v[140:141], v[140:141], s[8:9] op_sel_hi:[1,0]
	s_nop 0
	v_pk_fma_f32 v[70:71], v[70:71], v[166:167], v[140:141]
	v_add_u32_e32 v140, v149, v148
	ds_read_b64 v[140:141], v140
	v_add_u32_e32 v149, 0x14000, v181
	s_waitcnt lgkmcnt(0)
	v_cvt_f32_f16_e32 v142, v140
	v_cvt_f32_f16_sdwa v143, v140 dst_sel:DWORD dst_unused:UNUSED_PAD src0_sel:WORD_1
	v_cvt_f32_f16_e32 v140, v141
	v_cvt_f32_f16_sdwa v141, v141 dst_sel:DWORD dst_unused:UNUSED_PAD src0_sel:WORD_1
	v_pk_mul_f32 v[142:143], v[142:143], s[8:9] op_sel_hi:[1,0]
	s_nop 0
	v_pk_fma_f32 v[64:65], v[64:65], v[164:165], v[142:143]
	v_pk_mul_f32 v[140:141], v[140:141], s[8:9] op_sel_hi:[1,0]
	s_nop 0
	v_pk_fma_f32 v[66:67], v[66:67], v[162:163], v[140:141]
	v_add_u32_e32 v140, v149, v182
	ds_read_b64 v[140:141], v140
	s_waitcnt lgkmcnt(0)
	v_cvt_f32_f16_e32 v142, v140
	v_cvt_f32_f16_sdwa v143, v140 dst_sel:DWORD dst_unused:UNUSED_PAD src0_sel:WORD_1
	v_cvt_f32_f16_e32 v140, v141
	v_cvt_f32_f16_sdwa v141, v141 dst_sel:DWORD dst_unused:UNUSED_PAD src0_sel:WORD_1
	v_pk_mul_f32 v[142:143], v[142:143], s[8:9] op_sel_hi:[1,0]
	s_nop 0
	v_pk_fma_f32 v[60:61], v[60:61], v[176:177], v[142:143]
	v_pk_mul_f32 v[140:141], v[140:141], s[8:9] op_sel_hi:[1,0]
	s_nop 0
	v_pk_fma_f32 v[62:63], v[62:63], v[174:175], v[140:141]
	v_add_u32_e32 v140, v149, v156
	ds_read_b64 v[140:141], v140
	s_waitcnt lgkmcnt(0)
	v_cvt_f32_f16_e32 v142, v140
	v_cvt_f32_f16_sdwa v143, v140 dst_sel:DWORD dst_unused:UNUSED_PAD src0_sel:WORD_1
	v_cvt_f32_f16_e32 v140, v141
	v_cvt_f32_f16_sdwa v141, v141 dst_sel:DWORD dst_unused:UNUSED_PAD src0_sel:WORD_1
	v_pk_mul_f32 v[142:143], v[142:143], s[8:9] op_sel_hi:[1,0]
	s_nop 0
	v_pk_fma_f32 v[56:57], v[56:57], v[172:173], v[142:143]
	v_pk_mul_f32 v[140:141], v[140:141], s[8:9] op_sel_hi:[1,0]
	s_nop 0
	v_pk_fma_f32 v[58:59], v[58:59], v[170:171], v[140:141]
	v_add_u32_e32 v140, v149, v180
	ds_read_b64 v[140:141], v140
	s_waitcnt lgkmcnt(0)
	v_cvt_f32_f16_e32 v142, v140
	v_cvt_f32_f16_sdwa v143, v140 dst_sel:DWORD dst_unused:UNUSED_PAD src0_sel:WORD_1
	v_cvt_f32_f16_e32 v140, v141
	v_cvt_f32_f16_sdwa v141, v141 dst_sel:DWORD dst_unused:UNUSED_PAD src0_sel:WORD_1
	v_pk_mul_f32 v[142:143], v[142:143], s[8:9] op_sel_hi:[1,0]
	s_nop 0
	v_pk_fma_f32 v[52:53], v[52:53], v[168:169], v[142:143]
	v_pk_mul_f32 v[140:141], v[140:141], s[8:9] op_sel_hi:[1,0]
	s_nop 0
	v_pk_fma_f32 v[54:55], v[54:55], v[166:167], v[140:141]
	v_add_u32_e32 v140, v149, v148
	ds_read_b64 v[140:141], v140
	v_add_u32_e32 v149, 0x16000, v181
	s_waitcnt lgkmcnt(0)
	v_cvt_f32_f16_e32 v142, v140
	v_cvt_f32_f16_sdwa v143, v140 dst_sel:DWORD dst_unused:UNUSED_PAD src0_sel:WORD_1
	v_cvt_f32_f16_e32 v140, v141
	v_cvt_f32_f16_sdwa v141, v141 dst_sel:DWORD dst_unused:UNUSED_PAD src0_sel:WORD_1
	v_pk_mul_f32 v[142:143], v[142:143], s[8:9] op_sel_hi:[1,0]
	s_nop 0
	v_pk_fma_f32 v[48:49], v[48:49], v[164:165], v[142:143]
	v_pk_mul_f32 v[140:141], v[140:141], s[8:9] op_sel_hi:[1,0]
	s_nop 0
	v_pk_fma_f32 v[50:51], v[50:51], v[162:163], v[140:141]
	v_add_u32_e32 v140, v149, v182
	ds_read_b64 v[140:141], v140
	s_waitcnt lgkmcnt(0)
	v_cvt_f32_f16_e32 v142, v140
	v_cvt_f32_f16_sdwa v143, v140 dst_sel:DWORD dst_unused:UNUSED_PAD src0_sel:WORD_1
	v_cvt_f32_f16_e32 v140, v141
	v_cvt_f32_f16_sdwa v141, v141 dst_sel:DWORD dst_unused:UNUSED_PAD src0_sel:WORD_1
	v_pk_mul_f32 v[142:143], v[142:143], s[8:9] op_sel_hi:[1,0]
	s_nop 0
	v_pk_fma_f32 v[44:45], v[44:45], v[176:177], v[142:143]
	v_pk_mul_f32 v[140:141], v[140:141], s[8:9] op_sel_hi:[1,0]
	s_nop 0
	v_pk_fma_f32 v[46:47], v[46:47], v[174:175], v[140:141]
	v_add_u32_e32 v140, v149, v156
	ds_read_b64 v[140:141], v140
	s_waitcnt lgkmcnt(0)
	v_cvt_f32_f16_e32 v142, v140
	v_cvt_f32_f16_sdwa v143, v140 dst_sel:DWORD dst_unused:UNUSED_PAD src0_sel:WORD_1
	v_cvt_f32_f16_e32 v140, v141
	v_cvt_f32_f16_sdwa v141, v141 dst_sel:DWORD dst_unused:UNUSED_PAD src0_sel:WORD_1
	v_pk_mul_f32 v[142:143], v[142:143], s[8:9] op_sel_hi:[1,0]
	s_nop 0
	v_pk_fma_f32 v[40:41], v[40:41], v[172:173], v[142:143]
	v_pk_mul_f32 v[140:141], v[140:141], s[8:9] op_sel_hi:[1,0]
	s_nop 0
	v_pk_fma_f32 v[42:43], v[42:43], v[170:171], v[140:141]
	v_add_u32_e32 v140, v149, v180
	ds_read_b64 v[140:141], v140
	s_waitcnt lgkmcnt(0)
	v_cvt_f32_f16_e32 v142, v140
	v_cvt_f32_f16_sdwa v143, v140 dst_sel:DWORD dst_unused:UNUSED_PAD src0_sel:WORD_1
	v_cvt_f32_f16_e32 v140, v141
	v_cvt_f32_f16_sdwa v141, v141 dst_sel:DWORD dst_unused:UNUSED_PAD src0_sel:WORD_1
	v_pk_mul_f32 v[142:143], v[142:143], s[8:9] op_sel_hi:[1,0]
	s_nop 0
	v_pk_fma_f32 v[36:37], v[36:37], v[168:169], v[142:143]
	v_pk_mul_f32 v[140:141], v[140:141], s[8:9] op_sel_hi:[1,0]
	v_xor_b32_e32 v169, 64, v20
	v_pk_fma_f32 v[38:39], v[38:39], v[166:167], v[140:141]
	v_add_u32_e32 v140, v149, v148
	ds_read_b64 v[140:141], v140
	v_pk_add_f32 v[148:149], v[2:3], v[22:23]
	v_xor_b32_e32 v168, 0x80, v20
	v_pk_mov_b32 v[20:21], v[154:155], v[152:153] op_sel:[1,0]
	v_mov_b32_e32 v22, v154
	s_waitcnt lgkmcnt(0)
	v_cvt_f32_f16_e32 v142, v140
	v_cvt_f32_f16_sdwa v143, v140 dst_sel:DWORD dst_unused:UNUSED_PAD src0_sel:WORD_1
	v_cvt_f32_f16_e32 v140, v141
	v_cvt_f32_f16_sdwa v141, v141 dst_sel:DWORD dst_unused:UNUSED_PAD src0_sel:WORD_1
	v_mov_b32_e32 v23, v153
	v_pk_mul_f32 v[142:143], v[142:143], s[8:9] op_sel_hi:[1,0]
	v_pk_add_f32 v[20:21], v[20:21], v[22:23]
	v_pk_fma_f32 v[32:33], v[32:33], v[164:165], v[142:143]
	v_pk_add_f32 v[142:143], v[12:13], v[28:29]
	v_pk_mov_b32 v[22:23], v[150:151], v[148:149] op_sel:[1,0]
	v_mov_b32_e32 v28, v150
	v_mov_b32_e32 v29, v149
	v_pk_mul_f32 v[140:141], v[140:141], s[8:9] op_sel_hi:[1,0]
	v_pk_add_f32 v[22:23], v[22:23], v[28:29]
	v_pk_fma_f32 v[34:35], v[34:35], v[162:163], v[140:141]
	v_pk_add_f32 v[140:141], v[14:15], v[30:31]
	v_add_f32_e32 v20, v20, v21
	v_pk_add_f32 v[22:23], v[22:23], v[22:23] op_sel_hi:[0,1]
	v_add_f32_e32 v21, 0, v20
	v_add_f32_e32 v29, v142, v143
	v_add_f32_e32 v31, v140, v141
	v_mov_b32_e32 v28, v18
	v_mov_b32_e32 v30, v19
	v_mov_b32_e32 v22, v16
	v_mov_b32_e32 v20, v17
	v_pk_add_f32 v[28:29], v[28:29], v[30:31]
	v_pk_add_f32 v[20:21], v[22:23], v[20:21]
	s_waitcnt lgkmcnt(0)
	s_barrier
	v_pk_add_f32 v[20:21], v[28:29], v[20:21]
	s_nop 0
	v_add_f32_e32 v20, v20, v21
	s_mov_b32 s100, 0xffff0000
	s_mov_b32 s101, 0xffff0000
	s_mov_b32 s98, 0
	s_mov_b32 s99, -1
	v_mov_b32_e32 v21, v20
	v_mov_b32_e32 v210, v20
	s_nop 1
	v_permlane16_swap_b32_e32 v21, v210
	v_cndmask_b32_e64 v21, v210, v21, s[100:101]
	s_waitcnt lgkmcnt(0)
	v_add_f32_e32 v20, v20, v21
	v_mov_b32_e32 v21, v20
	v_mov_b32_e32 v210, v20
	s_nop 1
	v_permlane32_swap_b32_e32 v21, v210
	v_cndmask_b32_e64 v21, v210, v21, s[98:99]
	s_waitcnt lgkmcnt(0)
	v_add_f32_e32 v20, v20, v21
	v_fmamk_f32 v22, v20, 0xbc800000, v153
	v_fmamk_f32 v28, v20, 0xbc800000, v155
	v_fmamk_f32 v21, v20, 0xbc800000, v152
	v_fmamk_f32 v23, v20, 0xbc800000, v154
	v_mul_f32_e32 v28, v28, v28
	v_mul_f32_e32 v22, v22, v22
	v_fmac_f32_e32 v28, v23, v23
	v_fmac_f32_e32 v22, v21, v21
	v_fmamk_f32 v23, v20, 0xbc800000, v149
	v_fmamk_f32 v29, v20, 0xbc800000, v151
	v_add_f32_e32 v21, v28, v22
	v_fmamk_f32 v22, v20, 0xbc800000, v148
	v_fmamk_f32 v28, v20, 0xbc800000, v150
	v_mul_f32_e32 v29, v29, v29
	v_mul_f32_e32 v23, v23, v23
	v_fmac_f32_e32 v29, v28, v28
	v_fmac_f32_e32 v23, v22, v22
	v_add_f32_e32 v22, v29, v23
	v_fmamk_f32 v23, v20, 0xbc800000, v141
	v_fmamk_f32 v29, v20, 0xbc800000, v143
	v_add_f32_e32 v21, v21, v22
	v_fmamk_f32 v22, v20, 0xbc800000, v140
	v_fmamk_f32 v28, v20, 0xbc800000, v142
	v_mul_f32_e32 v29, v29, v29
	v_mul_f32_e32 v23, v23, v23
	v_fmac_f32_e32 v29, v28, v28
	v_fmac_f32_e32 v23, v22, v22
	v_add_f32_e32 v22, v29, v23
	v_fmamk_f32 v23, v20, 0xbc800000, v17
	v_fmamk_f32 v29, v20, 0xbc800000, v19
	v_add_f32_e32 v21, v22, v21
	v_fmamk_f32 v22, v20, 0xbc800000, v16
	v_fmamk_f32 v28, v20, 0xbc800000, v18
	v_mul_f32_e32 v29, v29, v29
	v_mul_f32_e32 v23, v23, v23
	v_fmac_f32_e32 v29, v28, v28
	v_fmac_f32_e32 v23, v22, v22
	v_add_f32_e32 v22, v29, v23
	v_add_f32_e32 v21, v22, v21
	v_mov_b32_e32 v22, v21
	v_mov_b32_e32 v210, v21
	s_nop 1
	v_permlane16_swap_b32_e32 v22, v210
	v_cndmask_b32_e64 v22, v210, v22, s[100:101]
	s_waitcnt lgkmcnt(0)
	v_add_f32_e32 v21, v21, v22
	v_mov_b32_e32 v22, v21
	v_mov_b32_e32 v210, v21
	s_nop 1
	v_permlane32_swap_b32_e32 v22, v210
	v_cndmask_b32_e64 v22, v210, v22, s[98:99]
	s_and_saveexec_b64 s[8:9], vcc
	s_cbranch_execz .LBB0_853
	s_lshl_b32 s3, s24, 11
	s_add_i32 s3, s11, s3
	v_mul_f32_e32 v20, 0x3c800000, v20
	s_waitcnt lgkmcnt(0)
	v_add_f32_e32 v21, v21, v22
	v_lshl_add_u32 v22, v178, 5, s3
	ds_write_b64 v22, v[20:21]
.LBB0_853:
	s_or_b64 exec, exec, s[8:9]
	v_pk_add_f32 v[144:145], v[6:7], v[26:27]
	v_pk_add_f32 v[146:147], v[4:5], v[24:25]
	v_pk_add_f32 v[138:139], v[2:3], v[138:139]
	v_pk_add_f32 v[136:137], v[0:1], v[136:137]
	v_pk_mov_b32 v[24:25], v[146:147], v[144:145] op_sel:[1,0]
	v_mov_b32_e32 v26, v146
	v_mov_b32_e32 v27, v145
	v_pk_add_f32 v[24:25], v[24:25], v[26:27]
	v_pk_mov_b32 v[26:27], v[136:137], v[138:139] op_sel:[1,0]
	v_mov_b32_e32 v28, v136
	v_mov_b32_e32 v29, v139
	v_pk_add_f32 v[26:27], v[26:27], v[28:29]
	v_pk_add_f32 v[134:135], v[14:15], v[134:135]
	v_pk_add_f32 v[132:133], v[12:13], v[132:133]
	v_pk_add_f32 v[20:21], v[10:11], v[130:131]
	s_waitcnt lgkmcnt(0)
	v_pk_add_f32 v[22:23], v[8:9], v[128:129]
	v_add_f32_e32 v24, v24, v25
	v_pk_add_f32 v[26:27], v[26:27], v[26:27] op_sel_hi:[0,1]
	v_add_f32_e32 v25, 0, v24
	v_add_f32_e32 v29, v132, v133
	v_add_f32_e32 v31, v134, v135
	v_mov_b32_e32 v28, v22
	v_mov_b32_e32 v30, v23
	v_mov_b32_e32 v26, v20
	v_mov_b32_e32 v24, v21
	v_pk_add_f32 v[28:29], v[28:29], v[30:31]
	v_pk_add_f32 v[24:25], v[26:27], v[24:25]
	s_nop 0
	v_pk_add_f32 v[24:25], v[28:29], v[24:25]
	s_nop 0
	v_add_f32_e32 v24, v24, v25
	v_mov_b32_e32 v25, v24
	v_mov_b32_e32 v210, v24
	s_nop 1
	v_permlane16_swap_b32_e32 v25, v210
	v_cndmask_b32_e64 v25, v210, v25, s[100:101]
	s_waitcnt lgkmcnt(0)
	v_add_f32_e32 v24, v24, v25
	v_mov_b32_e32 v25, v24
	v_mov_b32_e32 v210, v24
	s_nop 1
	v_permlane32_swap_b32_e32 v25, v210
	v_cndmask_b32_e64 v25, v210, v25, s[98:99]
	s_waitcnt lgkmcnt(0)
	v_add_f32_e32 v24, v24, v25
	v_fmamk_f32 v26, v24, 0xbc800000, v145
	v_fmamk_f32 v28, v24, 0xbc800000, v147
	v_fmamk_f32 v25, v24, 0xbc800000, v144
	v_fmamk_f32 v27, v24, 0xbc800000, v146
	v_mul_f32_e32 v28, v28, v28
	v_mul_f32_e32 v26, v26, v26
	v_fmac_f32_e32 v28, v27, v27
	v_fmac_f32_e32 v26, v25, v25
	v_fmamk_f32 v27, v24, 0xbc800000, v139
	v_fmamk_f32 v29, v24, 0xbc800000, v137
	v_add_f32_e32 v25, v28, v26
	v_fmamk_f32 v26, v24, 0xbc800000, v138
	v_fmamk_f32 v28, v24, 0xbc800000, v136
	v_mul_f32_e32 v29, v29, v29
	v_mul_f32_e32 v27, v27, v27
	v_fmac_f32_e32 v29, v28, v28
	v_fmac_f32_e32 v27, v26, v26
	v_add_f32_e32 v26, v29, v27
	v_fmamk_f32 v27, v24, 0xbc800000, v135
	v_fmamk_f32 v29, v24, 0xbc800000, v133
	v_add_f32_e32 v25, v25, v26
	v_fmamk_f32 v26, v24, 0xbc800000, v134
	v_fmamk_f32 v28, v24, 0xbc800000, v132
	v_mul_f32_e32 v29, v29, v29
	v_mul_f32_e32 v27, v27, v27
	v_fmac_f32_e32 v29, v28, v28
	v_fmac_f32_e32 v27, v26, v26
	v_add_f32_e32 v26, v29, v27
	v_fmamk_f32 v27, v24, 0xbc800000, v21
	v_fmamk_f32 v29, v24, 0xbc800000, v23
	v_add_f32_e32 v25, v26, v25
	v_fmamk_f32 v26, v24, 0xbc800000, v20
	v_fmamk_f32 v28, v24, 0xbc800000, v22
	v_mul_f32_e32 v29, v29, v29
	v_mul_f32_e32 v27, v27, v27
	v_fmac_f32_e32 v29, v28, v28
	v_fmac_f32_e32 v27, v26, v26
	v_add_f32_e32 v26, v29, v27
	v_add_f32_e32 v25, v26, v25
	v_mov_b32_e32 v26, v25
	v_mov_b32_e32 v210, v25
	s_nop 1
	v_permlane16_swap_b32_e32 v26, v210
	v_cndmask_b32_e64 v26, v210, v26, s[100:101]
	s_waitcnt lgkmcnt(0)
	v_add_f32_e32 v25, v25, v26
	v_mov_b32_e32 v26, v25
	v_mov_b32_e32 v210, v25
	s_nop 1
	v_permlane32_swap_b32_e32 v26, v210
	v_cndmask_b32_e64 v26, v210, v26, s[98:99]
	s_and_saveexec_b64 s[8:9], vcc
	s_cbranch_execz .LBB0_855
	s_lshl_b32 s3, s24, 11
	s_add_i32 s3, s11, s3
	v_mul_f32_e32 v24, 0x3c800000, v24
	s_waitcnt lgkmcnt(0)
	v_add_f32_e32 v25, v25, v26
	v_lshl_add_u32 v26, v178, 5, s3
	ds_write_b64 v26, v[24:25] offset:512
.LBB0_855:
	s_or_b64 exec, exec, s[8:9]
	v_pk_add_f32 v[126:127], v[6:7], v[126:127]
	v_pk_add_f32 v[124:125], v[4:5], v[124:125]
	v_pk_add_f32 v[122:123], v[2:3], v[122:123]
	v_pk_add_f32 v[120:121], v[0:1], v[120:121]
	v_pk_mov_b32 v[28:29], v[124:125], v[126:127] op_sel:[1,0]
	v_mov_b32_e32 v30, v124
	v_mov_b32_e32 v31, v127
	s_waitcnt lgkmcnt(0)
	v_pk_add_f32 v[26:27], v[8:9], v[112:113]
	v_pk_add_f32 v[28:29], v[28:29], v[30:31]
	v_pk_mov_b32 v[30:31], v[120:121], v[122:123] op_sel:[1,0]
	v_mov_b32_e32 v112, v120
	v_mov_b32_e32 v113, v123
	v_pk_add_f32 v[30:31], v[30:31], v[112:113]
	v_pk_add_f32 v[118:119], v[14:15], v[118:119]
	v_pk_add_f32 v[116:117], v[12:13], v[116:117]
	v_pk_add_f32 v[24:25], v[10:11], v[114:115]
	v_add_f32_e32 v28, v28, v29
	v_pk_add_f32 v[30:31], v[30:31], v[30:31] op_sel_hi:[0,1]
	v_add_f32_e32 v29, 0, v28
	v_add_f32_e32 v113, v116, v117
	v_add_f32_e32 v115, v118, v119
	v_mov_b32_e32 v112, v26
	v_mov_b32_e32 v114, v27
	v_mov_b32_e32 v30, v24
	v_mov_b32_e32 v28, v25
	v_pk_add_f32 v[112:113], v[112:113], v[114:115]
	v_pk_add_f32 v[28:29], v[30:31], v[28:29]
	s_nop 0
	v_pk_add_f32 v[28:29], v[112:113], v[28:29]
	s_nop 0
	v_add_f32_e32 v28, v28, v29
	v_mov_b32_e32 v29, v28
	v_mov_b32_e32 v210, v28
	s_nop 1
	v_permlane16_swap_b32_e32 v29, v210
	v_cndmask_b32_e64 v29, v210, v29, s[100:101]
	s_waitcnt lgkmcnt(0)
	v_add_f32_e32 v28, v28, v29
	v_mov_b32_e32 v29, v28
	v_mov_b32_e32 v210, v28
	s_nop 1
	v_permlane32_swap_b32_e32 v29, v210
	v_cndmask_b32_e64 v29, v210, v29, s[98:99]
	s_waitcnt lgkmcnt(0)
	v_add_f32_e32 v28, v28, v29
	v_fmamk_f32 v30, v28, 0xbc800000, v127
	v_fmamk_f32 v112, v28, 0xbc800000, v125
	v_fmamk_f32 v29, v28, 0xbc800000, v126
	v_fmamk_f32 v31, v28, 0xbc800000, v124
	v_mul_f32_e32 v112, v112, v112
	v_mul_f32_e32 v30, v30, v30
	v_fmac_f32_e32 v112, v31, v31
	v_fmac_f32_e32 v30, v29, v29
	v_fmamk_f32 v31, v28, 0xbc800000, v123
	v_fmamk_f32 v113, v28, 0xbc800000, v121
	v_add_f32_e32 v29, v112, v30
	v_fmamk_f32 v30, v28, 0xbc800000, v122
	v_fmamk_f32 v112, v28, 0xbc800000, v120
	v_mul_f32_e32 v113, v113, v113
	v_mul_f32_e32 v31, v31, v31
	v_fmac_f32_e32 v113, v112, v112
	v_fmac_f32_e32 v31, v30, v30
	v_add_f32_e32 v30, v113, v31
	v_fmamk_f32 v31, v28, 0xbc800000, v119
	v_fmamk_f32 v113, v28, 0xbc800000, v117
	v_add_f32_e32 v29, v29, v30
	v_fmamk_f32 v30, v28, 0xbc800000, v118
	v_fmamk_f32 v112, v28, 0xbc800000, v116
	v_mul_f32_e32 v113, v113, v113
	v_mul_f32_e32 v31, v31, v31
	v_fmac_f32_e32 v113, v112, v112
	v_fmac_f32_e32 v31, v30, v30
	v_add_f32_e32 v30, v113, v31
	v_fmamk_f32 v31, v28, 0xbc800000, v25
	v_fmamk_f32 v113, v28, 0xbc800000, v27
	v_add_f32_e32 v29, v30, v29
	v_fmamk_f32 v30, v28, 0xbc800000, v24
	v_fmamk_f32 v112, v28, 0xbc800000, v26
	v_mul_f32_e32 v113, v113, v113
	v_mul_f32_e32 v31, v31, v31
	v_fmac_f32_e32 v113, v112, v112
	v_fmac_f32_e32 v31, v30, v30
	v_add_f32_e32 v30, v113, v31
	v_add_f32_e32 v29, v30, v29
	v_mov_b32_e32 v30, v29
	v_mov_b32_e32 v210, v29
	s_nop 1
	v_permlane16_swap_b32_e32 v30, v210
	v_cndmask_b32_e64 v30, v210, v30, s[100:101]
	s_waitcnt lgkmcnt(0)
	v_add_f32_e32 v29, v29, v30
	v_mov_b32_e32 v30, v29
	v_mov_b32_e32 v210, v29
	s_nop 1
	v_permlane32_swap_b32_e32 v30, v210
	v_cndmask_b32_e64 v30, v210, v30, s[98:99]
	s_and_saveexec_b64 s[8:9], vcc
	s_cbranch_execz .LBB0_857
	s_lshl_b32 s3, s24, 11
	s_add_i32 s3, s11, s3
	v_mul_f32_e32 v28, 0x3c800000, v28
	s_waitcnt lgkmcnt(0)
	v_add_f32_e32 v29, v29, v30
	v_lshl_add_u32 v30, v178, 5, s3
	ds_write_b64 v30, v[28:29] offset:1024
.LBB0_857:
	s_or_b64 exec, exec, s[8:9]
	v_pk_add_f32 v[110:111], v[6:7], v[110:111]
	v_pk_add_f32 v[108:109], v[4:5], v[108:109]
	v_pk_add_f32 v[106:107], v[2:3], v[106:107]
	v_pk_add_f32 v[104:105], v[0:1], v[104:105]
	v_pk_add_f32 v[28:29], v[10:11], v[98:99]
	s_waitcnt lgkmcnt(0)
	v_pk_add_f32 v[30:31], v[8:9], v[96:97]
	v_pk_mov_b32 v[96:97], v[108:109], v[110:111] op_sel:[1,0]
	v_mov_b32_e32 v98, v108
	v_mov_b32_e32 v99, v111
	v_pk_add_f32 v[96:97], v[96:97], v[98:99]
	v_pk_mov_b32 v[98:99], v[104:105], v[106:107] op_sel:[1,0]
	v_mov_b32_e32 v112, v104
	v_mov_b32_e32 v113, v107
	v_pk_add_f32 v[98:99], v[98:99], v[112:113]
	v_pk_add_f32 v[102:103], v[14:15], v[102:103]
	v_pk_add_f32 v[100:101], v[12:13], v[100:101]
	v_add_f32_e32 v96, v96, v97
	v_pk_add_f32 v[98:99], v[98:99], v[98:99] op_sel_hi:[0,1]
	v_add_f32_e32 v97, 0, v96
	v_add_f32_e32 v113, v100, v101
	v_add_f32_e32 v115, v102, v103
	v_mov_b32_e32 v112, v30
	v_mov_b32_e32 v114, v31
	v_mov_b32_e32 v98, v28
	v_mov_b32_e32 v96, v29
	v_pk_add_f32 v[112:113], v[112:113], v[114:115]
	v_pk_add_f32 v[96:97], v[98:99], v[96:97]
	s_nop 0
	v_pk_add_f32 v[96:97], v[112:113], v[96:97]
	s_nop 0
	v_add_f32_e32 v96, v96, v97
	v_mov_b32_e32 v97, v96
	v_mov_b32_e32 v210, v96
	s_nop 1
	v_permlane16_swap_b32_e32 v97, v210
	v_cndmask_b32_e64 v97, v210, v97, s[100:101]
	s_waitcnt lgkmcnt(0)
	v_add_f32_e32 v96, v96, v97
	v_mov_b32_e32 v97, v96
	v_mov_b32_e32 v210, v96
	s_nop 1
	v_permlane32_swap_b32_e32 v97, v210
	v_cndmask_b32_e64 v97, v210, v97, s[98:99]
	s_waitcnt lgkmcnt(0)
	v_add_f32_e32 v96, v96, v97
	v_fmamk_f32 v98, v96, 0xbc800000, v111
	v_fmamk_f32 v112, v96, 0xbc800000, v109
	v_fmamk_f32 v97, v96, 0xbc800000, v110
	v_fmamk_f32 v99, v96, 0xbc800000, v108
	v_mul_f32_e32 v112, v112, v112
	v_mul_f32_e32 v98, v98, v98
	v_fmac_f32_e32 v112, v99, v99
	v_fmac_f32_e32 v98, v97, v97
	v_fmamk_f32 v99, v96, 0xbc800000, v107
	v_fmamk_f32 v113, v96, 0xbc800000, v105
	v_add_f32_e32 v97, v112, v98
	v_fmamk_f32 v98, v96, 0xbc800000, v106
	v_fmamk_f32 v112, v96, 0xbc800000, v104
	v_mul_f32_e32 v113, v113, v113
	v_mul_f32_e32 v99, v99, v99
	v_fmac_f32_e32 v113, v112, v112
	v_fmac_f32_e32 v99, v98, v98
	v_add_f32_e32 v98, v113, v99
	v_fmamk_f32 v99, v96, 0xbc800000, v103
	v_fmamk_f32 v113, v96, 0xbc800000, v101
	v_add_f32_e32 v97, v97, v98
	v_fmamk_f32 v98, v96, 0xbc800000, v102
	v_fmamk_f32 v112, v96, 0xbc800000, v100
	v_mul_f32_e32 v113, v113, v113
	v_mul_f32_e32 v99, v99, v99
	v_fmac_f32_e32 v113, v112, v112
	v_fmac_f32_e32 v99, v98, v98
	v_add_f32_e32 v98, v113, v99
	v_fmamk_f32 v99, v96, 0xbc800000, v29
	v_fmamk_f32 v113, v96, 0xbc800000, v31
	v_add_f32_e32 v97, v98, v97
	v_fmamk_f32 v98, v96, 0xbc800000, v28
	v_fmamk_f32 v112, v96, 0xbc800000, v30
	v_mul_f32_e32 v113, v113, v113
	v_mul_f32_e32 v99, v99, v99
	v_fmac_f32_e32 v113, v112, v112
	v_fmac_f32_e32 v99, v98, v98
	v_add_f32_e32 v98, v113, v99
	v_add_f32_e32 v97, v98, v97
	v_mov_b32_e32 v98, v97
	v_mov_b32_e32 v210, v97
	s_nop 1
	v_permlane16_swap_b32_e32 v98, v210
	v_cndmask_b32_e64 v98, v210, v98, s[100:101]
	s_waitcnt lgkmcnt(0)
	v_add_f32_e32 v97, v97, v98
	v_mov_b32_e32 v98, v97
	v_mov_b32_e32 v210, v97
	s_nop 1
	v_permlane32_swap_b32_e32 v98, v210
	v_cndmask_b32_e64 v98, v210, v98, s[98:99]
	s_and_saveexec_b64 s[8:9], vcc
	s_cbranch_execz .LBB0_859
	s_lshl_b32 s3, s24, 11
	s_add_i32 s3, s11, s3
	v_mul_f32_e32 v96, 0x3c800000, v96
	s_waitcnt lgkmcnt(0)
	v_add_f32_e32 v97, v97, v98
	v_lshl_add_u32 v98, v178, 5, s3
	ds_write_b64 v98, v[96:97] offset:1536
.LBB0_859:
	s_or_b64 exec, exec, s[8:9]
	v_pk_add_f32 v[96:97], v[6:7], v[94:95]
	s_waitcnt lgkmcnt(0)
	v_pk_add_f32 v[98:99], v[4:5], v[92:93]
	v_pk_add_f32 v[90:91], v[2:3], v[90:91]
	v_pk_add_f32 v[88:89], v[0:1], v[88:89]
	v_pk_mov_b32 v[92:93], v[98:99], v[96:97] op_sel:[1,0]
	v_mov_b32_e32 v94, v98
	v_mov_b32_e32 v95, v97
	v_pk_add_f32 v[92:93], v[92:93], v[94:95]
	v_pk_mov_b32 v[94:95], v[88:89], v[90:91] op_sel:[1,0]
	v_mov_b32_e32 v112, v88
	v_mov_b32_e32 v113, v91
	v_pk_add_f32 v[94:95], v[94:95], v[112:113]
	v_pk_add_f32 v[86:87], v[14:15], v[86:87]
	v_pk_add_f32 v[84:85], v[12:13], v[84:85]
	v_pk_add_f32 v[82:83], v[10:11], v[82:83]
	v_pk_add_f32 v[80:81], v[8:9], v[80:81]
	v_add_f32_e32 v92, v92, v93
	v_pk_add_f32 v[94:95], v[94:95], v[94:95] op_sel_hi:[0,1]
	v_add_f32_e32 v93, 0, v92
	v_add_f32_e32 v113, v84, v85
	v_add_f32_e32 v115, v86, v87
	v_mov_b32_e32 v112, v80
	v_mov_b32_e32 v114, v81
	v_mov_b32_e32 v94, v82
	v_mov_b32_e32 v92, v83
	v_pk_add_f32 v[112:113], v[112:113], v[114:115]
	v_pk_add_f32 v[92:93], v[94:95], v[92:93]
	s_nop 0
	v_pk_add_f32 v[92:93], v[112:113], v[92:93]
	s_nop 0
	v_add_f32_e32 v92, v92, v93
	v_mov_b32_e32 v93, v92
	v_mov_b32_e32 v210, v92
	s_nop 1
	v_permlane16_swap_b32_e32 v93, v210
	v_cndmask_b32_e64 v93, v210, v93, s[100:101]
	s_waitcnt lgkmcnt(0)
	v_add_f32_e32 v92, v92, v93
	v_mov_b32_e32 v93, v92
	v_mov_b32_e32 v210, v92
	s_nop 1
	v_permlane32_swap_b32_e32 v93, v210
	v_cndmask_b32_e64 v93, v210, v93, s[98:99]
	s_waitcnt lgkmcnt(0)
	v_add_f32_e32 v92, v92, v93
	v_fmamk_f32 v94, v92, 0xbc800000, v97
	v_fmamk_f32 v112, v92, 0xbc800000, v99
	v_fmamk_f32 v93, v92, 0xbc800000, v96
	v_fmamk_f32 v95, v92, 0xbc800000, v98
	v_mul_f32_e32 v112, v112, v112
	v_mul_f32_e32 v94, v94, v94
	v_fmac_f32_e32 v112, v95, v95
	v_fmac_f32_e32 v94, v93, v93
	v_fmamk_f32 v95, v92, 0xbc800000, v91
	v_fmamk_f32 v113, v92, 0xbc800000, v89
	v_add_f32_e32 v93, v112, v94
	v_fmamk_f32 v94, v92, 0xbc800000, v90
	v_fmamk_f32 v112, v92, 0xbc800000, v88
	v_mul_f32_e32 v113, v113, v113
	v_mul_f32_e32 v95, v95, v95
	v_fmac_f32_e32 v113, v112, v112
	v_fmac_f32_e32 v95, v94, v94
	v_add_f32_e32 v94, v113, v95
	v_fmamk_f32 v95, v92, 0xbc800000, v87
	v_fmamk_f32 v113, v92, 0xbc800000, v85
	v_add_f32_e32 v93, v93, v94
	v_fmamk_f32 v94, v92, 0xbc800000, v86
	v_fmamk_f32 v112, v92, 0xbc800000, v84
	v_mul_f32_e32 v113, v113, v113
	v_mul_f32_e32 v95, v95, v95
	v_fmac_f32_e32 v113, v112, v112
	v_fmac_f32_e32 v95, v94, v94
	v_add_f32_e32 v94, v113, v95
	v_fmamk_f32 v95, v92, 0xbc800000, v83
	v_fmamk_f32 v113, v92, 0xbc800000, v81
	v_add_f32_e32 v93, v94, v93
	v_fmamk_f32 v94, v92, 0xbc800000, v82
	v_fmamk_f32 v112, v92, 0xbc800000, v80
	v_mul_f32_e32 v113, v113, v113
	v_mul_f32_e32 v95, v95, v95
	v_fmac_f32_e32 v113, v112, v112
	v_fmac_f32_e32 v95, v94, v94
	v_add_f32_e32 v94, v113, v95
	v_add_f32_e32 v93, v94, v93
	v_mov_b32_e32 v94, v93
	v_mov_b32_e32 v210, v93
	s_nop 1
	v_permlane16_swap_b32_e32 v94, v210
	v_cndmask_b32_e64 v94, v210, v94, s[100:101]
	s_waitcnt lgkmcnt(0)
	v_add_f32_e32 v93, v93, v94
	v_mov_b32_e32 v94, v93
	v_mov_b32_e32 v210, v93
	s_nop 1
	v_permlane32_swap_b32_e32 v94, v210
	v_cndmask_b32_e64 v94, v210, v94, s[98:99]
	s_and_saveexec_b64 s[8:9], vcc
	s_cbranch_execz .LBB0_861
	s_lshl_b32 s3, s24, 11
	s_add_i32 s3, s11, s3
	v_mul_f32_e32 v92, 0x3c800000, v92
	s_waitcnt lgkmcnt(0)
	v_add_f32_e32 v93, v93, v94
	v_lshl_add_u32 v94, v178, 5, s3
	ds_write_b64 v94, v[92:93] offset:4096
.LBB0_861:
	s_or_b64 exec, exec, s[8:9]
	v_pk_add_f32 v[130:131], v[6:7], v[78:79]
	v_pk_add_f32 v[156:157], v[4:5], v[76:77]
	v_pk_add_f32 v[74:75], v[2:3], v[74:75]
	v_pk_add_f32 v[72:73], v[0:1], v[72:73]
	v_pk_mov_b32 v[76:77], v[156:157], v[130:131] op_sel:[1,0]
	v_mov_b32_e32 v78, v156
	v_mov_b32_e32 v79, v131
	v_pk_add_f32 v[76:77], v[76:77], v[78:79]
	v_pk_mov_b32 v[78:79], v[72:73], v[74:75] op_sel:[1,0]
	v_mov_b32_e32 v92, v72
	v_mov_b32_e32 v93, v75
	v_pk_add_f32 v[78:79], v[78:79], v[92:93]
	v_pk_add_f32 v[70:71], v[14:15], v[70:71]
	v_pk_add_f32 v[68:69], v[12:13], v[68:69]
	v_pk_add_f32 v[66:67], v[10:11], v[66:67]
	v_pk_add_f32 v[64:65], v[8:9], v[64:65]
	v_add_f32_e32 v76, v76, v77
	v_pk_add_f32 v[78:79], v[78:79], v[78:79] op_sel_hi:[0,1]
	v_add_f32_e32 v77, 0, v76
	v_add_f32_e32 v93, v68, v69
	v_add_f32_e32 v95, v70, v71
	v_mov_b32_e32 v92, v64
	s_waitcnt lgkmcnt(0)
	v_mov_b32_e32 v94, v65
	v_mov_b32_e32 v78, v66
	v_mov_b32_e32 v76, v67
	v_pk_add_f32 v[92:93], v[92:93], v[94:95]
	v_pk_add_f32 v[76:77], v[78:79], v[76:77]
	s_nop 0
	v_pk_add_f32 v[76:77], v[92:93], v[76:77]
	s_nop 0
	v_add_f32_e32 v76, v76, v77
	v_mov_b32_e32 v77, v76
	v_mov_b32_e32 v210, v76
	s_nop 1
	v_permlane16_swap_b32_e32 v77, v210
	v_cndmask_b32_e64 v77, v210, v77, s[100:101]
	s_waitcnt lgkmcnt(0)
	v_add_f32_e32 v76, v76, v77
	v_mov_b32_e32 v77, v76
	v_mov_b32_e32 v210, v76
	s_nop 1
	v_permlane32_swap_b32_e32 v77, v210
	v_cndmask_b32_e64 v77, v210, v77, s[98:99]
	s_waitcnt lgkmcnt(0)
	v_add_f32_e32 v76, v76, v77
	v_fmamk_f32 v78, v76, 0xbc800000, v131
	v_fmamk_f32 v92, v76, 0xbc800000, v157
	v_fmamk_f32 v77, v76, 0xbc800000, v130
	v_fmamk_f32 v79, v76, 0xbc800000, v156
	v_mul_f32_e32 v92, v92, v92
	v_mul_f32_e32 v78, v78, v78
	v_fmac_f32_e32 v92, v79, v79
	v_fmac_f32_e32 v78, v77, v77
	v_fmamk_f32 v79, v76, 0xbc800000, v75
	v_fmamk_f32 v93, v76, 0xbc800000, v73
	v_add_f32_e32 v77, v92, v78
	v_fmamk_f32 v78, v76, 0xbc800000, v74
	v_fmamk_f32 v92, v76, 0xbc800000, v72
	v_mul_f32_e32 v93, v93, v93
	v_mul_f32_e32 v79, v79, v79
	v_fmac_f32_e32 v93, v92, v92
	v_fmac_f32_e32 v79, v78, v78
	v_add_f32_e32 v78, v93, v79
	v_fmamk_f32 v79, v76, 0xbc800000, v71
	v_fmamk_f32 v93, v76, 0xbc800000, v69
	v_add_f32_e32 v77, v77, v78
	v_fmamk_f32 v78, v76, 0xbc800000, v70
	v_fmamk_f32 v92, v76, 0xbc800000, v68
	v_mul_f32_e32 v93, v93, v93
	v_mul_f32_e32 v79, v79, v79
	v_fmac_f32_e32 v93, v92, v92
	v_fmac_f32_e32 v79, v78, v78
	v_add_f32_e32 v78, v93, v79
	v_fmamk_f32 v79, v76, 0xbc800000, v67
	v_fmamk_f32 v93, v76, 0xbc800000, v65
	v_add_f32_e32 v77, v78, v77
	v_fmamk_f32 v78, v76, 0xbc800000, v66
	v_fmamk_f32 v92, v76, 0xbc800000, v64
	v_mul_f32_e32 v93, v93, v93
	v_mul_f32_e32 v79, v79, v79
	v_fmac_f32_e32 v93, v92, v92
	v_fmac_f32_e32 v79, v78, v78
	v_add_f32_e32 v78, v93, v79
	v_add_f32_e32 v77, v78, v77
	v_mov_b32_e32 v78, v77
	v_mov_b32_e32 v210, v77
	s_nop 1
	v_permlane16_swap_b32_e32 v78, v210
	v_cndmask_b32_e64 v78, v210, v78, s[100:101]
	s_waitcnt lgkmcnt(0)
	v_add_f32_e32 v77, v77, v78
	v_mov_b32_e32 v78, v77
	v_mov_b32_e32 v210, v77
	s_nop 1
	v_permlane32_swap_b32_e32 v78, v210
	v_cndmask_b32_e64 v78, v210, v78, s[98:99]
	s_and_saveexec_b64 s[8:9], vcc
	s_cbranch_execz .LBB0_863
	s_lshl_b32 s3, s24, 11
	s_add_i32 s3, s11, s3
	v_mul_f32_e32 v76, 0x3c800000, v76
	s_waitcnt lgkmcnt(0)
	v_add_f32_e32 v77, v77, v78
	v_lshl_add_u32 v78, v178, 5, s3
	ds_write_b64 v78, v[76:77] offset:4608
.LBB0_863:
	s_or_b64 exec, exec, s[8:9]
	v_pk_add_f32 v[158:159], v[6:7], v[62:63]
	v_pk_add_f32 v[162:163], v[4:5], v[60:61]
	v_pk_add_f32 v[58:59], v[2:3], v[58:59]
	v_pk_add_f32 v[56:57], v[0:1], v[56:57]
	v_pk_mov_b32 v[60:61], v[162:163], v[158:159] op_sel:[1,0]
	v_mov_b32_e32 v62, v162
	v_mov_b32_e32 v63, v159
	v_pk_add_f32 v[60:61], v[60:61], v[62:63]
	v_pk_mov_b32 v[62:63], v[56:57], v[58:59] op_sel:[1,0]
	v_mov_b32_e32 v76, v56
	v_mov_b32_e32 v77, v59
	v_pk_add_f32 v[62:63], v[62:63], v[76:77]
	v_pk_add_f32 v[54:55], v[14:15], v[54:55]
	v_pk_add_f32 v[52:53], v[12:13], v[52:53]
	v_pk_add_f32 v[50:51], v[10:11], v[50:51]
	v_pk_add_f32 v[48:49], v[8:9], v[48:49]
	v_add_f32_e32 v60, v60, v61
	v_pk_add_f32 v[62:63], v[62:63], v[62:63] op_sel_hi:[0,1]
	v_add_f32_e32 v61, 0, v60
	v_add_f32_e32 v77, v52, v53
	v_add_f32_e32 v79, v54, v55
	v_mov_b32_e32 v76, v48
	s_waitcnt lgkmcnt(0)
	v_mov_b32_e32 v78, v49
	v_mov_b32_e32 v62, v50
	v_mov_b32_e32 v60, v51
	v_pk_add_f32 v[76:77], v[76:77], v[78:79]
	v_pk_add_f32 v[60:61], v[62:63], v[60:61]
	s_nop 0
	v_pk_add_f32 v[60:61], v[76:77], v[60:61]
	s_nop 0
	v_add_f32_e32 v60, v60, v61
	v_mov_b32_e32 v61, v60
	v_mov_b32_e32 v210, v60
	s_nop 1
	v_permlane16_swap_b32_e32 v61, v210
	v_cndmask_b32_e64 v61, v210, v61, s[100:101]
	s_waitcnt lgkmcnt(0)
	v_add_f32_e32 v60, v60, v61
	v_mov_b32_e32 v61, v60
	v_mov_b32_e32 v210, v60
	s_nop 1
	v_permlane32_swap_b32_e32 v61, v210
	v_cndmask_b32_e64 v61, v210, v61, s[98:99]
	s_waitcnt lgkmcnt(0)
	v_add_f32_e32 v60, v60, v61
	v_fmamk_f32 v62, v60, 0xbc800000, v159
	v_fmamk_f32 v76, v60, 0xbc800000, v163
	v_fmamk_f32 v61, v60, 0xbc800000, v158
	v_fmamk_f32 v63, v60, 0xbc800000, v162
	v_mul_f32_e32 v76, v76, v76
	v_mul_f32_e32 v62, v62, v62
	v_fmac_f32_e32 v76, v63, v63
	v_fmac_f32_e32 v62, v61, v61
	v_fmamk_f32 v63, v60, 0xbc800000, v59
	v_fmamk_f32 v77, v60, 0xbc800000, v57
	v_add_f32_e32 v61, v76, v62
	v_fmamk_f32 v62, v60, 0xbc800000, v58
	v_fmamk_f32 v76, v60, 0xbc800000, v56
	v_mul_f32_e32 v77, v77, v77
	v_mul_f32_e32 v63, v63, v63
	v_fmac_f32_e32 v77, v76, v76
	v_fmac_f32_e32 v63, v62, v62
	v_add_f32_e32 v62, v77, v63
	v_fmamk_f32 v63, v60, 0xbc800000, v55
	v_fmamk_f32 v77, v60, 0xbc800000, v53
	v_add_f32_e32 v61, v61, v62
	v_fmamk_f32 v62, v60, 0xbc800000, v54
	v_fmamk_f32 v76, v60, 0xbc800000, v52
	v_mul_f32_e32 v77, v77, v77
	v_mul_f32_e32 v63, v63, v63
	v_fmac_f32_e32 v77, v76, v76
	v_fmac_f32_e32 v63, v62, v62
	v_add_f32_e32 v62, v77, v63
	v_fmamk_f32 v63, v60, 0xbc800000, v51
	v_fmamk_f32 v77, v60, 0xbc800000, v49
	v_add_f32_e32 v61, v62, v61
	v_fmamk_f32 v62, v60, 0xbc800000, v50
	v_fmamk_f32 v76, v60, 0xbc800000, v48
	v_mul_f32_e32 v77, v77, v77
	v_mul_f32_e32 v63, v63, v63
	v_fmac_f32_e32 v77, v76, v76
	v_fmac_f32_e32 v63, v62, v62
	v_add_f32_e32 v62, v77, v63
	v_add_f32_e32 v61, v62, v61
	v_mov_b32_e32 v62, v61
	v_mov_b32_e32 v210, v61
	s_nop 1
	v_permlane16_swap_b32_e32 v62, v210
	v_cndmask_b32_e64 v62, v210, v62, s[100:101]
	s_waitcnt lgkmcnt(0)
	v_add_f32_e32 v61, v61, v62
	v_mov_b32_e32 v62, v61
	v_mov_b32_e32 v210, v61
	s_nop 1
	v_permlane32_swap_b32_e32 v62, v210
	v_cndmask_b32_e64 v62, v210, v62, s[98:99]
	s_and_saveexec_b64 s[8:9], vcc
	s_cbranch_execz .LBB0_865
	s_lshl_b32 s3, s24, 11
	s_add_i32 s3, s11, s3
	v_mul_f32_e32 v60, 0x3c800000, v60
	s_waitcnt lgkmcnt(0)
	v_add_f32_e32 v61, v61, v62
	v_lshl_add_u32 v62, v178, 5, s3
	ds_write_b64 v62, v[60:61] offset:5120
.LBB0_865:
	s_or_b64 exec, exec, s[8:9]
	v_pk_add_f32 v[164:165], v[6:7], v[46:47]
	v_pk_add_f32 v[166:167], v[4:5], v[44:45]
	v_pk_add_f32 v[42:43], v[2:3], v[42:43]
	v_pk_add_f32 v[44:45], v[0:1], v[40:41]
	v_pk_mov_b32 v[0:1], v[166:167], v[164:165] op_sel:[1,0]
	v_mov_b32_e32 v2, v166
	v_mov_b32_e32 v3, v165
	v_pk_add_f32 v[0:1], v[0:1], v[2:3]
	v_pk_mov_b32 v[2:3], v[44:45], v[42:43] op_sel:[1,0]
	v_mov_b32_e32 v4, v44
	v_mov_b32_e32 v5, v43
	v_pk_add_f32 v[2:3], v[2:3], v[4:5]
	v_pk_add_f32 v[38:39], v[14:15], v[38:39]
	v_pk_add_f32 v[36:37], v[12:13], v[36:37]
	v_pk_add_f32 v[34:35], v[10:11], v[34:35]
	v_pk_add_f32 v[32:33], v[8:9], v[32:33]
	v_add_f32_e32 v0, v0, v1
	v_pk_add_f32 v[2:3], v[2:3], v[2:3] op_sel_hi:[0,1]
	v_add_f32_e32 v1, 0, v0
	v_add_f32_e32 v5, v36, v37
	v_add_f32_e32 v7, v38, v39
	v_mov_b32_e32 v4, v32
	v_mov_b32_e32 v6, v33
	v_mov_b32_e32 v2, v34
	v_mov_b32_e32 v0, v35
	v_pk_add_f32 v[4:5], v[4:5], v[6:7]
	v_pk_add_f32 v[0:1], v[2:3], v[0:1]
	s_nop 0
	v_pk_add_f32 v[0:1], v[4:5], v[0:1]
	s_nop 0
	v_add_f32_e32 v0, v0, v1
	v_mov_b32_e32 v1, v0
	v_mov_b32_e32 v210, v0
	s_nop 1
	v_permlane16_swap_b32_e32 v1, v210
	v_cndmask_b32_e64 v1, v210, v1, s[100:101]
	s_waitcnt lgkmcnt(0)
	v_add_f32_e32 v0, v0, v1
	v_mov_b32_e32 v1, v0
	v_mov_b32_e32 v210, v0
	s_nop 1
	v_permlane32_swap_b32_e32 v1, v210
	v_cndmask_b32_e64 v1, v210, v1, s[98:99]
	s_waitcnt lgkmcnt(0)
	v_add_f32_e32 v0, v0, v1
	v_fmamk_f32 v2, v0, 0xbc800000, v165
	v_fmamk_f32 v4, v0, 0xbc800000, v167
	v_fmamk_f32 v1, v0, 0xbc800000, v164
	v_fmamk_f32 v3, v0, 0xbc800000, v166
	v_mul_f32_e32 v4, v4, v4
	v_mul_f32_e32 v2, v2, v2
	v_fmac_f32_e32 v4, v3, v3
	v_fmac_f32_e32 v2, v1, v1
	v_fmamk_f32 v3, v0, 0xbc800000, v43
	v_fmamk_f32 v5, v0, 0xbc800000, v45
	v_add_f32_e32 v1, v4, v2
	v_fmamk_f32 v2, v0, 0xbc800000, v42
	v_fmamk_f32 v4, v0, 0xbc800000, v44
	v_mul_f32_e32 v5, v5, v5
	v_mul_f32_e32 v3, v3, v3
	v_fmac_f32_e32 v5, v4, v4
	v_fmac_f32_e32 v3, v2, v2
	v_add_f32_e32 v2, v5, v3
	v_fmamk_f32 v3, v0, 0xbc800000, v39
	v_fmamk_f32 v5, v0, 0xbc800000, v37
	v_add_f32_e32 v1, v1, v2
	v_fmamk_f32 v2, v0, 0xbc800000, v38
	v_fmamk_f32 v4, v0, 0xbc800000, v36
	v_mul_f32_e32 v5, v5, v5
	v_mul_f32_e32 v3, v3, v3
	v_fmac_f32_e32 v5, v4, v4
	v_fmac_f32_e32 v3, v2, v2
	v_add_f32_e32 v2, v5, v3
	v_fmamk_f32 v3, v0, 0xbc800000, v35
	v_fmamk_f32 v5, v0, 0xbc800000, v33
	v_add_f32_e32 v1, v2, v1
	v_fmamk_f32 v2, v0, 0xbc800000, v34
	v_fmamk_f32 v4, v0, 0xbc800000, v32
	v_mul_f32_e32 v5, v5, v5
	v_mul_f32_e32 v3, v3, v3
	v_fmac_f32_e32 v5, v4, v4
	v_fmac_f32_e32 v3, v2, v2
	v_add_f32_e32 v2, v5, v3
	v_add_f32_e32 v1, v2, v1
	v_mov_b32_e32 v2, v1
	v_mov_b32_e32 v210, v1
	s_nop 1
	v_permlane16_swap_b32_e32 v2, v210
	v_cndmask_b32_e64 v2, v210, v2, s[100:101]
	s_waitcnt lgkmcnt(0)
	v_add_f32_e32 v1, v1, v2
	v_mov_b32_e32 v2, v1
	v_mov_b32_e32 v210, v1
	s_nop 1
	v_permlane32_swap_b32_e32 v2, v210
	v_cndmask_b32_e64 v2, v210, v2, s[98:99]
	s_and_saveexec_b64 s[8:9], vcc
	s_cbranch_execz .LBB0_867
	s_lshl_b32 s3, s24, 11
	s_add_i32 s11, s11, s3
	v_mul_f32_e32 v0, 0x3c800000, v0
	s_waitcnt lgkmcnt(0)
	v_add_f32_e32 v1, v1, v2
	v_lshl_add_u32 v2, v178, 5, s11
	ds_write_b64 v2, v[0:1] offset:5632

.LBB0_1003:
	v_lshl_add_u64 v[20:21], v[160:161], 2, s[18:19]
	global_load_dwordx4 v[196:199], v[20:21], off
	global_load_dwordx4 v[200:203], v[20:21], off offset:64
	global_load_dwordx4 v[204:207], v[20:21], off offset:512
	global_load_dwordx4 v[208:211], v[20:21], off offset:576
	s_mov_b32 s8, 0x3a800000
	s_lshl_b32 s10, s23, 5
	v_readlane_b32 s3, v254, 17
	s_add_i32 s3, s3, s10
	s_lshl_b32 s11, s5, 2
	v_cmp_gt_u32_e32 vcc, 16, v178
	s_waitcnt vmcnt(0)
	v_pk_mul_f32 v[174:175], v[198:199], s[8:9] op_sel_hi:[1,0]
	v_pk_mul_f32 v[176:177], v[196:197], s[8:9] op_sel_hi:[1,0]
	v_pk_mul_f32 v[170:171], v[202:203], s[8:9] op_sel_hi:[1,0]
	v_pk_mul_f32 v[172:173], v[200:201], s[8:9] op_sel_hi:[1,0]
	v_pk_mul_f32 v[166:167], v[206:207], s[8:9] op_sel_hi:[1,0]
	v_pk_mul_f32 v[168:169], v[204:205], s[8:9] op_sel_hi:[1,0]
	v_mbcnt_lo_u32_b32 v30, -1, 0
	v_mbcnt_hi_u32_b32 v30, -1, v30
	v_pk_mul_f32 v[164:165], v[208:209], s[8:9] op_sel_hi:[1,0]
	v_pk_mul_f32 v[162:163], v[210:211], s[8:9] op_sel_hi:[1,0]
	v_ashrrev_i32_e32 v31, 5, v30
	v_add_u32_e32 v16, s3, v31
	v_and_b32_e32 v180, 31, v30
	v_ashrrev_i32_e32 v17, 31, v16
	v_readlane_b32 s8, v253, 47
	v_lshlrev_b64 v[16:17], 11, v[16:17]
	v_readlane_b32 s9, v253, 48
	s_lshl_b32 s3, s23, 14
	v_bitop3_b32 v18, v31, v180, 15 bitop3:0x6c
	v_lshl_add_u64 v[16:17], s[8:9], 0, v[16:17]
	s_add_i32 s3, s3, 0
	v_lshlrev_b32_e32 v230, 4, v18
	v_lshl_add_u64 v[18:19], v[16:17], 0, v[230:231]
	s_mov_b32 m0, s3
	s_mov_b64 s[8:9], 0x1000
	global_load_lds_dwordx4 v[18:19], off
	v_lshl_add_u64 v[18:19], v[16:17], 0, s[8:9]
	v_add_u32_e32 v16, 2, v31
	v_bitop3_b32 v16, v16, v180, 15 bitop3:0x6c
	v_lshlrev_b32_e32 v16, 4, v16
	v_mov_b32_e32 v17, v231
	s_add_i32 m0, s3, 0x400
	v_lshl_add_u64 v[20:21], v[18:19], 0, v[16:17]
	global_load_lds_dwordx4 v[20:21], off
	v_lshl_add_u64 v[20:21], v[18:19], 0, s[8:9]
	v_add_u32_e32 v18, 4, v31
	v_bitop3_b32 v18, v18, v180, 15 bitop3:0x6c
	v_lshlrev_b32_e32 v18, 4, v18
	v_mov_b32_e32 v19, v231
	s_add_i32 m0, s3, 0x800
	v_lshl_add_u64 v[22:23], v[20:21], 0, v[18:19]
	global_load_lds_dwordx4 v[22:23], off
	v_lshl_add_u64 v[22:23], v[20:21], 0, s[8:9]
	v_add_u32_e32 v20, 6, v31
	v_bitop3_b32 v20, v20, v180, 15 bitop3:0x6c
	v_lshlrev_b32_e32 v20, 4, v20
	v_mov_b32_e32 v21, v231
	s_add_i32 m0, s3, 0xc00
	v_lshl_add_u64 v[24:25], v[22:23], 0, v[20:21]
	global_load_lds_dwordx4 v[24:25], off
	v_lshl_add_u64 v[24:25], v[22:23], 0, s[8:9]
	v_xor_b32_e32 v22, 0x80, v230
	v_mov_b32_e32 v23, v231
	s_add_i32 m0, s3, 0x1000
	v_lshl_add_u64 v[26:27], v[24:25], 0, v[22:23]
	global_load_lds_dwordx4 v[26:27], off
	v_lshl_add_u64 v[26:27], v[24:25], 0, s[8:9]
	v_add_u32_e32 v24, 10, v31
	v_bitop3_b32 v24, v24, v180, 15 bitop3:0x6c
	v_lshlrev_b32_e32 v24, 4, v24
	v_mov_b32_e32 v25, v231
	s_add_i32 m0, s3, 0x1400
	v_lshl_add_u64 v[28:29], v[26:27], 0, v[24:25]
	global_load_lds_dwordx4 v[28:29], off
	v_add_u32_e32 v28, 12, v31
	v_lshl_add_u64 v[26:27], v[26:27], 0, s[8:9]
	v_bitop3_b32 v28, v28, v180, 15 bitop3:0x6c
	v_lshlrev_b32_e32 v28, 4, v28
	v_mov_b32_e32 v29, v231
	v_add_u32_e32 v181, 14, v31
	v_lshl_add_u64 v[182:183], v[26:27], 0, v[28:29]
	s_add_i32 m0, s3, 0x1800
	v_lshl_add_u64 v[26:27], v[26:27], 0, s[8:9]
	v_bitop3_b32 v180, v181, v180, 15 bitop3:0x6c
	global_load_lds_dwordx4 v[182:183], off
	v_lshlrev_b32_e32 v180, 4, v180
	v_mov_b32_e32 v181, v231
	v_lshl_add_u64 v[182:183], v[26:27], 0, v[180:181]
	s_add_i32 m0, s3, 0x1c00
	v_lshl_add_u64 v[26:27], v[26:27], 0, s[8:9]
	global_load_lds_dwordx4 v[182:183], off
	s_add_i32 m0, s3, 0x2000
	v_lshl_add_u64 v[182:183], v[26:27], 0, v[230:231]
	v_lshl_add_u64 v[26:27], v[26:27], 0, s[8:9]
	global_load_lds_dwordx4 v[182:183], off
	s_add_i32 m0, s3, 0x2400
	v_lshl_add_u64 v[16:17], v[26:27], 0, v[16:17]
	global_load_lds_dwordx4 v[16:17], off
	v_lshl_add_u64 v[16:17], v[26:27], 0, s[8:9]
	s_add_i32 m0, s3, 0x2800
	v_lshl_add_u64 v[18:19], v[16:17], 0, v[18:19]
	v_lshl_add_u64 v[16:17], v[16:17], 0, s[8:9]
	global_load_lds_dwordx4 v[18:19], off
	s_add_i32 m0, s3, 0x2c00
	v_lshl_add_u64 v[18:19], v[16:17], 0, v[20:21]
	v_lshl_add_u64 v[16:17], v[16:17], 0, s[8:9]
	global_load_lds_dwordx4 v[18:19], off
	s_add_i32 m0, s3, 0x3000
	v_lshl_add_u64 v[18:19], v[16:17], 0, v[22:23]
	v_lshl_add_u64 v[16:17], v[16:17], 0, s[8:9]
	global_load_lds_dwordx4 v[18:19], off
	s_add_i32 m0, s3, 0x3400
	v_lshl_add_u64 v[18:19], v[16:17], 0, v[24:25]
	v_lshl_add_u64 v[16:17], v[16:17], 0, s[8:9]
	global_load_lds_dwordx4 v[18:19], off
	s_add_i32 m0, s3, 0x3800
	v_lshl_add_u64 v[18:19], v[16:17], 0, v[28:29]
	v_lshl_add_u64 v[16:17], v[16:17], 0, s[8:9]
	global_load_lds_dwordx4 v[18:19], off
	s_add_i32 m0, s3, 0x3c00
	v_lshl_add_u64 v[18:19], v[16:17], 0, v[180:181]
	v_lshl_add_u64 v[16:17], v[16:17], 0, s[8:9]
	global_load_lds_dwordx4 v[18:19], off
	v_lshrrev_b32_e32 v18, 1, v30
	v_lshlrev_b32_e32 v17, 9, v30
	v_and_b32_e32 v17, 0x200, v17
	v_and_b32_e32 v18, 8, v18
	v_add_u32_e32 v28, s11, v31
	v_and_b32_e32 v16, 15, v30
	v_add3_u32 v183, 0, v17, v18
	v_add_u32_e32 v17, 16, v28
	v_bitop3_b32 v17, v17, v30, 15 bitop3:0x78
	s_lshl_b32 s3, s22, 15
	v_lshlrev_b32_e32 v16, 9, v16
	v_lshlrev_b32_e32 v180, 4, v17
	v_or_b32_e32 v184, s3, v16
	v_mov_b32_e32 v17, s3
	s_movk_i32 s3, 0x9c00
	v_bitop3_b32 v16, v16, s3, v17 bitop3:0xc8
	v_add_u32_e32 v181, v183, v16
	v_bitop3_b32 v16, v28, v30, 15 bitop3:0x78
	v_lshlrev_b32_e32 v182, 4, v16
	s_waitcnt vmcnt(0)
	s_barrier
	v_add_u32_e32 v185, v181, v182
	ds_read_b64 v[16:17], v185
	s_mov_b32 s8, 0x3fd744fd
	s_lshl_b32 s3, s5, 3
	s_add_i32 s12, s3, 0
	s_waitcnt lgkmcnt(0)
	v_cvt_f32_f16_e32 v18, v16
	v_cvt_f32_f16_sdwa v19, v16 dst_sel:DWORD dst_unused:UNUSED_PAD src0_sel:WORD_1
	v_cvt_f32_f16_e32 v16, v17
	v_cvt_f32_f16_sdwa v17, v17 dst_sel:DWORD dst_unused:UNUSED_PAD src0_sel:WORD_1
	v_pk_mul_f32 v[20:21], v[18:19], s[8:9] op_sel_hi:[1,0]
	v_pk_mul_f32 v[16:17], v[16:17], s[8:9] op_sel_hi:[1,0]
	s_nop 0
	v_pk_fma_f32 v[18:19], v[158:159], v[174:175], v[16:17]
	v_pk_fma_f32 v[16:17], v[156:157], v[176:177], v[20:21]
	v_add_u32_e32 v20, 2, v28
	v_bitop3_b32 v20, v20, v30, 15 bitop3:0x78
	v_lshlrev_b32_e32 v156, 4, v20
	v_add_u32_e32 v157, v181, v156
	ds_read_b64 v[20:21], v157
	s_waitcnt lgkmcnt(0)
	v_cvt_f32_f16_e32 v22, v20
	v_cvt_f32_f16_sdwa v23, v20 dst_sel:DWORD dst_unused:UNUSED_PAD src0_sel:WORD_1
	v_cvt_f32_f16_e32 v20, v21
	v_cvt_f32_f16_sdwa v21, v21 dst_sel:DWORD dst_unused:UNUSED_PAD src0_sel:WORD_1
	v_pk_mul_f32 v[22:23], v[22:23], s[8:9] op_sel_hi:[1,0]
	s_nop 0
	v_pk_fma_f32 v[24:25], v[152:153], v[172:173], v[22:23]
	v_pk_mul_f32 v[20:21], v[20:21], s[8:9] op_sel_hi:[1,0]
	v_add_u32_e32 v153, v181, v180
	v_pk_fma_f32 v[26:27], v[154:155], v[170:171], v[20:21]
	ds_read_b64 v[20:21], v153
	s_waitcnt lgkmcnt(0)
	v_cvt_f32_f16_e32 v22, v20
	v_cvt_f32_f16_sdwa v23, v20 dst_sel:DWORD dst_unused:UNUSED_PAD src0_sel:WORD_1
	v_cvt_f32_f16_e32 v20, v21
	v_cvt_f32_f16_sdwa v21, v21 dst_sel:DWORD dst_unused:UNUSED_PAD src0_sel:WORD_1
	v_pk_mul_f32 v[22:23], v[22:23], s[8:9] op_sel_hi:[1,0]
	s_nop 0
	v_pk_fma_f32 v[148:149], v[148:149], v[168:169], v[22:23]
	v_pk_mul_f32 v[20:21], v[20:21], s[8:9] op_sel_hi:[1,0]
	s_nop 0
	v_pk_fma_f32 v[150:151], v[150:151], v[166:167], v[20:21]
	v_add_u32_e32 v20, 18, v28
	v_bitop3_b32 v20, v20, v30, 15 bitop3:0x78
	v_lshlrev_b32_e32 v152, 4, v20
	v_add_u32_e32 v154, v181, v152
	ds_read_b64 v[20:21], v154
	s_waitcnt lgkmcnt(0)
	v_cvt_f32_f16_e32 v22, v20
	v_cvt_f32_f16_sdwa v23, v20 dst_sel:DWORD dst_unused:UNUSED_PAD src0_sel:WORD_1
	v_cvt_f32_f16_e32 v20, v21
	v_cvt_f32_f16_sdwa v21, v21 dst_sel:DWORD dst_unused:UNUSED_PAD src0_sel:WORD_1
	v_pk_mul_f32 v[22:23], v[22:23], s[8:9] op_sel_hi:[1,0]
	s_nop 0
	v_pk_fma_f32 v[144:145], v[144:145], v[164:165], v[22:23]
	v_pk_mul_f32 v[20:21], v[20:21], s[8:9] op_sel_hi:[1,0]
	s_nop 0
	v_pk_fma_f32 v[146:147], v[146:147], v[162:163], v[20:21]
	s_nop 0
	ds_read_b64 v[20:21], v185 offset:8192
	s_waitcnt lgkmcnt(0)
	v_cvt_f32_f16_e32 v22, v20
	v_cvt_f32_f16_sdwa v23, v20 dst_sel:DWORD dst_unused:UNUSED_PAD src0_sel:WORD_1
	v_cvt_f32_f16_e32 v20, v21
	v_cvt_f32_f16_sdwa v21, v21 dst_sel:DWORD dst_unused:UNUSED_PAD src0_sel:WORD_1
	v_pk_mul_f32 v[28:29], v[22:23], s[8:9] op_sel_hi:[1,0]
	v_pk_mul_f32 v[20:21], v[20:21], s[8:9] op_sel_hi:[1,0]
	s_nop 0
	v_pk_fma_f32 v[22:23], v[142:143], v[174:175], v[20:21]
	v_pk_fma_f32 v[20:21], v[140:141], v[176:177], v[28:29]
	ds_read_b64 v[28:29], v157 offset:8192
	v_pk_add_f32 v[142:143], v[0:1], v[24:25]
	v_lshlrev_b32_e32 v24, 2, v178
	s_waitcnt lgkmcnt(0)
	v_cvt_f32_f16_e32 v30, v28
	v_cvt_f32_f16_sdwa v31, v28 dst_sel:DWORD dst_unused:UNUSED_PAD src0_sel:WORD_1
	v_cvt_f32_f16_e32 v28, v29
	v_cvt_f32_f16_sdwa v29, v29 dst_sel:DWORD dst_unused:UNUSED_PAD src0_sel:WORD_1
	v_pk_mul_f32 v[140:141], v[30:31], s[8:9] op_sel_hi:[1,0]
	v_pk_mul_f32 v[28:29], v[28:29], s[8:9] op_sel_hi:[1,0]
	s_nop 0
	v_pk_fma_f32 v[30:31], v[138:139], v[170:171], v[28:29]
	v_pk_fma_f32 v[28:29], v[136:137], v[172:173], v[140:141]
	ds_read_b64 v[136:137], v153 offset:8192
	v_add_u32_e32 v140, 0x10000, v181
	s_waitcnt lgkmcnt(0)
	v_cvt_f32_f16_e32 v138, v136
	v_cvt_f32_f16_sdwa v139, v136 dst_sel:DWORD dst_unused:UNUSED_PAD src0_sel:WORD_1
	v_cvt_f32_f16_e32 v136, v137
	v_cvt_f32_f16_sdwa v137, v137 dst_sel:DWORD dst_unused:UNUSED_PAD src0_sel:WORD_1
	v_pk_mul_f32 v[138:139], v[138:139], s[8:9] op_sel_hi:[1,0]
	s_nop 0
	v_pk_fma_f32 v[132:133], v[132:133], v[168:169], v[138:139]
	v_pk_mul_f32 v[136:137], v[136:137], s[8:9] op_sel_hi:[1,0]
	s_nop 0
	v_pk_fma_f32 v[134:135], v[134:135], v[166:167], v[136:137]
	ds_read_b64 v[136:137], v154 offset:8192
	s_waitcnt lgkmcnt(0)
	v_cvt_f32_f16_e32 v138, v136
	v_cvt_f32_f16_sdwa v139, v136 dst_sel:DWORD dst_unused:UNUSED_PAD src0_sel:WORD_1
	v_cvt_f32_f16_e32 v136, v137
	v_cvt_f32_f16_sdwa v137, v137 dst_sel:DWORD dst_unused:UNUSED_PAD src0_sel:WORD_1
	v_pk_mul_f32 v[138:139], v[138:139], s[8:9] op_sel_hi:[1,0]
	s_nop 0
	v_pk_fma_f32 v[128:129], v[128:129], v[164:165], v[138:139]
	v_pk_mul_f32 v[136:137], v[136:137], s[8:9] op_sel_hi:[1,0]
	s_nop 0
	v_pk_fma_f32 v[130:131], v[130:131], v[162:163], v[136:137]
	s_nop 0
	ds_read_b64 v[136:137], v185 offset:16384
	s_waitcnt lgkmcnt(0)
	v_cvt_f32_f16_e32 v138, v136
	v_cvt_f32_f16_sdwa v139, v136 dst_sel:DWORD dst_unused:UNUSED_PAD src0_sel:WORD_1
	v_cvt_f32_f16_e32 v136, v137
	v_cvt_f32_f16_sdwa v137, v137 dst_sel:DWORD dst_unused:UNUSED_PAD src0_sel:WORD_1
	v_pk_mul_f32 v[138:139], v[138:139], s[8:9] op_sel_hi:[1,0]
	s_nop 0
	v_pk_fma_f32 v[124:125], v[124:125], v[176:177], v[138:139]
	v_pk_mul_f32 v[136:137], v[136:137], s[8:9] op_sel_hi:[1,0]
	s_nop 0
	v_pk_fma_f32 v[126:127], v[126:127], v[174:175], v[136:137]
	ds_read_b64 v[136:137], v157 offset:16384
	s_waitcnt lgkmcnt(0)
	v_cvt_f32_f16_e32 v138, v136
	v_cvt_f32_f16_sdwa v139, v136 dst_sel:DWORD dst_unused:UNUSED_PAD src0_sel:WORD_1
	v_cvt_f32_f16_e32 v136, v137
	v_cvt_f32_f16_sdwa v137, v137 dst_sel:DWORD dst_unused:UNUSED_PAD src0_sel:WORD_1
	v_pk_mul_f32 v[138:139], v[138:139], s[8:9] op_sel_hi:[1,0]
	s_nop 0
	v_pk_fma_f32 v[120:121], v[120:121], v[172:173], v[138:139]
	v_pk_mul_f32 v[136:137], v[136:137], s[8:9] op_sel_hi:[1,0]
	s_nop 0
	v_pk_fma_f32 v[122:123], v[122:123], v[170:171], v[136:137]
	ds_read_b64 v[136:137], v153 offset:16384
	s_waitcnt lgkmcnt(0)
	v_cvt_f32_f16_e32 v138, v136
	v_cvt_f32_f16_sdwa v139, v136 dst_sel:DWORD dst_unused:UNUSED_PAD src0_sel:WORD_1
	v_cvt_f32_f16_e32 v136, v137
	v_cvt_f32_f16_sdwa v137, v137 dst_sel:DWORD dst_unused:UNUSED_PAD src0_sel:WORD_1
	v_pk_mul_f32 v[138:139], v[138:139], s[8:9] op_sel_hi:[1,0]
	s_nop 0
	v_pk_fma_f32 v[116:117], v[116:117], v[168:169], v[138:139]
	v_pk_mul_f32 v[136:137], v[136:137], s[8:9] op_sel_hi:[1,0]
	s_nop 0
	v_pk_fma_f32 v[118:119], v[118:119], v[166:167], v[136:137]
	ds_read_b64 v[136:137], v154 offset:16384
	s_waitcnt lgkmcnt(0)
	v_cvt_f32_f16_e32 v138, v136
	v_cvt_f32_f16_sdwa v139, v136 dst_sel:DWORD dst_unused:UNUSED_PAD src0_sel:WORD_1
	v_cvt_f32_f16_e32 v136, v137
	v_cvt_f32_f16_sdwa v137, v137 dst_sel:DWORD dst_unused:UNUSED_PAD src0_sel:WORD_1
	v_pk_mul_f32 v[138:139], v[138:139], s[8:9] op_sel_hi:[1,0]
	s_nop 0
	v_pk_fma_f32 v[112:113], v[112:113], v[164:165], v[138:139]
	v_pk_mul_f32 v[136:137], v[136:137], s[8:9] op_sel_hi:[1,0]
	s_nop 0
	v_pk_fma_f32 v[114:115], v[114:115], v[162:163], v[136:137]
	s_nop 0
	ds_read_b64 v[136:137], v185 offset:24576
	s_waitcnt lgkmcnt(0)
	v_cvt_f32_f16_e32 v138, v136
	v_cvt_f32_f16_sdwa v139, v136 dst_sel:DWORD dst_unused:UNUSED_PAD src0_sel:WORD_1
	v_cvt_f32_f16_e32 v136, v137
	v_cvt_f32_f16_sdwa v137, v137 dst_sel:DWORD dst_unused:UNUSED_PAD src0_sel:WORD_1
	v_pk_mul_f32 v[138:139], v[138:139], s[8:9] op_sel_hi:[1,0]
	s_nop 0
	v_pk_fma_f32 v[108:109], v[108:109], v[176:177], v[138:139]
	v_pk_mul_f32 v[136:137], v[136:137], s[8:9] op_sel_hi:[1,0]
	s_nop 0
	v_pk_fma_f32 v[110:111], v[110:111], v[174:175], v[136:137]
	ds_read_b64 v[136:137], v157 offset:24576
	v_xor_b32_e32 v157, 64, v24
	s_waitcnt lgkmcnt(0)
	v_cvt_f32_f16_e32 v138, v136
	v_cvt_f32_f16_sdwa v139, v136 dst_sel:DWORD dst_unused:UNUSED_PAD src0_sel:WORD_1
	v_cvt_f32_f16_e32 v136, v137
	v_cvt_f32_f16_sdwa v137, v137 dst_sel:DWORD dst_unused:UNUSED_PAD src0_sel:WORD_1
	v_pk_mul_f32 v[138:139], v[138:139], s[8:9] op_sel_hi:[1,0]
	s_nop 0
	v_pk_fma_f32 v[104:105], v[104:105], v[172:173], v[138:139]
	v_pk_mul_f32 v[136:137], v[136:137], s[8:9] op_sel_hi:[1,0]
	s_nop 0
	v_pk_fma_f32 v[106:107], v[106:107], v[170:171], v[136:137]
	ds_read_b64 v[136:137], v153 offset:24576
	s_waitcnt lgkmcnt(0)
	v_cvt_f32_f16_e32 v138, v136
	v_cvt_f32_f16_sdwa v139, v136 dst_sel:DWORD dst_unused:UNUSED_PAD src0_sel:WORD_1
	v_cvt_f32_f16_e32 v136, v137
	v_cvt_f32_f16_sdwa v137, v137 dst_sel:DWORD dst_unused:UNUSED_PAD src0_sel:WORD_1
	v_pk_mul_f32 v[138:139], v[138:139], s[8:9] op_sel_hi:[1,0]
	s_nop 0
	v_pk_fma_f32 v[100:101], v[100:101], v[168:169], v[138:139]
	v_pk_mul_f32 v[136:137], v[136:137], s[8:9] op_sel_hi:[1,0]
	s_nop 0
	v_pk_fma_f32 v[102:103], v[102:103], v[166:167], v[136:137]
	ds_read_b64 v[136:137], v154 offset:24576
	v_pk_add_f32 v[154:155], v[4:5], v[16:17]
	v_pk_add_f32 v[16:17], v[10:11], v[146:147]
	s_waitcnt lgkmcnt(0)
	v_cvt_f32_f16_e32 v138, v136
	v_cvt_f32_f16_sdwa v139, v136 dst_sel:DWORD dst_unused:UNUSED_PAD src0_sel:WORD_1
	v_cvt_f32_f16_e32 v136, v137
	v_cvt_f32_f16_sdwa v137, v137 dst_sel:DWORD dst_unused:UNUSED_PAD src0_sel:WORD_1
	v_pk_mul_f32 v[138:139], v[138:139], s[8:9] op_sel_hi:[1,0]
	s_nop 0
	v_pk_fma_f32 v[96:97], v[96:97], v[164:165], v[138:139]
	v_pk_mul_f32 v[136:137], v[136:137], s[8:9] op_sel_hi:[1,0]
	s_nop 0
	v_pk_fma_f32 v[98:99], v[98:99], v[162:163], v[136:137]
	v_add_u32_e32 v136, v140, v182
	ds_read_b64 v[136:137], v136
	s_waitcnt lgkmcnt(0)
	v_cvt_f32_f16_e32 v138, v136
	v_cvt_f32_f16_sdwa v139, v136 dst_sel:DWORD dst_unused:UNUSED_PAD src0_sel:WORD_1
	v_cvt_f32_f16_e32 v136, v137
	v_cvt_f32_f16_sdwa v137, v137 dst_sel:DWORD dst_unused:UNUSED_PAD src0_sel:WORD_1
	v_pk_mul_f32 v[138:139], v[138:139], s[8:9] op_sel_hi:[1,0]
	s_nop 0
	v_pk_fma_f32 v[92:93], v[92:93], v[176:177], v[138:139]
	v_pk_mul_f32 v[136:137], v[136:137], s[8:9] op_sel_hi:[1,0]
	s_nop 0
	v_pk_fma_f32 v[94:95], v[94:95], v[174:175], v[136:137]
	v_add_u32_e32 v136, v140, v156
	ds_read_b64 v[136:137], v136
	s_waitcnt lgkmcnt(0)
	v_cvt_f32_f16_e32 v138, v136
	v_cvt_f32_f16_sdwa v139, v136 dst_sel:DWORD dst_unused:UNUSED_PAD src0_sel:WORD_1
	v_cvt_f32_f16_e32 v136, v137
	v_cvt_f32_f16_sdwa v137, v137 dst_sel:DWORD dst_unused:UNUSED_PAD src0_sel:WORD_1
	v_pk_mul_f32 v[138:139], v[138:139], s[8:9] op_sel_hi:[1,0]
	s_nop 0
	v_pk_fma_f32 v[88:89], v[88:89], v[172:173], v[138:139]
	v_pk_mul_f32 v[136:137], v[136:137], s[8:9] op_sel_hi:[1,0]
	s_nop 0
	v_pk_fma_f32 v[90:91], v[90:91], v[170:171], v[136:137]
	v_add_u32_e32 v136, v140, v180
	ds_read_b64 v[136:137], v136
	s_waitcnt lgkmcnt(0)
	v_cvt_f32_f16_e32 v138, v136
	v_cvt_f32_f16_sdwa v139, v136 dst_sel:DWORD dst_unused:UNUSED_PAD src0_sel:WORD_1
	v_cvt_f32_f16_e32 v136, v137
	v_cvt_f32_f16_sdwa v137, v137 dst_sel:DWORD dst_unused:UNUSED_PAD src0_sel:WORD_1
	v_pk_mul_f32 v[138:139], v[138:139], s[8:9] op_sel_hi:[1,0]
	s_nop 0
	v_pk_fma_f32 v[84:85], v[84:85], v[168:169], v[138:139]
	v_pk_mul_f32 v[136:137], v[136:137], s[8:9] op_sel_hi:[1,0]
	s_nop 0
	v_pk_fma_f32 v[86:87], v[86:87], v[166:167], v[136:137]
	v_add_u32_e32 v136, v140, v152
	ds_read_b64 v[136:137], v136
	s_waitcnt lgkmcnt(0)
	v_cvt_f32_f16_e32 v138, v136
	v_cvt_f32_f16_sdwa v139, v136 dst_sel:DWORD dst_unused:UNUSED_PAD src0_sel:WORD_1
	v_cvt_f32_f16_e32 v136, v137
	v_cvt_f32_f16_sdwa v137, v137 dst_sel:DWORD dst_unused:UNUSED_PAD src0_sel:WORD_1
	v_pk_mul_f32 v[138:139], v[138:139], s[8:9] op_sel_hi:[1,0]
	s_nop 0
	v_pk_fma_f32 v[80:81], v[80:81], v[164:165], v[138:139]
	v_pk_mul_f32 v[136:137], v[136:137], s[8:9] op_sel_hi:[1,0]
	s_nop 0
	v_pk_fma_f32 v[82:83], v[82:83], v[162:163], v[136:137]
	v_add_u32_e32 v136, 0x12000, v184
	v_and_b32_e32 v136, 0xffffbc00, v136
	v_add_u32_e32 v140, v183, v136
	v_add_u32_e32 v136, v140, v182
	ds_read_b64 v[136:137], v136
	s_waitcnt lgkmcnt(0)
	v_cvt_f32_f16_e32 v138, v136
	v_cvt_f32_f16_sdwa v139, v136 dst_sel:DWORD dst_unused:UNUSED_PAD src0_sel:WORD_1
	v_cvt_f32_f16_e32 v136, v137
	v_cvt_f32_f16_sdwa v137, v137 dst_sel:DWORD dst_unused:UNUSED_PAD src0_sel:WORD_1
	v_pk_mul_f32 v[138:139], v[138:139], s[8:9] op_sel_hi:[1,0]
	s_nop 0
	v_pk_fma_f32 v[76:77], v[76:77], v[176:177], v[138:139]
	v_pk_mul_f32 v[136:137], v[136:137], s[8:9] op_sel_hi:[1,0]
	s_nop 0
	v_pk_fma_f32 v[78:79], v[78:79], v[174:175], v[136:137]
	v_add_u32_e32 v136, v140, v156
	ds_read_b64 v[136:137], v136
	s_waitcnt lgkmcnt(0)
	v_cvt_f32_f16_e32 v138, v136
	v_cvt_f32_f16_sdwa v139, v136 dst_sel:DWORD dst_unused:UNUSED_PAD src0_sel:WORD_1
	v_cvt_f32_f16_e32 v136, v137
	v_cvt_f32_f16_sdwa v137, v137 dst_sel:DWORD dst_unused:UNUSED_PAD src0_sel:WORD_1
	v_pk_mul_f32 v[138:139], v[138:139], s[8:9] op_sel_hi:[1,0]
	s_nop 0
	v_pk_fma_f32 v[72:73], v[72:73], v[172:173], v[138:139]
	v_pk_mul_f32 v[136:137], v[136:137], s[8:9] op_sel_hi:[1,0]
	s_nop 0
	v_pk_fma_f32 v[74:75], v[74:75], v[170:171], v[136:137]
	v_add_u32_e32 v136, v140, v180
	ds_read_b64 v[136:137], v136
	s_waitcnt lgkmcnt(0)
	v_cvt_f32_f16_e32 v138, v136
	v_cvt_f32_f16_sdwa v139, v136 dst_sel:DWORD dst_unused:UNUSED_PAD src0_sel:WORD_1
	v_cvt_f32_f16_e32 v136, v137
	v_cvt_f32_f16_sdwa v137, v137 dst_sel:DWORD dst_unused:UNUSED_PAD src0_sel:WORD_1
	v_pk_mul_f32 v[138:139], v[138:139], s[8:9] op_sel_hi:[1,0]
	s_nop 0
	v_pk_fma_f32 v[68:69], v[68:69], v[168:169], v[138:139]
	v_pk_mul_f32 v[136:137], v[136:137], s[8:9] op_sel_hi:[1,0]
	s_nop 0
	v_pk_fma_f32 v[70:71], v[70:71], v[166:167], v[136:137]
	v_add_u32_e32 v136, v140, v152
	ds_read_b64 v[136:137], v136
	v_add_u32_e32 v140, 0x14000, v181
	s_waitcnt lgkmcnt(0)
	v_cvt_f32_f16_e32 v138, v136
	v_cvt_f32_f16_sdwa v139, v136 dst_sel:DWORD dst_unused:UNUSED_PAD src0_sel:WORD_1
	v_cvt_f32_f16_e32 v136, v137
	v_cvt_f32_f16_sdwa v137, v137 dst_sel:DWORD dst_unused:UNUSED_PAD src0_sel:WORD_1
	v_pk_mul_f32 v[138:139], v[138:139], s[8:9] op_sel_hi:[1,0]
	s_nop 0
	v_pk_fma_f32 v[64:65], v[64:65], v[164:165], v[138:139]
	v_pk_mul_f32 v[136:137], v[136:137], s[8:9] op_sel_hi:[1,0]
	s_nop 0
	v_pk_fma_f32 v[66:67], v[66:67], v[162:163], v[136:137]
	v_add_u32_e32 v136, v140, v182
	ds_read_b64 v[136:137], v136
	s_waitcnt lgkmcnt(0)
	v_cvt_f32_f16_e32 v138, v136
	v_cvt_f32_f16_sdwa v139, v136 dst_sel:DWORD dst_unused:UNUSED_PAD src0_sel:WORD_1
	v_cvt_f32_f16_e32 v136, v137
	v_cvt_f32_f16_sdwa v137, v137 dst_sel:DWORD dst_unused:UNUSED_PAD src0_sel:WORD_1
	v_pk_mul_f32 v[138:139], v[138:139], s[8:9] op_sel_hi:[1,0]
	s_nop 0
	v_pk_fma_f32 v[60:61], v[60:61], v[176:177], v[138:139]
	v_pk_mul_f32 v[136:137], v[136:137], s[8:9] op_sel_hi:[1,0]
	s_nop 0
	v_pk_fma_f32 v[62:63], v[62:63], v[174:175], v[136:137]
	v_add_u32_e32 v136, v140, v156
	ds_read_b64 v[136:137], v136
	s_waitcnt lgkmcnt(0)
	v_cvt_f32_f16_e32 v138, v136
	v_cvt_f32_f16_sdwa v139, v136 dst_sel:DWORD dst_unused:UNUSED_PAD src0_sel:WORD_1
	v_cvt_f32_f16_e32 v136, v137
	v_cvt_f32_f16_sdwa v137, v137 dst_sel:DWORD dst_unused:UNUSED_PAD src0_sel:WORD_1
	v_pk_mul_f32 v[138:139], v[138:139], s[8:9] op_sel_hi:[1,0]
	s_nop 0
	v_pk_fma_f32 v[56:57], v[56:57], v[172:173], v[138:139]
	v_pk_mul_f32 v[136:137], v[136:137], s[8:9] op_sel_hi:[1,0]
	s_nop 0
	v_pk_fma_f32 v[58:59], v[58:59], v[170:171], v[136:137]
	v_add_u32_e32 v136, v140, v180
	ds_read_b64 v[136:137], v136
	s_waitcnt lgkmcnt(0)
	v_cvt_f32_f16_e32 v138, v136
	v_cvt_f32_f16_sdwa v139, v136 dst_sel:DWORD dst_unused:UNUSED_PAD src0_sel:WORD_1
	v_cvt_f32_f16_e32 v136, v137
	v_cvt_f32_f16_sdwa v137, v137 dst_sel:DWORD dst_unused:UNUSED_PAD src0_sel:WORD_1
	v_pk_mul_f32 v[138:139], v[138:139], s[8:9] op_sel_hi:[1,0]
	s_nop 0
	v_pk_fma_f32 v[52:53], v[52:53], v[168:169], v[138:139]
	v_pk_mul_f32 v[136:137], v[136:137], s[8:9] op_sel_hi:[1,0]
	s_nop 0
	v_pk_fma_f32 v[54:55], v[54:55], v[166:167], v[136:137]
	v_add_u32_e32 v136, v140, v152
	ds_read_b64 v[136:137], v136
	v_add_u32_e32 v140, 0x16000, v181
	s_waitcnt lgkmcnt(0)
	v_cvt_f32_f16_e32 v138, v136
	v_cvt_f32_f16_sdwa v139, v136 dst_sel:DWORD dst_unused:UNUSED_PAD src0_sel:WORD_1
	v_cvt_f32_f16_e32 v136, v137
	v_cvt_f32_f16_sdwa v137, v137 dst_sel:DWORD dst_unused:UNUSED_PAD src0_sel:WORD_1
	v_pk_mul_f32 v[138:139], v[138:139], s[8:9] op_sel_hi:[1,0]
	s_nop 0
	v_pk_fma_f32 v[48:49], v[48:49], v[164:165], v[138:139]
	v_pk_mul_f32 v[136:137], v[136:137], s[8:9] op_sel_hi:[1,0]
	s_nop 0
	v_pk_fma_f32 v[50:51], v[50:51], v[162:163], v[136:137]
	v_add_u32_e32 v136, v140, v182
	ds_read_b64 v[136:137], v136
	s_waitcnt lgkmcnt(0)
	v_cvt_f32_f16_e32 v138, v136
	v_cvt_f32_f16_sdwa v139, v136 dst_sel:DWORD dst_unused:UNUSED_PAD src0_sel:WORD_1
	v_cvt_f32_f16_e32 v136, v137
	v_cvt_f32_f16_sdwa v137, v137 dst_sel:DWORD dst_unused:UNUSED_PAD src0_sel:WORD_1
	v_pk_mul_f32 v[138:139], v[138:139], s[8:9] op_sel_hi:[1,0]
	s_nop 0
	v_pk_fma_f32 v[44:45], v[44:45], v[176:177], v[138:139]
	v_pk_mul_f32 v[136:137], v[136:137], s[8:9] op_sel_hi:[1,0]
	s_nop 0
	v_pk_fma_f32 v[46:47], v[46:47], v[174:175], v[136:137]
	v_add_u32_e32 v136, v140, v156
	ds_read_b64 v[136:137], v136
	v_xor_b32_e32 v156, 0x80, v24
	s_waitcnt lgkmcnt(0)
	v_cvt_f32_f16_e32 v138, v136
	v_cvt_f32_f16_sdwa v139, v136 dst_sel:DWORD dst_unused:UNUSED_PAD src0_sel:WORD_1
	v_cvt_f32_f16_e32 v136, v137
	v_cvt_f32_f16_sdwa v137, v137 dst_sel:DWORD dst_unused:UNUSED_PAD src0_sel:WORD_1
	v_pk_mul_f32 v[138:139], v[138:139], s[8:9] op_sel_hi:[1,0]
	s_nop 0
	v_pk_fma_f32 v[40:41], v[40:41], v[172:173], v[138:139]
	v_pk_mul_f32 v[136:137], v[136:137], s[8:9] op_sel_hi:[1,0]
	s_nop 0
	v_pk_fma_f32 v[42:43], v[42:43], v[170:171], v[136:137]
	v_add_u32_e32 v136, v140, v180
	ds_read_b64 v[136:137], v136
	s_waitcnt lgkmcnt(0)
	v_cvt_f32_f16_e32 v138, v136
	v_cvt_f32_f16_sdwa v139, v136 dst_sel:DWORD dst_unused:UNUSED_PAD src0_sel:WORD_1
	v_cvt_f32_f16_e32 v136, v137
	v_cvt_f32_f16_sdwa v137, v137 dst_sel:DWORD dst_unused:UNUSED_PAD src0_sel:WORD_1
	v_pk_mul_f32 v[138:139], v[138:139], s[8:9] op_sel_hi:[1,0]
	s_nop 0
	v_pk_fma_f32 v[36:37], v[36:37], v[168:169], v[138:139]
	v_pk_mul_f32 v[136:137], v[136:137], s[8:9] op_sel_hi:[1,0]
	s_nop 0
	v_pk_fma_f32 v[38:39], v[38:39], v[166:167], v[136:137]
	v_add_u32_e32 v136, v140, v152
	ds_read_b64 v[136:137], v136
	v_pk_add_f32 v[152:153], v[6:7], v[18:19]
	v_pk_add_f32 v[140:141], v[2:3], v[26:27]
	v_pk_mov_b32 v[24:25], v[154:155], v[152:153] op_sel:[1,0]
	v_mov_b32_e32 v26, v154
	s_waitcnt lgkmcnt(0)
	v_cvt_f32_f16_e32 v138, v136
	v_cvt_f32_f16_sdwa v139, v136 dst_sel:DWORD dst_unused:UNUSED_PAD src0_sel:WORD_1
	v_cvt_f32_f16_e32 v136, v137
	v_cvt_f32_f16_sdwa v137, v137 dst_sel:DWORD dst_unused:UNUSED_PAD src0_sel:WORD_1
	v_mov_b32_e32 v27, v153
	v_pk_add_f32 v[18:19], v[8:9], v[144:145]
	v_pk_add_f32 v[24:25], v[24:25], v[26:27]
	v_pk_mov_b32 v[26:27], v[142:143], v[140:141] op_sel:[1,0]
	v_mov_b32_e32 v144, v142
	v_mov_b32_e32 v145, v141
	v_pk_mul_f32 v[138:139], v[138:139], s[8:9] op_sel_hi:[1,0]
	v_pk_mul_f32 v[136:137], v[136:137], s[8:9] op_sel_hi:[1,0]
	v_pk_add_f32 v[26:27], v[26:27], v[144:145]
	v_pk_fma_f32 v[34:35], v[34:35], v[162:163], v[136:137]
	v_pk_fma_f32 v[32:33], v[32:33], v[164:165], v[138:139]
	v_pk_add_f32 v[136:137], v[14:15], v[150:151]
	v_pk_add_f32 v[138:139], v[12:13], v[148:149]
	v_add_f32_e32 v24, v24, v25
	v_pk_add_f32 v[26:27], v[26:27], v[26:27] op_sel_hi:[0,1]
	v_add_f32_e32 v25, 0, v24
	v_add_f32_e32 v145, v138, v139
	v_add_f32_e32 v147, v136, v137
	v_mov_b32_e32 v144, v18
	v_mov_b32_e32 v146, v19
	v_mov_b32_e32 v26, v16
	v_mov_b32_e32 v24, v17
	v_pk_add_f32 v[144:145], v[144:145], v[146:147]
	v_pk_add_f32 v[24:25], v[26:27], v[24:25]
	s_waitcnt lgkmcnt(0)
	s_barrier
	v_pk_add_f32 v[24:25], v[144:145], v[24:25]
	s_nop 0
	v_add_f32_e32 v24, v24, v25
	s_mov_b32 s100, 0xffff0000
	s_mov_b32 s101, 0xffff0000
	s_mov_b32 s98, 0
	s_mov_b32 s99, -1
	v_mov_b32_e32 v25, v24
	v_mov_b32_e32 v210, v24
	s_nop 1
	v_permlane16_swap_b32_e32 v25, v210
	v_cndmask_b32_e64 v25, v210, v25, s[100:101]
	s_waitcnt lgkmcnt(0)
	v_add_f32_e32 v24, v24, v25
	v_mov_b32_e32 v25, v24
	v_mov_b32_e32 v210, v24
	s_nop 1
	v_permlane32_swap_b32_e32 v25, v210
	v_cndmask_b32_e64 v25, v210, v25, s[98:99]
	s_waitcnt lgkmcnt(0)
	v_add_f32_e32 v24, v24, v25
	v_fmamk_f32 v26, v24, 0xbc800000, v153
	v_fmamk_f32 v144, v24, 0xbc800000, v155
	v_fmamk_f32 v25, v24, 0xbc800000, v152
	v_fmamk_f32 v27, v24, 0xbc800000, v154
	v_mul_f32_e32 v144, v144, v144
	v_mul_f32_e32 v26, v26, v26
	v_fmac_f32_e32 v144, v27, v27
	v_fmac_f32_e32 v26, v25, v25
	v_fmamk_f32 v27, v24, 0xbc800000, v141
	v_fmamk_f32 v145, v24, 0xbc800000, v143
	v_add_f32_e32 v25, v144, v26
	v_fmamk_f32 v26, v24, 0xbc800000, v140
	v_fmamk_f32 v144, v24, 0xbc800000, v142
	v_mul_f32_e32 v145, v145, v145
	v_mul_f32_e32 v27, v27, v27
	v_fmac_f32_e32 v145, v144, v144
	v_fmac_f32_e32 v27, v26, v26
	v_add_f32_e32 v26, v145, v27
	v_fmamk_f32 v27, v24, 0xbc800000, v137
	v_fmamk_f32 v145, v24, 0xbc800000, v139
	v_add_f32_e32 v25, v25, v26
	v_fmamk_f32 v26, v24, 0xbc800000, v136
	v_fmamk_f32 v144, v24, 0xbc800000, v138
	v_mul_f32_e32 v145, v145, v145
	v_mul_f32_e32 v27, v27, v27
	v_fmac_f32_e32 v145, v144, v144
	v_fmac_f32_e32 v27, v26, v26
	v_add_f32_e32 v26, v145, v27
	v_fmamk_f32 v27, v24, 0xbc800000, v17
	v_fmamk_f32 v145, v24, 0xbc800000, v19
	v_add_f32_e32 v25, v26, v25
	v_fmamk_f32 v26, v24, 0xbc800000, v16
	v_fmamk_f32 v144, v24, 0xbc800000, v18
	v_mul_f32_e32 v145, v145, v145
	v_mul_f32_e32 v27, v27, v27
	v_fmac_f32_e32 v145, v144, v144
	v_fmac_f32_e32 v27, v26, v26
	v_add_f32_e32 v26, v145, v27
	v_add_f32_e32 v25, v26, v25
	v_mov_b32_e32 v26, v25
	v_mov_b32_e32 v210, v25
	s_nop 1
	v_permlane16_swap_b32_e32 v26, v210
	v_cndmask_b32_e64 v26, v210, v26, s[100:101]
	s_waitcnt lgkmcnt(0)
	v_add_f32_e32 v25, v25, v26
	v_mov_b32_e32 v26, v25
	v_mov_b32_e32 v210, v25
	s_nop 1
	v_permlane32_swap_b32_e32 v26, v210
	v_cndmask_b32_e64 v26, v210, v26, s[98:99]
	s_and_saveexec_b64 s[8:9], vcc
	s_cbranch_execz .LBB0_1005
	s_lshl_b32 s3, s22, 11
	s_add_i32 s3, s12, s3
	v_mul_f32_e32 v24, 0x3c800000, v24
	s_waitcnt lgkmcnt(0)
	v_add_f32_e32 v25, v25, v26
	v_lshl_add_u32 v26, v178, 5, s3
	ds_write_b64 v26, v[24:25]
